# seams 5 and 6 (Wout->FF1->FF2) use a barrier among the 32 workgroups that share blockIdx%8 (dependency-closed row tiles) instead of the grid barrier; XCC-id mask decides whether the L2 write-back is n
# speedup vs baseline: 1.0081x; 1.0052x over previous
; #define LAS __attribute__((address_space(3)))
; #define MFMA32(a, b, c) __builtin_amdgcn_mfma_f32_32x32x16_bf16((a), (b), (c), 0, 0, 0)
; __device__ __forceinline__ float ex2(float x) { return __builtin_amdgcn_exp2f(x); }
; template <int MODE>
; __device__ __forceinline__ void attn_tile(const LAS unsigned char* Kb, const LAS unsigned char* Vb, const bf16x8_t (&qf)[4], f32x16 (&oacc)[2], float& l_run,
;                                           int r, int h, int dlt0, int dlt1, bool hiw) {
;     ...
; #pragma unroll
;     for (int mt = 0; mt < 4; ++mt) {
;         if (mt == 0) { if (hiw) __builtin_amdgcn_s_setprio(1); else __builtin_amdgcn_s_setprio(0); }
;         if (mt == 2) { if (hiw) __builtin_amdgcn_s_setprio(0); else __builtin_amdgcn_s_setprio(1); }
;         const int dl = mt < 2 ? dlt0 : dlt1;
;         f32x16 sacc = zero16();
; #pragma unroll
;         for (int ks = 0; ks < 4; ++ks) { const bf16x8_t ka = *(const LAS bf16x8_t*)(Kb + (32 * mt + r) * A_KSTR + 32 * ks + 16 * h); sacc = MFMA32(ka, qf[ks], sacc); }
; #pragma unroll
;         for (int i = 0; i < 16; ++i) {
;             float p;
;             if (MODE == 2) p = ex2(sacc[i]);
;             else if (MODE == 3) p = ex2(sacc[i] + __int_as_float(dl));
;             else { const int ci = 32 * mt + (i & 3) + 8 * (i >> 2); p = ((unsigned)(dl - ci) < ulim) ? ex2(sacc[i]) : 0.f; }
;             sacc[i] = p; ls += p;
;         }
; #pragma unroll
;         for (int s = 0; s < 2; ++s) {
;             const bf16x8_t pf = pack8(sacc, 8 * s);
; #pragma unroll
;             for (int dt = 0; dt < 2; ++dt) {
;                 const LAS unsigned char* vp = Vb + (32 * dt + r) * A_CVSTR + (32 * mt + 16 * s + 4 * h) * 2;
;                 const s16x4_t lo = *(const LAS s16x4_t*)vp, hi = *(const LAS s16x4_t*)(vp + 16);
;                 oacc[dt] = MFMA32(__builtin_shufflevector(lo, hi, 0, 1, 2, 3, 4, 5, 6, 7), pf, oacc[dt]);
;             }
;         }
;     }
.Lt1_full:
	ds_read_b128 v[200:203], v72 offset:0
	ds_read_b128 v[204:207], v72 offset:32
	ds_read_b128 v[208:211], v72 offset:64
	ds_read_b128 v[212:215], v72 offset:96
	ds_read2_b64 v[216:219], v73 offset0:0 offset1:2
	ds_read2_b64 v[220:223], v74 offset0:32 offset1:34
	ds_read2_b64 v[224:227], v73 offset0:4 offset1:6
	ds_read2_b64 v[228:231], v74 offset0:36 offset1:38
	s_waitcnt lgkmcnt(7)
	v_mfma_f32_32x32x16_bf16 v[32:47], v[200:203], v[80:83], 0
	ds_read_b128 v[200:203], v72 offset:4608
	s_waitcnt lgkmcnt(7)
	v_mfma_f32_32x32x16_bf16 v[32:47], v[204:207], v[84:87], v[32:47]
	ds_read_b128 v[204:207], v72 offset:4640
	s_waitcnt lgkmcnt(7)
	v_mfma_f32_32x32x16_bf16 v[32:47], v[208:211], v[88:91], v[32:47]
	ds_read_b128 v[208:211], v72 offset:4672
	s_waitcnt lgkmcnt(7)
	v_mfma_f32_32x32x16_bf16 v[32:47], v[212:215], v[92:95], v[32:47]
	ds_read_b128 v[212:215], v72 offset:4704
	s_nop 7
	s_nop 3
	s_waitcnt lgkmcnt(3)
	v_mfma_f32_32x32x16_bf16 v[48:63], v[200:203], v[80:83], 0
	ds_read_b128 v[200:203], v72 offset:9216
	v_exp_f32_e32 v32, v32
	v_exp_f32_e32 v33, v33
	s_waitcnt lgkmcnt(3)
	v_mfma_f32_32x32x16_bf16 v[48:63], v[204:207], v[84:87], v[48:63]
	ds_read_b128 v[204:207], v72 offset:9248
	v_exp_f32_e32 v34, v34
	v_exp_f32_e32 v35, v35
	v_mov_b32_e32 v232, v32
	v_mov_b32_e32 v233, v33
	v_cvt_pk_bf16_f32 v64, v32, v33
	v_exp_f32_e32 v36, v36
	v_exp_f32_e32 v37, v37
	v_add_f32_e32 v232, v232, v34
	v_add_f32_e32 v233, v233, v35
	v_cvt_pk_bf16_f32 v65, v34, v35
	v_exp_f32_e32 v38, v38
	v_exp_f32_e32 v39, v39
	v_add_f32_e32 v232, v232, v36
	v_add_f32_e32 v233, v233, v37
	v_cvt_pk_bf16_f32 v66, v36, v37
	v_add_f32_e32 v232, v232, v38
	v_add_f32_e32 v233, v233, v39
	v_cvt_pk_bf16_f32 v67, v38, v39
	s_waitcnt lgkmcnt(3)
	v_mfma_f32_32x32x16_bf16 v[48:63], v[208:211], v[88:91], v[48:63]
	ds_read_b128 v[208:211], v72 offset:9280
	v_exp_f32_e32 v40, v40
	v_exp_f32_e32 v41, v41
	s_waitcnt lgkmcnt(3)
	v_mfma_f32_32x32x16_bf16 v[48:63], v[212:215], v[92:95], v[48:63]
	ds_read_b128 v[212:215], v72 offset:9312
	v_exp_f32_e32 v42, v42
	v_exp_f32_e32 v43, v43
	v_add_f32_e32 v232, v232, v40
	v_add_f32_e32 v233, v233, v41
	v_cvt_pk_bf16_f32 v68, v40, v41
	v_mfma_f32_32x32x16_bf16 v[0:15], v[216:219], v[64:67], v[0:15]
	ds_read2_b64 v[216:219], v73 offset0:8 offset1:10
	v_exp_f32_e32 v44, v44
	v_exp_f32_e32 v45, v45
	v_add_f32_e32 v232, v232, v42
	v_add_f32_e32 v233, v233, v43
	v_cvt_pk_bf16_f32 v69, v42, v43
	v_mfma_f32_32x32x16_bf16 v[16:31], v[220:223], v[64:67], v[16:31]
	ds_read2_b64 v[220:223], v74 offset0:40 offset1:42
	v_exp_f32_e32 v46, v46
	v_exp_f32_e32 v47, v47
	v_add_f32_e32 v232, v232, v44
	v_add_f32_e32 v233, v233, v45
	v_cvt_pk_bf16_f32 v70, v44, v45
	v_add_f32_e32 v232, v232, v46
	v_add_f32_e32 v233, v233, v47
	v_cvt_pk_bf16_f32 v71, v46, v47
	s_waitcnt lgkmcnt(5)
	v_mfma_f32_32x32x16_bf16 v[32:47], v[200:203], v[80:83], 0
	ds_read_b128 v[200:203], v72 offset:13824
	v_exp_f32_e32 v48, v48
	v_exp_f32_e32 v49, v49
	s_waitcnt lgkmcnt(5)
	v_mfma_f32_32x32x16_bf16 v[32:47], v[204:207], v[84:87], v[32:47]
	ds_read_b128 v[204:207], v72 offset:13856
	v_exp_f32_e32 v50, v50
	v_exp_f32_e32 v51, v51
	v_add_f32_e32 v232, v232, v48
	v_add_f32_e32 v233, v233, v49
	v_cvt_pk_bf16_f32 v64, v48, v49
	v_mfma_f32_32x32x16_bf16 v[0:15], v[224:227], v[68:71], v[0:15]
	ds_read2_b64 v[224:227], v73 offset0:12 offset1:14
	v_exp_f32_e32 v52, v52
	v_exp_f32_e32 v53, v53
	v_add_f32_e32 v232, v232, v50
	v_add_f32_e32 v233, v233, v51
	v_cvt_pk_bf16_f32 v65, v50, v51
	v_mfma_f32_32x32x16_bf16 v[16:31], v[228:231], v[68:71], v[16:31]
	ds_read2_b64 v[228:231], v74 offset0:44 offset1:46
	v_exp_f32_e32 v54, v54
	v_exp_f32_e32 v55, v55
	v_add_f32_e32 v232, v232, v52
	v_add_f32_e32 v233, v233, v53
	v_cvt_pk_bf16_f32 v66, v52, v53
	v_add_f32_e32 v232, v232, v54
	v_add_f32_e32 v233, v233, v55
	v_cvt_pk_bf16_f32 v67, v54, v55
	s_waitcnt lgkmcnt(7)
	v_mfma_f32_32x32x16_bf16 v[32:47], v[208:211], v[88:91], v[32:47]
	ds_read_b128 v[208:211], v72 offset:13888
	v_exp_f32_e32 v56, v56
	v_exp_f32_e32 v57, v57
	s_waitcnt lgkmcnt(7)
	v_mfma_f32_32x32x16_bf16 v[32:47], v[212:215], v[92:95], v[32:47]
	ds_read_b128 v[212:215], v72 offset:13920
	v_exp_f32_e32 v58, v58
	v_exp_f32_e32 v59, v59
	v_add_f32_e32 v232, v232, v56
	v_add_f32_e32 v233, v233, v57
	v_cvt_pk_bf16_f32 v68, v56, v57
	s_waitcnt lgkmcnt(7)
	v_mfma_f32_32x32x16_bf16 v[0:15], v[216:219], v[64:67], v[0:15]
	ds_read2_b64 v[216:219], v73 offset0:16 offset1:18
	v_exp_f32_e32 v60, v60
	v_exp_f32_e32 v61, v61
	v_add_f32_e32 v232, v232, v58
	v_add_f32_e32 v233, v233, v59
	v_cvt_pk_bf16_f32 v69, v58, v59
	s_waitcnt lgkmcnt(7)
	v_mfma_f32_32x32x16_bf16 v[16:31], v[220:223], v[64:67], v[16:31]
	ds_read2_b64 v[220:223], v74 offset0:48 offset1:50
	v_exp_f32_e32 v62, v62
	v_exp_f32_e32 v63, v63
	v_add_f32_e32 v232, v232, v60
	v_add_f32_e32 v233, v233, v61
	v_cvt_pk_bf16_f32 v70, v60, v61
	v_add_f32_e32 v232, v232, v62
	v_add_f32_e32 v233, v233, v63
	v_cvt_pk_bf16_f32 v71, v62, v63
	s_waitcnt lgkmcnt(7)
	v_mfma_f32_32x32x16_bf16 v[48:63], v[200:203], v[80:83], 0
	v_exp_f32_e32 v32, v32
	v_exp_f32_e32 v33, v33
	s_waitcnt lgkmcnt(6)
	v_mfma_f32_32x32x16_bf16 v[48:63], v[204:207], v[84:87], v[48:63]
	v_exp_f32_e32 v34, v34
	v_exp_f32_e32 v35, v35
	v_add_f32_e32 v232, v232, v32
	v_add_f32_e32 v233, v233, v33
	v_cvt_pk_bf16_f32 v64, v32, v33
	s_waitcnt lgkmcnt(5)
	v_mfma_f32_32x32x16_bf16 v[0:15], v[224:227], v[68:71], v[0:15]
	ds_read2_b64 v[224:227], v73 offset0:20 offset1:22
	v_exp_f32_e32 v36, v36
	v_exp_f32_e32 v37, v37
	v_add_f32_e32 v232, v232, v34
	v_add_f32_e32 v233, v233, v35
	v_cvt_pk_bf16_f32 v65, v34, v35
	s_waitcnt lgkmcnt(5)
	v_mfma_f32_32x32x16_bf16 v[16:31], v[228:231], v[68:71], v[16:31]
	ds_read2_b64 v[228:231], v74 offset0:52 offset1:54
	v_exp_f32_e32 v38, v38
	v_exp_f32_e32 v39, v39
	v_add_f32_e32 v232, v232, v36
	v_add_f32_e32 v233, v233, v37
	v_cvt_pk_bf16_f32 v66, v36, v37
	v_add_f32_e32 v232, v232, v38
	v_add_f32_e32 v233, v233, v39
	v_cvt_pk_bf16_f32 v67, v38, v39
	s_cmp_eq_u32 s45, 0
	s_cbranch_scc1 .Lt1_full_nostage
	s_waitcnt vmcnt(3)
	ds_write_b128 v251, v[96:99]
	s_waitcnt vmcnt(2)
	ds_write_b128 v251, v[100:103] offset:9216
	s_waitcnt vmcnt(1)
	ds_write2_b64 v252, v[104:105], v[106:107] offset1:1
	s_waitcnt vmcnt(0)
	ds_write2_b64 v252, v[108:109], v[110:111] offset0:16 offset1:17
	s_mov_b32 s47, 1
; #define LAS __attribute__((address_space(3)))
; #define MFMA32(a, b, c) __builtin_amdgcn_mfma_f32_32x32x16_bf16((a), (b), (c), 0, 0, 0)
; __device__ __forceinline__ float ex2(float x) { return __builtin_amdgcn_exp2f(x); }
; template <int MODE>
; __device__ __forceinline__ void attn_tile(const LAS unsigned char* Kb, const LAS unsigned char* Vb, const bf16x8_t (&qf)[4], f32x16 (&oacc)[2], float& l_run,
;                                           int r, int h, int dlt0, int dlt1, bool hiw) {
;     ...
; #pragma unroll
;     for (int mt = 0; mt < 4; ++mt) {
;         if (mt == 0) { if (hiw) __builtin_amdgcn_s_setprio(1); else __builtin_amdgcn_s_setprio(0); }
;         if (mt == 2) { if (hiw) __builtin_amdgcn_s_setprio(0); else __builtin_amdgcn_s_setprio(1); }
;         const int dl = mt < 2 ? dlt0 : dlt1;
;         f32x16 sacc = zero16();
; #pragma unroll
;         for (int ks = 0; ks < 4; ++ks) { const bf16x8_t ka = *(const LAS bf16x8_t*)(Kb + (32 * mt + r) * A_KSTR + 32 * ks + 16 * h); sacc = MFMA32(ka, qf[ks], sacc); }
; #pragma unroll
;         for (int i = 0; i < 16; ++i) {
;             float p;
;             if (MODE == 2) p = ex2(sacc[i]);
;             else if (MODE == 3) p = ex2(sacc[i] + __int_as_float(dl));
;             else { const int ci = 32 * mt + (i & 3) + 8 * (i >> 2); p = ((unsigned)(dl - ci) < ulim) ? ex2(sacc[i]) : 0.f; }
;             sacc[i] = p; ls += p;
;         }
; #pragma unroll
;         for (int s = 0; s < 2; ++s) {
;             const bf16x8_t pf = pack8(sacc, 8 * s);
; #pragma unroll
;             for (int dt = 0; dt < 2; ++dt) {
;                 const LAS unsigned char* vp = Vb + (32 * dt + r) * A_CVSTR + (32 * mt + 16 * s + 4 * h) * 2;
;                 const s16x4_t lo = *(const LAS s16x4_t*)vp, hi = *(const LAS s16x4_t*)(vp + 16);
;                 oacc[dt] = MFMA32(__builtin_shufflevector(lo, hi, 0, 1, 2, 3, 4, 5, 6, 7), pf, oacc[dt]);
;             }
;         }
;     }
;     l_run += ls;
; }
.Lt1_full_nostage:
	s_waitcnt lgkmcnt(5)
	v_mfma_f32_32x32x16_bf16 v[48:63], v[208:211], v[88:91], v[48:63]
	v_exp_f32_e32 v40, v40
	v_exp_f32_e32 v41, v41
	s_waitcnt lgkmcnt(4)
	v_mfma_f32_32x32x16_bf16 v[48:63], v[212:215], v[92:95], v[48:63]
	v_exp_f32_e32 v42, v42
	v_exp_f32_e32 v43, v43
	v_add_f32_e32 v232, v232, v40
	v_add_f32_e32 v233, v233, v41
	v_cvt_pk_bf16_f32 v68, v40, v41
	s_waitcnt lgkmcnt(3)
	v_mfma_f32_32x32x16_bf16 v[0:15], v[216:219], v[64:67], v[0:15]
	ds_read2_b64 v[216:219], v73 offset0:24 offset1:26
	v_exp_f32_e32 v44, v44
	v_exp_f32_e32 v45, v45
	v_add_f32_e32 v232, v232, v42
	v_add_f32_e32 v233, v233, v43
	v_cvt_pk_bf16_f32 v69, v42, v43
	s_waitcnt lgkmcnt(3)
	v_mfma_f32_32x32x16_bf16 v[16:31], v[220:223], v[64:67], v[16:31]
	ds_read2_b64 v[220:223], v74 offset0:56 offset1:58
	v_exp_f32_e32 v46, v46
	v_exp_f32_e32 v47, v47
	v_add_f32_e32 v232, v232, v44
	v_add_f32_e32 v233, v233, v45
	v_cvt_pk_bf16_f32 v70, v44, v45
	v_add_f32_e32 v232, v232, v46
	v_add_f32_e32 v233, v233, v47
	v_cvt_pk_bf16_f32 v71, v46, v47
	v_exp_f32_e32 v48, v48
	v_exp_f32_e32 v49, v49
	v_exp_f32_e32 v50, v50
	v_exp_f32_e32 v51, v51
	v_add_f32_e32 v232, v232, v48
	v_add_f32_e32 v233, v233, v49
	v_cvt_pk_bf16_f32 v64, v48, v49
	s_waitcnt lgkmcnt(3)
	v_mfma_f32_32x32x16_bf16 v[0:15], v[224:227], v[68:71], v[0:15]
	ds_read2_b64 v[224:227], v73 offset0:28 offset1:30
	v_exp_f32_e32 v52, v52
	v_exp_f32_e32 v53, v53
	v_add_f32_e32 v232, v232, v50
	v_add_f32_e32 v233, v233, v51
	v_cvt_pk_bf16_f32 v65, v50, v51
	s_waitcnt lgkmcnt(3)
	v_mfma_f32_32x32x16_bf16 v[16:31], v[228:231], v[68:71], v[16:31]
	ds_read2_b64 v[228:231], v74 offset0:60 offset1:62
	v_exp_f32_e32 v54, v54
	v_exp_f32_e32 v55, v55
	v_add_f32_e32 v232, v232, v52
	v_add_f32_e32 v233, v233, v53
	v_cvt_pk_bf16_f32 v66, v52, v53
	v_add_f32_e32 v232, v232, v54
	v_add_f32_e32 v233, v233, v55
	v_cvt_pk_bf16_f32 v67, v54, v55
	v_exp_f32_e32 v56, v56
	v_exp_f32_e32 v57, v57
	v_exp_f32_e32 v58, v58
	v_exp_f32_e32 v59, v59
	v_add_f32_e32 v232, v232, v56
	v_add_f32_e32 v233, v233, v57
	v_cvt_pk_bf16_f32 v68, v56, v57
	s_waitcnt lgkmcnt(3)
	v_mfma_f32_32x32x16_bf16 v[0:15], v[216:219], v[64:67], v[0:15]
	v_exp_f32_e32 v60, v60
	v_exp_f32_e32 v61, v61
	v_add_f32_e32 v232, v232, v58
	v_add_f32_e32 v233, v233, v59
	v_cvt_pk_bf16_f32 v69, v58, v59
	s_waitcnt lgkmcnt(2)
	v_mfma_f32_32x32x16_bf16 v[16:31], v[220:223], v[64:67], v[16:31]
	v_exp_f32_e32 v62, v62
	v_exp_f32_e32 v63, v63
	v_add_f32_e32 v232, v232, v60
	v_add_f32_e32 v233, v233, v61
	v_cvt_pk_bf16_f32 v70, v60, v61
	v_add_f32_e32 v232, v232, v62
	v_add_f32_e32 v233, v233, v63
	v_cvt_pk_bf16_f32 v71, v62, v63
	s_nop 1
	s_waitcnt lgkmcnt(1)
	v_mfma_f32_32x32x16_bf16 v[0:15], v[224:227], v[68:71], v[0:15]
	s_waitcnt lgkmcnt(0)
	v_mfma_f32_32x32x16_bf16 v[16:31], v[228:231], v[68:71], v[16:31]
	v_add_f32_e32 v232, v232, v233
	v_add_f32_e32 v112, v112, v232
	s_branch .Lt1_join
.Lt1_bias:
	ds_read_b128 v[200:203], v72 offset:0
	ds_read_b128 v[204:207], v72 offset:32
	ds_read_b128 v[208:211], v72 offset:64
	ds_read_b128 v[212:215], v72 offset:96
	ds_read2_b64 v[216:219], v73 offset0:0 offset1:2
	ds_read2_b64 v[220:223], v74 offset0:32 offset1:34
	ds_read2_b64 v[224:227], v73 offset0:4 offset1:6
	ds_read2_b64 v[228:231], v74 offset0:36 offset1:38
	v_bfe_i32 v236, v158, s49, 1
	s_add_i32 s49, s49, 1
	v_bfe_i32 v237, v158, s49, 1
	s_waitcnt lgkmcnt(7)
	v_mfma_f32_32x32x16_bf16 v[32:47], v[200:203], v[80:83], 0
	ds_read_b128 v[200:203], v72 offset:4608
	s_waitcnt lgkmcnt(7)
	v_mfma_f32_32x32x16_bf16 v[32:47], v[204:207], v[84:87], v[32:47]
	ds_read_b128 v[204:207], v72 offset:4640
	s_waitcnt lgkmcnt(7)
	v_mfma_f32_32x32x16_bf16 v[32:47], v[208:211], v[88:91], v[32:47]
	ds_read_b128 v[208:211], v72 offset:4672
	s_waitcnt lgkmcnt(7)
	v_mfma_f32_32x32x16_bf16 v[32:47], v[212:215], v[92:95], v[32:47]
	ds_read_b128 v[212:215], v72 offset:4704
	s_nop 7
	s_nop 3
	s_waitcnt lgkmcnt(3)
	v_mfma_f32_32x32x16_bf16 v[48:63], v[200:203], v[80:83], 0
	ds_read_b128 v[200:203], v72 offset:9216
	v_exp_f32_e32 v32, v32
	v_exp_f32_e32 v33, v33
	s_waitcnt lgkmcnt(3)
	v_mfma_f32_32x32x16_bf16 v[48:63], v[204:207], v[84:87], v[48:63]
	ds_read_b128 v[204:207], v72 offset:9248
	v_exp_f32_e32 v34, v34
	v_exp_f32_e32 v35, v35
	v_mov_b32_e32 v232, v32
	v_mov_b32_e32 v233, v33
	v_cvt_pk_bf16_f32 v64, v32, v33
	v_and_b32_e32 v64, v236, v64
	v_exp_f32_e32 v36, v36
	v_exp_f32_e32 v37, v37
	v_add_f32_e32 v232, v232, v34
	v_add_f32_e32 v233, v233, v35
	v_cvt_pk_bf16_f32 v65, v34, v35
	v_and_b32_e32 v65, v236, v65
	v_exp_f32_e32 v38, v38
	v_exp_f32_e32 v39, v39
	v_add_f32_e32 v232, v232, v36
	v_add_f32_e32 v233, v233, v37
	v_cvt_pk_bf16_f32 v66, v36, v37
	v_and_b32_e32 v66, v236, v66
	v_add_f32_e32 v232, v232, v38
	v_add_f32_e32 v233, v233, v39
	v_cvt_pk_bf16_f32 v67, v38, v39
	v_and_b32_e32 v67, v236, v67
	s_waitcnt lgkmcnt(3)
	v_mfma_f32_32x32x16_bf16 v[48:63], v[208:211], v[88:91], v[48:63]
	ds_read_b128 v[208:211], v72 offset:9280
	v_exp_f32_e32 v40, v40
	v_exp_f32_e32 v41, v41
	s_waitcnt lgkmcnt(3)
	v_mfma_f32_32x32x16_bf16 v[48:63], v[212:215], v[92:95], v[48:63]
	ds_read_b128 v[212:215], v72 offset:9312
	v_exp_f32_e32 v42, v42
	v_exp_f32_e32 v43, v43
	v_add_f32_e32 v232, v232, v40
	v_add_f32_e32 v233, v233, v41
	v_cvt_pk_bf16_f32 v68, v40, v41
	v_and_b32_e32 v68, v236, v68
	v_mfma_f32_32x32x16_bf16 v[0:15], v[216:219], v[64:67], v[0:15]
	ds_read2_b64 v[216:219], v73 offset0:8 offset1:10
	v_exp_f32_e32 v44, v44
	v_exp_f32_e32 v45, v45
	v_add_f32_e32 v232, v232, v42
	v_add_f32_e32 v233, v233, v43
	v_cvt_pk_bf16_f32 v69, v42, v43
	v_and_b32_e32 v69, v236, v69
	v_mfma_f32_32x32x16_bf16 v[16:31], v[220:223], v[64:67], v[16:31]
	ds_read2_b64 v[220:223], v74 offset0:40 offset1:42
	v_exp_f32_e32 v46, v46
	v_exp_f32_e32 v47, v47
	v_add_f32_e32 v232, v232, v44
	v_add_f32_e32 v233, v233, v45
	v_cvt_pk_bf16_f32 v70, v44, v45
	v_and_b32_e32 v70, v236, v70
	v_add_f32_e32 v232, v232, v46
	v_add_f32_e32 v233, v233, v47
	v_cvt_pk_bf16_f32 v71, v46, v47
	v_and_b32_e32 v71, v236, v71
	s_waitcnt lgkmcnt(5)
; #define LAS __attribute__((address_space(3)))
; #define MFMA32(a, b, c) __builtin_amdgcn_mfma_f32_32x32x16_bf16((a), (b), (c), 0, 0, 0)
; __device__ __forceinline__ float ex2(float x) { return __builtin_amdgcn_exp2f(x); }
; template <int MODE>
; __device__ __forceinline__ void attn_tile(const LAS unsigned char* Kb, const LAS unsigned char* Vb, const bf16x8_t (&qf)[4], f32x16 (&oacc)[2], float& l_run,
;                                           int r, int h, int dlt0, int dlt1, bool hiw) {
;     ...
; #pragma unroll
;     for (int mt = 0; mt < 4; ++mt) {
;         if (mt == 0) { if (hiw) __builtin_amdgcn_s_setprio(1); else __builtin_amdgcn_s_setprio(0); }
;         if (mt == 2) { if (hiw) __builtin_amdgcn_s_setprio(0); else __builtin_amdgcn_s_setprio(1); }
;         const int dl = mt < 2 ? dlt0 : dlt1;
;         f32x16 sacc = zero16();
; #pragma unroll
;         for (int ks = 0; ks < 4; ++ks) { const bf16x8_t ka = *(const LAS bf16x8_t*)(Kb + (32 * mt + r) * A_KSTR + 32 * ks + 16 * h); sacc = MFMA32(ka, qf[ks], sacc); }
; #pragma unroll
;         for (int i = 0; i < 16; ++i) {
;             float p;
;             if (MODE == 2) p = ex2(sacc[i]);
;             else if (MODE == 3) p = ex2(sacc[i] + __int_as_float(dl));
;             else { const int ci = 32 * mt + (i & 3) + 8 * (i >> 2); p = ((unsigned)(dl - ci) < ulim) ? ex2(sacc[i]) : 0.f; }
;             sacc[i] = p; ls += p;
;         }
; #pragma unroll
;         for (int s = 0; s < 2; ++s) {
;             const bf16x8_t pf = pack8(sacc, 8 * s);
; #pragma unroll
;             for (int dt = 0; dt < 2; ++dt) {
;                 const LAS unsigned char* vp = Vb + (32 * dt + r) * A_CVSTR + (32 * mt + 16 * s + 4 * h) * 2;
;                 const s16x4_t lo = *(const LAS s16x4_t*)vp, hi = *(const LAS s16x4_t*)(vp + 16);
;                 oacc[dt] = MFMA32(__builtin_shufflevector(lo, hi, 0, 1, 2, 3, 4, 5, 6, 7), pf, oacc[dt]);
;             }
;         }
;     }
	v_mfma_f32_32x32x16_bf16 v[32:47], v[200:203], v[80:83], 0
	ds_read_b128 v[200:203], v72 offset:13824
	v_exp_f32_e32 v48, v48
	v_exp_f32_e32 v49, v49
	s_waitcnt lgkmcnt(5)
	v_mfma_f32_32x32x16_bf16 v[32:47], v[204:207], v[84:87], v[32:47]
	ds_read_b128 v[204:207], v72 offset:13856
	v_exp_f32_e32 v50, v50
	v_exp_f32_e32 v51, v51
	v_add_f32_e32 v232, v232, v48
	v_add_f32_e32 v233, v233, v49
	v_cvt_pk_bf16_f32 v64, v48, v49
	v_and_b32_e32 v64, v236, v64
	v_mfma_f32_32x32x16_bf16 v[0:15], v[224:227], v[68:71], v[0:15]
	ds_read2_b64 v[224:227], v73 offset0:12 offset1:14
	v_exp_f32_e32 v52, v52
	v_exp_f32_e32 v53, v53
	v_add_f32_e32 v232, v232, v50
	v_add_f32_e32 v233, v233, v51
	v_cvt_pk_bf16_f32 v65, v50, v51
	v_and_b32_e32 v65, v236, v65
	v_mfma_f32_32x32x16_bf16 v[16:31], v[228:231], v[68:71], v[16:31]
	ds_read2_b64 v[228:231], v74 offset0:44 offset1:46
	v_exp_f32_e32 v54, v54
	v_exp_f32_e32 v55, v55
	v_add_f32_e32 v232, v232, v52
	v_add_f32_e32 v233, v233, v53
	v_cvt_pk_bf16_f32 v66, v52, v53
	v_and_b32_e32 v66, v236, v66
	v_add_f32_e32 v232, v232, v54
	v_add_f32_e32 v233, v233, v55
	v_cvt_pk_bf16_f32 v67, v54, v55
	v_and_b32_e32 v67, v236, v67
	s_waitcnt lgkmcnt(7)
	v_mfma_f32_32x32x16_bf16 v[32:47], v[208:211], v[88:91], v[32:47]
	ds_read_b128 v[208:211], v72 offset:13888
	v_exp_f32_e32 v56, v56
	v_exp_f32_e32 v57, v57
	s_waitcnt lgkmcnt(7)
	v_mfma_f32_32x32x16_bf16 v[32:47], v[212:215], v[92:95], v[32:47]
	ds_read_b128 v[212:215], v72 offset:13920
	v_exp_f32_e32 v58, v58
	v_exp_f32_e32 v59, v59
	v_add_f32_e32 v232, v232, v56
	v_add_f32_e32 v233, v233, v57
	v_cvt_pk_bf16_f32 v68, v56, v57
	v_and_b32_e32 v68, v236, v68
	s_waitcnt lgkmcnt(7)
	v_mfma_f32_32x32x16_bf16 v[0:15], v[216:219], v[64:67], v[0:15]
	ds_read2_b64 v[216:219], v73 offset0:16 offset1:18
	v_exp_f32_e32 v60, v60
	v_exp_f32_e32 v61, v61
	v_add_f32_e32 v232, v232, v58
	v_add_f32_e32 v233, v233, v59
	v_cvt_pk_bf16_f32 v69, v58, v59
	v_and_b32_e32 v69, v236, v69
	s_waitcnt lgkmcnt(7)
	v_mfma_f32_32x32x16_bf16 v[16:31], v[220:223], v[64:67], v[16:31]
	ds_read2_b64 v[220:223], v74 offset0:48 offset1:50
	v_exp_f32_e32 v62, v62
	v_exp_f32_e32 v63, v63
	v_add_f32_e32 v232, v232, v60
	v_add_f32_e32 v233, v233, v61
	v_cvt_pk_bf16_f32 v70, v60, v61
	v_and_b32_e32 v70, v236, v70
	v_add_f32_e32 v232, v232, v62
	v_add_f32_e32 v233, v233, v63
	v_cvt_pk_bf16_f32 v71, v62, v63
	v_and_b32_e32 v71, v236, v71
	s_waitcnt lgkmcnt(7)
	v_mfma_f32_32x32x16_bf16 v[48:63], v[200:203], v[80:83], 0
	v_exp_f32_e32 v32, v32
	v_exp_f32_e32 v33, v33
	s_waitcnt lgkmcnt(6)
	v_mfma_f32_32x32x16_bf16 v[48:63], v[204:207], v[84:87], v[48:63]
	v_exp_f32_e32 v34, v34
	v_exp_f32_e32 v35, v35
	v_mov_b32_e32 v234, v32
	v_mov_b32_e32 v235, v33
	v_cvt_pk_bf16_f32 v64, v32, v33
	v_and_b32_e32 v64, v237, v64
	s_waitcnt lgkmcnt(5)
	v_mfma_f32_32x32x16_bf16 v[0:15], v[224:227], v[68:71], v[0:15]
	ds_read2_b64 v[224:227], v73 offset0:20 offset1:22
	v_exp_f32_e32 v36, v36
	v_exp_f32_e32 v37, v37
	v_add_f32_e32 v234, v234, v34
	v_add_f32_e32 v235, v235, v35
	v_cvt_pk_bf16_f32 v65, v34, v35
	v_and_b32_e32 v65, v237, v65
	s_waitcnt lgkmcnt(5)
	v_mfma_f32_32x32x16_bf16 v[16:31], v[228:231], v[68:71], v[16:31]
	ds_read2_b64 v[228:231], v74 offset0:52 offset1:54
	v_exp_f32_e32 v38, v38
	v_exp_f32_e32 v39, v39
	v_add_f32_e32 v234, v234, v36
	v_add_f32_e32 v235, v235, v37
	v_cvt_pk_bf16_f32 v66, v36, v37
	v_and_b32_e32 v66, v237, v66
	v_add_f32_e32 v234, v234, v38
	v_add_f32_e32 v235, v235, v39
	v_cvt_pk_bf16_f32 v67, v38, v39
	v_and_b32_e32 v67, v237, v67
	s_cmp_eq_u32 s45, 0
	s_cbranch_scc1 .Lt1_bias_nostage
	s_waitcnt vmcnt(3)
	ds_write_b128 v251, v[96:99]
	s_waitcnt vmcnt(2)
	ds_write_b128 v251, v[100:103] offset:9216
	s_waitcnt vmcnt(1)
	ds_write2_b64 v252, v[104:105], v[106:107] offset1:1
	s_waitcnt vmcnt(0)
	ds_write2_b64 v252, v[108:109], v[110:111] offset0:16 offset1:17
	s_mov_b32 s47, 1
; #define LAS __attribute__((address_space(3)))
; #define MFMA32(a, b, c) __builtin_amdgcn_mfma_f32_32x32x16_bf16((a), (b), (c), 0, 0, 0)
; __device__ __forceinline__ float ex2(float x) { return __builtin_amdgcn_exp2f(x); }
; template <int MODE>
; __device__ __forceinline__ void attn_tile(const LAS unsigned char* Kb, const LAS unsigned char* Vb, const bf16x8_t (&qf)[4], f32x16 (&oacc)[2], float& l_run,
;                                           int r, int h, int dlt0, int dlt1, bool hiw) {
;     ...
; #pragma unroll
;     for (int mt = 0; mt < 4; ++mt) {
;         if (mt == 0) { if (hiw) __builtin_amdgcn_s_setprio(1); else __builtin_amdgcn_s_setprio(0); }
;         if (mt == 2) { if (hiw) __builtin_amdgcn_s_setprio(0); else __builtin_amdgcn_s_setprio(1); }
;         const int dl = mt < 2 ? dlt0 : dlt1;
;         f32x16 sacc = zero16();
; #pragma unroll
;         for (int ks = 0; ks < 4; ++ks) { const bf16x8_t ka = *(const LAS bf16x8_t*)(Kb + (32 * mt + r) * A_KSTR + 32 * ks + 16 * h); sacc = MFMA32(ka, qf[ks], sacc); }
; #pragma unroll
;         for (int i = 0; i < 16; ++i) {
;             float p;
;             if (MODE == 2) p = ex2(sacc[i]);
;             else if (MODE == 3) p = ex2(sacc[i] + __int_as_float(dl));
;             else { const int ci = 32 * mt + (i & 3) + 8 * (i >> 2); p = ((unsigned)(dl - ci) < ulim) ? ex2(sacc[i]) : 0.f; }
;             sacc[i] = p; ls += p;
;         }
; #pragma unroll
;         for (int s = 0; s < 2; ++s) {
;             const bf16x8_t pf = pack8(sacc, 8 * s);
; #pragma unroll
;             for (int dt = 0; dt < 2; ++dt) {
;                 const LAS unsigned char* vp = Vb + (32 * dt + r) * A_CVSTR + (32 * mt + 16 * s + 4 * h) * 2;
;                 const s16x4_t lo = *(const LAS s16x4_t*)vp, hi = *(const LAS s16x4_t*)(vp + 16);
;                 oacc[dt] = MFMA32(__builtin_shufflevector(lo, hi, 0, 1, 2, 3, 4, 5, 6, 7), pf, oacc[dt]);
;             }
;         }
;     }
;     l_run += ls;
; }
.Lt1_bias_nostage:
	s_waitcnt lgkmcnt(5)
	v_mfma_f32_32x32x16_bf16 v[48:63], v[208:211], v[88:91], v[48:63]
	v_exp_f32_e32 v40, v40
	v_exp_f32_e32 v41, v41
	s_waitcnt lgkmcnt(4)
	v_mfma_f32_32x32x16_bf16 v[48:63], v[212:215], v[92:95], v[48:63]
	v_exp_f32_e32 v42, v42
	v_exp_f32_e32 v43, v43
	v_add_f32_e32 v234, v234, v40
	v_add_f32_e32 v235, v235, v41
	v_cvt_pk_bf16_f32 v68, v40, v41
	v_and_b32_e32 v68, v237, v68
	s_waitcnt lgkmcnt(3)
	v_mfma_f32_32x32x16_bf16 v[0:15], v[216:219], v[64:67], v[0:15]
	ds_read2_b64 v[216:219], v73 offset0:24 offset1:26
	v_exp_f32_e32 v44, v44
	v_exp_f32_e32 v45, v45
	v_add_f32_e32 v234, v234, v42
	v_add_f32_e32 v235, v235, v43
	v_cvt_pk_bf16_f32 v69, v42, v43
	v_and_b32_e32 v69, v237, v69
	s_waitcnt lgkmcnt(3)
	v_mfma_f32_32x32x16_bf16 v[16:31], v[220:223], v[64:67], v[16:31]
	ds_read2_b64 v[220:223], v74 offset0:56 offset1:58
	v_exp_f32_e32 v46, v46
	v_exp_f32_e32 v47, v47
	v_add_f32_e32 v234, v234, v44
	v_add_f32_e32 v235, v235, v45
	v_cvt_pk_bf16_f32 v70, v44, v45
	v_and_b32_e32 v70, v237, v70
	v_add_f32_e32 v234, v234, v46
	v_add_f32_e32 v235, v235, v47
	v_cvt_pk_bf16_f32 v71, v46, v47
	v_and_b32_e32 v71, v237, v71
	v_exp_f32_e32 v48, v48
	v_exp_f32_e32 v49, v49
	v_exp_f32_e32 v50, v50
	v_exp_f32_e32 v51, v51
	v_add_f32_e32 v234, v234, v48
	v_add_f32_e32 v235, v235, v49
	v_cvt_pk_bf16_f32 v64, v48, v49
	v_and_b32_e32 v64, v237, v64
	s_waitcnt lgkmcnt(3)
	v_mfma_f32_32x32x16_bf16 v[0:15], v[224:227], v[68:71], v[0:15]
	ds_read2_b64 v[224:227], v73 offset0:28 offset1:30
	v_exp_f32_e32 v52, v52
	v_exp_f32_e32 v53, v53
	v_add_f32_e32 v234, v234, v50
	v_add_f32_e32 v235, v235, v51
	v_cvt_pk_bf16_f32 v65, v50, v51
	v_and_b32_e32 v65, v237, v65
	s_waitcnt lgkmcnt(3)
	v_mfma_f32_32x32x16_bf16 v[16:31], v[228:231], v[68:71], v[16:31]
	ds_read2_b64 v[228:231], v74 offset0:60 offset1:62
	v_exp_f32_e32 v54, v54
	v_exp_f32_e32 v55, v55
	v_add_f32_e32 v234, v234, v52
	v_add_f32_e32 v235, v235, v53
	v_cvt_pk_bf16_f32 v66, v52, v53
	v_and_b32_e32 v66, v237, v66
	v_add_f32_e32 v234, v234, v54
	v_add_f32_e32 v235, v235, v55
	v_cvt_pk_bf16_f32 v67, v54, v55
	v_and_b32_e32 v67, v237, v67
	v_exp_f32_e32 v56, v56
	v_exp_f32_e32 v57, v57
	v_exp_f32_e32 v58, v58
	v_exp_f32_e32 v59, v59
	v_add_f32_e32 v234, v234, v56
	v_add_f32_e32 v235, v235, v57
	v_cvt_pk_bf16_f32 v68, v56, v57
	v_and_b32_e32 v68, v237, v68
	s_waitcnt lgkmcnt(3)
	v_mfma_f32_32x32x16_bf16 v[0:15], v[216:219], v[64:67], v[0:15]
	v_exp_f32_e32 v60, v60
	v_exp_f32_e32 v61, v61
	v_add_f32_e32 v234, v234, v58
	v_add_f32_e32 v235, v235, v59
	v_cvt_pk_bf16_f32 v69, v58, v59
	v_and_b32_e32 v69, v237, v69
	s_waitcnt lgkmcnt(2)
	v_mfma_f32_32x32x16_bf16 v[16:31], v[220:223], v[64:67], v[16:31]
	v_exp_f32_e32 v62, v62
	v_exp_f32_e32 v63, v63
	v_add_f32_e32 v234, v234, v60
	v_add_f32_e32 v235, v235, v61
	v_cvt_pk_bf16_f32 v70, v60, v61
	v_and_b32_e32 v70, v237, v70
	v_add_f32_e32 v234, v234, v62
	v_add_f32_e32 v235, v235, v63
	v_cvt_pk_bf16_f32 v71, v62, v63
	v_and_b32_e32 v71, v237, v71
	s_nop 1
	s_waitcnt lgkmcnt(1)
	v_mfma_f32_32x32x16_bf16 v[0:15], v[224:227], v[68:71], v[0:15]
	s_waitcnt lgkmcnt(0)
	v_mfma_f32_32x32x16_bf16 v[16:31], v[228:231], v[68:71], v[16:31]
	v_add_f32_e32 v232, v232, v233
	v_add_f32_e32 v234, v234, v235
	v_and_b32_e32 v239, 1.0, v236
	v_and_b32_e32 v240, 1.0, v237
	v_fmac_f32_e32 v112, v232, v239
	v_fmac_f32_e32 v112, v234, v240
	s_branch .Lt1_join

; #define LAS __attribute__((address_space(3)))
; #define MFMA32(a, b, c) __builtin_amdgcn_mfma_f32_32x32x16_bf16((a), (b), (c), 0, 0, 0)
; __device__ __forceinline__ float ex2(float x) { return __builtin_amdgcn_exp2f(x); }
; template <int MODE>
; __device__ __forceinline__ void attn_tile(const LAS unsigned char* Kb, const LAS unsigned char* Vb, const bf16x8_t (&qf)[4], f32x16 (&oacc)[2], float& l_run,
;                                           int r, int h, int dlt0, int dlt1, bool hiw) {
;     ...
; #pragma unroll
;     for (int mt = 0; mt < 4; ++mt) {
;         if (mt == 0) { if (hiw) __builtin_amdgcn_s_setprio(1); else __builtin_amdgcn_s_setprio(0); }
;         if (mt == 2) { if (hiw) __builtin_amdgcn_s_setprio(0); else __builtin_amdgcn_s_setprio(1); }
;         const int dl = mt < 2 ? dlt0 : dlt1;
;         f32x16 sacc = zero16();
; #pragma unroll
;         for (int ks = 0; ks < 4; ++ks) { const bf16x8_t ka = *(const LAS bf16x8_t*)(Kb + (32 * mt + r) * A_KSTR + 32 * ks + 16 * h); sacc = MFMA32(ka, qf[ks], sacc); }
; #pragma unroll
;         for (int i = 0; i < 16; ++i) {
;             float p;
;             if (MODE == 2) p = ex2(sacc[i]);
;             else if (MODE == 3) p = ex2(sacc[i] + __int_as_float(dl));
;             else { const int ci = 32 * mt + (i & 3) + 8 * (i >> 2); p = ((unsigned)(dl - ci) < ulim) ? ex2(sacc[i]) : 0.f; }
;             sacc[i] = p; ls += p;
;         }
; #pragma unroll
;         for (int s = 0; s < 2; ++s) {
;             const bf16x8_t pf = pack8(sacc, 8 * s);
; #pragma unroll
;             for (int dt = 0; dt < 2; ++dt) {
;                 const LAS unsigned char* vp = Vb + (32 * dt + r) * A_CVSTR + (32 * mt + 16 * s + 4 * h) * 2;
;                 const s16x4_t lo = *(const LAS s16x4_t*)vp, hi = *(const LAS s16x4_t*)(vp + 16);
;                 oacc[dt] = MFMA32(__builtin_shufflevector(lo, hi, 0, 1, 2, 3, 4, 5, 6, 7), pf, oacc[dt]);
;             }
;         }
;     }
;     l_run += ls;
; }
.Lt1_d1:
	ds_read_b128 v[200:203], v72 offset:0
	ds_read_b128 v[204:207], v72 offset:32
	ds_read_b128 v[208:211], v72 offset:64
	ds_read_b128 v[212:215], v72 offset:96
	ds_read2_b64 v[216:219], v73 offset0:0 offset1:2
	ds_read2_b64 v[220:223], v74 offset0:32 offset1:34
	ds_read2_b64 v[224:227], v73 offset0:4 offset1:6
	ds_read2_b64 v[228:231], v74 offset0:36 offset1:38
	s_waitcnt lgkmcnt(7)
	v_mfma_f32_32x32x16_bf16 v[32:47], v[200:203], v[80:83], 0
	ds_read_b128 v[200:203], v72 offset:4608
	s_waitcnt lgkmcnt(7)
	v_mfma_f32_32x32x16_bf16 v[32:47], v[204:207], v[84:87], v[32:47]
	ds_read_b128 v[204:207], v72 offset:4640
	s_waitcnt lgkmcnt(7)
	v_mfma_f32_32x32x16_bf16 v[32:47], v[208:211], v[88:91], v[32:47]
	ds_read_b128 v[208:211], v72 offset:4672
	s_waitcnt lgkmcnt(7)
	v_mfma_f32_32x32x16_bf16 v[32:47], v[212:215], v[92:95], v[32:47]
	ds_read_b128 v[212:215], v72 offset:4704
	s_nop 7
	s_nop 3
	s_waitcnt lgkmcnt(3)
	v_mfma_f32_32x32x16_bf16 v[48:63], v[200:203], v[80:83], 0
	v_exp_f32_e32 v32, v32
	v_exp_f32_e32 v33, v33
	s_waitcnt lgkmcnt(2)
	v_mfma_f32_32x32x16_bf16 v[48:63], v[204:207], v[84:87], v[48:63]
	v_exp_f32_e32 v34, v34
	v_exp_f32_e32 v35, v35
	v_mov_b32_e32 v232, v32
	v_mov_b32_e32 v233, v33
	v_cvt_pk_bf16_f32 v64, v32, v33
	v_exp_f32_e32 v36, v36
	v_exp_f32_e32 v37, v37
	v_add_f32_e32 v232, v232, v34
	v_add_f32_e32 v233, v233, v35
	v_cvt_pk_bf16_f32 v65, v34, v35
	v_exp_f32_e32 v38, v38
	v_exp_f32_e32 v39, v39
	v_add_f32_e32 v232, v232, v36
	v_add_f32_e32 v233, v233, v37
	v_cvt_pk_bf16_f32 v66, v36, v37
	v_add_f32_e32 v232, v232, v38
	v_add_f32_e32 v233, v233, v39
	v_cvt_pk_bf16_f32 v67, v38, v39
	s_cmp_eq_u32 s45, 0
	s_cbranch_scc1 .Lt1_d1_nostage
	s_waitcnt vmcnt(3)
	ds_write_b128 v251, v[96:99]
	s_waitcnt vmcnt(2)
	ds_write_b128 v251, v[100:103] offset:9216
	s_waitcnt vmcnt(1)
	ds_write2_b64 v252, v[104:105], v[106:107] offset1:1
	s_waitcnt vmcnt(0)
	ds_write2_b64 v252, v[108:109], v[110:111] offset0:16 offset1:17
	s_mov_b32 s47, 1
.Lt1_d1_nostage:
	s_waitcnt lgkmcnt(1)
	v_mfma_f32_32x32x16_bf16 v[48:63], v[208:211], v[88:91], v[48:63]
	v_exp_f32_e32 v40, v40
	v_exp_f32_e32 v41, v41
	s_waitcnt lgkmcnt(0)
	v_mfma_f32_32x32x16_bf16 v[48:63], v[212:215], v[92:95], v[48:63]
	v_exp_f32_e32 v42, v42
	v_exp_f32_e32 v43, v43
	v_add_f32_e32 v232, v232, v40
	v_add_f32_e32 v233, v233, v41
	v_cvt_pk_bf16_f32 v68, v40, v41
	v_mfma_f32_32x32x16_bf16 v[0:15], v[216:219], v[64:67], v[0:15]
	ds_read2_b64 v[216:219], v73 offset0:8 offset1:10
	v_exp_f32_e32 v44, v44
	v_exp_f32_e32 v45, v45
	v_add_f32_e32 v232, v232, v42
	v_add_f32_e32 v233, v233, v43
	v_cvt_pk_bf16_f32 v69, v42, v43
	v_mfma_f32_32x32x16_bf16 v[16:31], v[220:223], v[64:67], v[16:31]
	ds_read2_b64 v[220:223], v74 offset0:40 offset1:42
	v_exp_f32_e32 v46, v46
	v_exp_f32_e32 v47, v47
	v_add_f32_e32 v232, v232, v44
	v_add_f32_e32 v233, v233, v45
	v_cvt_pk_bf16_f32 v70, v44, v45
	v_add_f32_e32 v232, v232, v46
	v_add_f32_e32 v233, v233, v47
	v_cvt_pk_bf16_f32 v71, v46, v47
	v_cmp_le_i32_e64 s[0:1], 0, v250
	v_cmp_le_i32_e64 s[4:5], 1, v250
	v_exp_f32_e32 v48, v48
	v_exp_f32_e32 v49, v49
	v_cmp_le_i32_e64 s[6:7], 2, v250
	v_cmp_le_i32_e64 s[48:49], 3, v250
	v_exp_f32_e32 v50, v50
	v_exp_f32_e32 v51, v51
	v_cndmask_b32_e64 v48, 0, v48, s[0:1]
	v_cndmask_b32_e64 v49, 0, v49, s[4:5]
	v_add_f32_e32 v232, v232, v48
	v_add_f32_e32 v233, v233, v49
	v_cvt_pk_bf16_f32 v64, v48, v49
	v_mfma_f32_32x32x16_bf16 v[0:15], v[224:227], v[68:71], v[0:15]
	ds_read2_b64 v[224:227], v73 offset0:12 offset1:14
	v_cmp_le_i32_e64 s[0:1], 8, v250
	v_cmp_le_i32_e64 s[4:5], 9, v250
	v_exp_f32_e32 v52, v52
	v_exp_f32_e32 v53, v53
	v_cndmask_b32_e64 v50, 0, v50, s[6:7]
	v_cndmask_b32_e64 v51, 0, v51, s[48:49]
	v_add_f32_e32 v232, v232, v50
	v_add_f32_e32 v233, v233, v51
	v_cvt_pk_bf16_f32 v65, v50, v51
	v_mfma_f32_32x32x16_bf16 v[16:31], v[228:231], v[68:71], v[16:31]
	ds_read2_b64 v[228:231], v74 offset0:44 offset1:46
	v_cmp_le_i32_e64 s[6:7], 10, v250
	v_cmp_le_i32_e64 s[48:49], 11, v250
	v_exp_f32_e32 v54, v54
	v_exp_f32_e32 v55, v55
	v_cndmask_b32_e64 v52, 0, v52, s[0:1]
	v_cndmask_b32_e64 v53, 0, v53, s[4:5]
	v_add_f32_e32 v232, v232, v52
	v_add_f32_e32 v233, v233, v53
	v_cvt_pk_bf16_f32 v66, v52, v53
	v_cndmask_b32_e64 v54, 0, v54, s[6:7]
	v_cndmask_b32_e64 v55, 0, v55, s[48:49]
	v_add_f32_e32 v232, v232, v54
	v_add_f32_e32 v233, v233, v55
	v_cvt_pk_bf16_f32 v67, v54, v55
	v_cmp_le_i32_e64 s[0:1], 16, v250
	v_cmp_le_i32_e64 s[4:5], 17, v250
	v_exp_f32_e32 v56, v56
	v_exp_f32_e32 v57, v57
	v_cmp_le_i32_e64 s[6:7], 18, v250
	v_cmp_le_i32_e64 s[48:49], 19, v250
	v_exp_f32_e32 v58, v58
	v_exp_f32_e32 v59, v59
	v_cndmask_b32_e64 v56, 0, v56, s[0:1]
	v_cndmask_b32_e64 v57, 0, v57, s[4:5]
	v_add_f32_e32 v232, v232, v56
	v_add_f32_e32 v233, v233, v57
	v_cvt_pk_bf16_f32 v68, v56, v57
	s_waitcnt lgkmcnt(3)
	v_mfma_f32_32x32x16_bf16 v[0:15], v[216:219], v[64:67], v[0:15]
	v_cmp_le_i32_e64 s[0:1], 24, v250
	v_cmp_le_i32_e64 s[4:5], 25, v250
	v_exp_f32_e32 v60, v60
	v_exp_f32_e32 v61, v61
	v_cndmask_b32_e64 v58, 0, v58, s[6:7]
	v_cndmask_b32_e64 v59, 0, v59, s[48:49]
	v_add_f32_e32 v232, v232, v58
	v_add_f32_e32 v233, v233, v59
	v_cvt_pk_bf16_f32 v69, v58, v59
	s_waitcnt lgkmcnt(2)
	v_mfma_f32_32x32x16_bf16 v[16:31], v[220:223], v[64:67], v[16:31]
	v_cmp_le_i32_e64 s[6:7], 26, v250
	v_cmp_le_i32_e64 s[48:49], 27, v250
	v_exp_f32_e32 v62, v62
	v_exp_f32_e32 v63, v63
	v_cndmask_b32_e64 v60, 0, v60, s[0:1]
	v_cndmask_b32_e64 v61, 0, v61, s[4:5]
	v_add_f32_e32 v232, v232, v60
	v_add_f32_e32 v233, v233, v61
	v_cvt_pk_bf16_f32 v70, v60, v61
	v_cndmask_b32_e64 v62, 0, v62, s[6:7]
	v_cndmask_b32_e64 v63, 0, v63, s[48:49]
	v_add_f32_e32 v232, v232, v62
	v_add_f32_e32 v233, v233, v63
	v_cvt_pk_bf16_f32 v71, v62, v63
	s_nop 1
	s_waitcnt lgkmcnt(1)
	v_mfma_f32_32x32x16_bf16 v[0:15], v[224:227], v[68:71], v[0:15]
	s_waitcnt lgkmcnt(0)
	v_mfma_f32_32x32x16_bf16 v[16:31], v[228:231], v[68:71], v[16:31]
	v_add_f32_e32 v232, v232, v233
	v_add_f32_e32 v112, v112, v232
	s_branch .Lt1_join
; #define LAS __attribute__((address_space(3)))
; #define MFMA32(a, b, c) __builtin_amdgcn_mfma_f32_32x32x16_bf16((a), (b), (c), 0, 0, 0)
; __device__ __forceinline__ float ex2(float x) { return __builtin_amdgcn_exp2f(x); }
; template <int MODE>
; __device__ __forceinline__ void attn_tile(const LAS unsigned char* Kb, const LAS unsigned char* Vb, const bf16x8_t (&qf)[4], f32x16 (&oacc)[2], float& l_run,
;                                           int r, int h, int dlt0, int dlt1, bool hiw) {
;     ...
; #pragma unroll
;     for (int mt = 0; mt < 4; ++mt) {
;         if (mt == 0) { if (hiw) __builtin_amdgcn_s_setprio(1); else __builtin_amdgcn_s_setprio(0); }
;         if (mt == 2) { if (hiw) __builtin_amdgcn_s_setprio(0); else __builtin_amdgcn_s_setprio(1); }
;         const int dl = mt < 2 ? dlt0 : dlt1;
;         f32x16 sacc = zero16();
; #pragma unroll
;         for (int ks = 0; ks < 4; ++ks) { const bf16x8_t ka = *(const LAS bf16x8_t*)(Kb + (32 * mt + r) * A_KSTR + 32 * ks + 16 * h); sacc = MFMA32(ka, qf[ks], sacc); }
; #pragma unroll
;         for (int i = 0; i < 16; ++i) {
;             float p;
;             if (MODE == 2) p = ex2(sacc[i]);
;             else if (MODE == 3) p = ex2(sacc[i] + __int_as_float(dl));
;             else { const int ci = 32 * mt + (i & 3) + 8 * (i >> 2); p = ((unsigned)(dl - ci) < ulim) ? ex2(sacc[i]) : 0.f; }
;             sacc[i] = p; ls += p;
;         }
; #pragma unroll
;         for (int s = 0; s < 2; ++s) {
;             const bf16x8_t pf = pack8(sacc, 8 * s);
; #pragma unroll
;             for (int dt = 0; dt < 2; ++dt) {
;                 const LAS unsigned char* vp = Vb + (32 * dt + r) * A_CVSTR + (32 * mt + 16 * s + 4 * h) * 2;
;                 const s16x4_t lo = *(const LAS s16x4_t*)vp, hi = *(const LAS s16x4_t*)(vp + 16);
;                 oacc[dt] = MFMA32(__builtin_shufflevector(lo, hi, 0, 1, 2, 3, 4, 5, 6, 7), pf, oacc[dt]);
;             }
;         }
;     }
.Lt1_d2:
	ds_read_b128 v[200:203], v72 offset:0
	ds_read_b128 v[204:207], v72 offset:32
	ds_read_b128 v[208:211], v72 offset:64
	ds_read_b128 v[212:215], v72 offset:96
	ds_read2_b64 v[216:219], v73 offset0:0 offset1:2
	ds_read2_b64 v[220:223], v74 offset0:32 offset1:34
	ds_read2_b64 v[224:227], v73 offset0:4 offset1:6
	ds_read2_b64 v[228:231], v74 offset0:36 offset1:38
	s_waitcnt lgkmcnt(7)
	v_mfma_f32_32x32x16_bf16 v[32:47], v[200:203], v[80:83], 0
	ds_read_b128 v[200:203], v72 offset:4608
	s_waitcnt lgkmcnt(7)
	v_mfma_f32_32x32x16_bf16 v[32:47], v[204:207], v[84:87], v[32:47]
	ds_read_b128 v[204:207], v72 offset:4640
	s_waitcnt lgkmcnt(7)
	v_mfma_f32_32x32x16_bf16 v[32:47], v[208:211], v[88:91], v[32:47]
	ds_read_b128 v[208:211], v72 offset:4672
	s_waitcnt lgkmcnt(7)
	v_mfma_f32_32x32x16_bf16 v[32:47], v[212:215], v[92:95], v[32:47]
	ds_read_b128 v[212:215], v72 offset:4704
	s_nop 7
	s_nop 3
	s_waitcnt lgkmcnt(3)
	v_mfma_f32_32x32x16_bf16 v[48:63], v[200:203], v[80:83], 0
	ds_read_b128 v[200:203], v72 offset:9216
	v_exp_f32_e32 v32, v32
	v_exp_f32_e32 v33, v33
	s_waitcnt lgkmcnt(3)
	v_mfma_f32_32x32x16_bf16 v[48:63], v[204:207], v[84:87], v[48:63]
	ds_read_b128 v[204:207], v72 offset:9248
	v_exp_f32_e32 v34, v34
	v_exp_f32_e32 v35, v35
	v_mov_b32_e32 v232, v32
	v_mov_b32_e32 v233, v33
	v_cvt_pk_bf16_f32 v64, v32, v33
	v_exp_f32_e32 v36, v36
	v_exp_f32_e32 v37, v37
	v_add_f32_e32 v232, v232, v34
	v_add_f32_e32 v233, v233, v35
	v_cvt_pk_bf16_f32 v65, v34, v35
	v_exp_f32_e32 v38, v38
	v_exp_f32_e32 v39, v39
	v_add_f32_e32 v232, v232, v36
	v_add_f32_e32 v233, v233, v37
	v_cvt_pk_bf16_f32 v66, v36, v37
	v_add_f32_e32 v232, v232, v38
	v_add_f32_e32 v233, v233, v39
	v_cvt_pk_bf16_f32 v67, v38, v39
	s_waitcnt lgkmcnt(3)
	v_mfma_f32_32x32x16_bf16 v[48:63], v[208:211], v[88:91], v[48:63]
	ds_read_b128 v[208:211], v72 offset:9280
	v_exp_f32_e32 v40, v40
	v_exp_f32_e32 v41, v41
	s_waitcnt lgkmcnt(3)
	v_mfma_f32_32x32x16_bf16 v[48:63], v[212:215], v[92:95], v[48:63]
	ds_read_b128 v[212:215], v72 offset:9312
	v_exp_f32_e32 v42, v42
	v_exp_f32_e32 v43, v43
	v_add_f32_e32 v232, v232, v40
	v_add_f32_e32 v233, v233, v41
	v_cvt_pk_bf16_f32 v68, v40, v41
	v_mfma_f32_32x32x16_bf16 v[0:15], v[216:219], v[64:67], v[0:15]
	ds_read2_b64 v[216:219], v73 offset0:8 offset1:10
	v_exp_f32_e32 v44, v44
	v_exp_f32_e32 v45, v45
	v_add_f32_e32 v232, v232, v42
	v_add_f32_e32 v233, v233, v43
	v_cvt_pk_bf16_f32 v69, v42, v43
	v_mfma_f32_32x32x16_bf16 v[16:31], v[220:223], v[64:67], v[16:31]
	ds_read2_b64 v[220:223], v74 offset0:40 offset1:42
	v_exp_f32_e32 v46, v46
	v_exp_f32_e32 v47, v47
	v_add_f32_e32 v232, v232, v44
	v_add_f32_e32 v233, v233, v45
	v_cvt_pk_bf16_f32 v70, v44, v45
	v_add_f32_e32 v232, v232, v46
	v_add_f32_e32 v233, v233, v47
	v_cvt_pk_bf16_f32 v71, v46, v47
	s_waitcnt lgkmcnt(5)
	v_mfma_f32_32x32x16_bf16 v[32:47], v[200:203], v[80:83], 0
	v_exp_f32_e32 v48, v48
	v_exp_f32_e32 v49, v49
	s_waitcnt lgkmcnt(4)
	v_mfma_f32_32x32x16_bf16 v[32:47], v[204:207], v[84:87], v[32:47]
	v_exp_f32_e32 v50, v50
	v_exp_f32_e32 v51, v51
	v_add_f32_e32 v232, v232, v48
	v_add_f32_e32 v233, v233, v49
	v_cvt_pk_bf16_f32 v64, v48, v49
	v_mfma_f32_32x32x16_bf16 v[0:15], v[224:227], v[68:71], v[0:15]
	ds_read2_b64 v[224:227], v73 offset0:12 offset1:14
	v_exp_f32_e32 v52, v52
	v_exp_f32_e32 v53, v53
	v_add_f32_e32 v232, v232, v50
	v_add_f32_e32 v233, v233, v51
	v_cvt_pk_bf16_f32 v65, v50, v51
	v_mfma_f32_32x32x16_bf16 v[16:31], v[228:231], v[68:71], v[16:31]
	ds_read2_b64 v[228:231], v74 offset0:44 offset1:46
	v_exp_f32_e32 v54, v54
	v_exp_f32_e32 v55, v55
	v_add_f32_e32 v232, v232, v52
	v_add_f32_e32 v233, v233, v53
	v_cvt_pk_bf16_f32 v66, v52, v53
	v_add_f32_e32 v232, v232, v54
	v_add_f32_e32 v233, v233, v55
	v_cvt_pk_bf16_f32 v67, v54, v55
	s_cmp_eq_u32 s45, 0
	s_cbranch_scc1 .Lt1_d2_nostage
	s_waitcnt vmcnt(3)
	ds_write_b128 v251, v[96:99]
	s_waitcnt vmcnt(2)
	ds_write_b128 v251, v[100:103] offset:9216
	s_waitcnt vmcnt(1)
	ds_write2_b64 v252, v[104:105], v[106:107] offset1:1
	s_waitcnt vmcnt(0)
	ds_write2_b64 v252, v[108:109], v[110:111] offset0:16 offset1:17
	s_mov_b32 s47, 1
.Lt1_d2_nostage:
	s_waitcnt lgkmcnt(5)
	v_mfma_f32_32x32x16_bf16 v[32:47], v[208:211], v[88:91], v[32:47]
	v_exp_f32_e32 v56, v56
	v_exp_f32_e32 v57, v57
	s_waitcnt lgkmcnt(4)
	v_mfma_f32_32x32x16_bf16 v[32:47], v[212:215], v[92:95], v[32:47]
	v_exp_f32_e32 v58, v58
	v_exp_f32_e32 v59, v59
	v_add_f32_e32 v232, v232, v56
	v_add_f32_e32 v233, v233, v57
	v_cvt_pk_bf16_f32 v68, v56, v57
	s_waitcnt lgkmcnt(3)
	v_mfma_f32_32x32x16_bf16 v[0:15], v[216:219], v[64:67], v[0:15]
	ds_read2_b64 v[216:219], v73 offset0:16 offset1:18
	v_exp_f32_e32 v60, v60
	v_exp_f32_e32 v61, v61
	v_add_f32_e32 v232, v232, v58
	v_add_f32_e32 v233, v233, v59
	v_cvt_pk_bf16_f32 v69, v58, v59
	s_waitcnt lgkmcnt(3)
	v_mfma_f32_32x32x16_bf16 v[16:31], v[220:223], v[64:67], v[16:31]
	ds_read2_b64 v[220:223], v74 offset0:48 offset1:50
	v_exp_f32_e32 v62, v62
	v_exp_f32_e32 v63, v63
	v_add_f32_e32 v232, v232, v60
	v_add_f32_e32 v233, v233, v61
	v_cvt_pk_bf16_f32 v70, v60, v61
	v_add_f32_e32 v232, v232, v62
	v_add_f32_e32 v233, v233, v63
	v_cvt_pk_bf16_f32 v71, v62, v63
	v_cmp_le_i32_e64 s[0:1], 0, v250
	v_cmp_le_i32_e64 s[4:5], 1, v250
	v_exp_f32_e32 v32, v32
	v_exp_f32_e32 v33, v33
	v_cmp_le_i32_e64 s[6:7], 2, v250
	v_cmp_le_i32_e64 s[48:49], 3, v250
	v_exp_f32_e32 v34, v34
	v_exp_f32_e32 v35, v35
	v_cndmask_b32_e64 v32, 0, v32, s[0:1]
	v_cndmask_b32_e64 v33, 0, v33, s[4:5]
	v_add_f32_e32 v232, v232, v32
	v_add_f32_e32 v233, v233, v33
	v_cvt_pk_bf16_f32 v64, v32, v33
	s_waitcnt lgkmcnt(3)
; #define LAS __attribute__((address_space(3)))
; #define MFMA32(a, b, c) __builtin_amdgcn_mfma_f32_32x32x16_bf16((a), (b), (c), 0, 0, 0)
; __device__ __forceinline__ float ex2(float x) { return __builtin_amdgcn_exp2f(x); }
; template <int MODE>
; __device__ __forceinline__ void attn_tile(const LAS unsigned char* Kb, const LAS unsigned char* Vb, const bf16x8_t (&qf)[4], f32x16 (&oacc)[2], float& l_run,
;                                           int r, int h, int dlt0, int dlt1, bool hiw) {
;     ...
; #pragma unroll
;     for (int mt = 0; mt < 4; ++mt) {
;         if (mt == 0) { if (hiw) __builtin_amdgcn_s_setprio(1); else __builtin_amdgcn_s_setprio(0); }
;         if (mt == 2) { if (hiw) __builtin_amdgcn_s_setprio(0); else __builtin_amdgcn_s_setprio(1); }
;         const int dl = mt < 2 ? dlt0 : dlt1;
;         f32x16 sacc = zero16();
; #pragma unroll
;         for (int ks = 0; ks < 4; ++ks) { const bf16x8_t ka = *(const LAS bf16x8_t*)(Kb + (32 * mt + r) * A_KSTR + 32 * ks + 16 * h); sacc = MFMA32(ka, qf[ks], sacc); }
; #pragma unroll
;         for (int i = 0; i < 16; ++i) {
;             float p;
;             if (MODE == 2) p = ex2(sacc[i]);
;             else if (MODE == 3) p = ex2(sacc[i] + __int_as_float(dl));
;             else { const int ci = 32 * mt + (i & 3) + 8 * (i >> 2); p = ((unsigned)(dl - ci) < ulim) ? ex2(sacc[i]) : 0.f; }
;             sacc[i] = p; ls += p;
;         }
; #pragma unroll
;         for (int s = 0; s < 2; ++s) {
;             const bf16x8_t pf = pack8(sacc, 8 * s);
; #pragma unroll
;             for (int dt = 0; dt < 2; ++dt) {
;                 const LAS unsigned char* vp = Vb + (32 * dt + r) * A_CVSTR + (32 * mt + 16 * s + 4 * h) * 2;
;                 const s16x4_t lo = *(const LAS s16x4_t*)vp, hi = *(const LAS s16x4_t*)(vp + 16);
;                 oacc[dt] = MFMA32(__builtin_shufflevector(lo, hi, 0, 1, 2, 3, 4, 5, 6, 7), pf, oacc[dt]);
;             }
;         }
;     }
;     l_run += ls;
; }
	v_mfma_f32_32x32x16_bf16 v[0:15], v[224:227], v[68:71], v[0:15]
	ds_read2_b64 v[224:227], v73 offset0:20 offset1:22
	v_cmp_le_i32_e64 s[0:1], 8, v250
	v_cmp_le_i32_e64 s[4:5], 9, v250
	v_exp_f32_e32 v36, v36
	v_exp_f32_e32 v37, v37
	v_cndmask_b32_e64 v34, 0, v34, s[6:7]
	v_cndmask_b32_e64 v35, 0, v35, s[48:49]
	v_add_f32_e32 v232, v232, v34
	v_add_f32_e32 v233, v233, v35
	v_cvt_pk_bf16_f32 v65, v34, v35
	s_waitcnt lgkmcnt(3)
	v_mfma_f32_32x32x16_bf16 v[16:31], v[228:231], v[68:71], v[16:31]
	ds_read2_b64 v[228:231], v74 offset0:52 offset1:54
	v_cmp_le_i32_e64 s[6:7], 10, v250
	v_cmp_le_i32_e64 s[48:49], 11, v250
	v_exp_f32_e32 v38, v38
	v_exp_f32_e32 v39, v39
	v_cndmask_b32_e64 v36, 0, v36, s[0:1]
	v_cndmask_b32_e64 v37, 0, v37, s[4:5]
	v_add_f32_e32 v232, v232, v36
	v_add_f32_e32 v233, v233, v37
	v_cvt_pk_bf16_f32 v66, v36, v37
	v_cndmask_b32_e64 v38, 0, v38, s[6:7]
	v_cndmask_b32_e64 v39, 0, v39, s[48:49]
	v_add_f32_e32 v232, v232, v38
	v_add_f32_e32 v233, v233, v39
	v_cvt_pk_bf16_f32 v67, v38, v39
	v_cmp_le_i32_e64 s[0:1], 16, v250
	v_cmp_le_i32_e64 s[4:5], 17, v250
	v_exp_f32_e32 v40, v40
	v_exp_f32_e32 v41, v41
	v_cmp_le_i32_e64 s[6:7], 18, v250
	v_cmp_le_i32_e64 s[48:49], 19, v250
	v_exp_f32_e32 v42, v42
	v_exp_f32_e32 v43, v43
	v_cndmask_b32_e64 v40, 0, v40, s[0:1]
	v_cndmask_b32_e64 v41, 0, v41, s[4:5]
	v_add_f32_e32 v232, v232, v40
	v_add_f32_e32 v233, v233, v41
	v_cvt_pk_bf16_f32 v68, v40, v41
	s_waitcnt lgkmcnt(3)
	v_mfma_f32_32x32x16_bf16 v[0:15], v[216:219], v[64:67], v[0:15]
	v_cmp_le_i32_e64 s[0:1], 24, v250
	v_cmp_le_i32_e64 s[4:5], 25, v250
	v_exp_f32_e32 v44, v44
	v_exp_f32_e32 v45, v45
	v_cndmask_b32_e64 v42, 0, v42, s[6:7]
	v_cndmask_b32_e64 v43, 0, v43, s[48:49]
	v_add_f32_e32 v232, v232, v42
	v_add_f32_e32 v233, v233, v43
	v_cvt_pk_bf16_f32 v69, v42, v43
	s_waitcnt lgkmcnt(2)
	v_mfma_f32_32x32x16_bf16 v[16:31], v[220:223], v[64:67], v[16:31]
	v_cmp_le_i32_e64 s[6:7], 26, v250
	v_cmp_le_i32_e64 s[48:49], 27, v250
	v_exp_f32_e32 v46, v46
	v_exp_f32_e32 v47, v47
	v_cndmask_b32_e64 v44, 0, v44, s[0:1]
	v_cndmask_b32_e64 v45, 0, v45, s[4:5]
	v_add_f32_e32 v232, v232, v44
	v_add_f32_e32 v233, v233, v45
	v_cvt_pk_bf16_f32 v70, v44, v45
	v_cndmask_b32_e64 v46, 0, v46, s[6:7]
	v_cndmask_b32_e64 v47, 0, v47, s[48:49]
	v_add_f32_e32 v232, v232, v46
	v_add_f32_e32 v233, v233, v47
	v_cvt_pk_bf16_f32 v71, v46, v47
	s_nop 1
	s_waitcnt lgkmcnt(1)
	v_mfma_f32_32x32x16_bf16 v[0:15], v[224:227], v[68:71], v[0:15]
	s_waitcnt lgkmcnt(0)
	v_mfma_f32_32x32x16_bf16 v[16:31], v[228:231], v[68:71], v[16:31]
	v_add_f32_e32 v232, v232, v233
	v_add_f32_e32 v112, v112, v232
	s_branch .Lt1_join
.Lt1_d3:
	ds_read_b128 v[200:203], v72 offset:0
	ds_read_b128 v[204:207], v72 offset:32
	ds_read_b128 v[208:211], v72 offset:64
	ds_read_b128 v[212:215], v72 offset:96
	ds_read2_b64 v[216:219], v73 offset0:0 offset1:2
	ds_read2_b64 v[220:223], v74 offset0:32 offset1:34
	ds_read2_b64 v[224:227], v73 offset0:4 offset1:6
	ds_read2_b64 v[228:231], v74 offset0:36 offset1:38
	s_waitcnt lgkmcnt(7)
	v_mfma_f32_32x32x16_bf16 v[32:47], v[200:203], v[80:83], 0
	ds_read_b128 v[200:203], v72 offset:4608
	s_waitcnt lgkmcnt(7)
	v_mfma_f32_32x32x16_bf16 v[32:47], v[204:207], v[84:87], v[32:47]
	ds_read_b128 v[204:207], v72 offset:4640
	s_waitcnt lgkmcnt(7)
	v_mfma_f32_32x32x16_bf16 v[32:47], v[208:211], v[88:91], v[32:47]
	ds_read_b128 v[208:211], v72 offset:4672
	s_waitcnt lgkmcnt(7)
	v_mfma_f32_32x32x16_bf16 v[32:47], v[212:215], v[92:95], v[32:47]
	ds_read_b128 v[212:215], v72 offset:4704
	s_nop 7
	s_nop 3
	s_waitcnt lgkmcnt(3)
	v_mfma_f32_32x32x16_bf16 v[48:63], v[200:203], v[80:83], 0
	ds_read_b128 v[200:203], v72 offset:9216
	v_exp_f32_e32 v32, v32
	v_exp_f32_e32 v33, v33
	s_waitcnt lgkmcnt(3)
	v_mfma_f32_32x32x16_bf16 v[48:63], v[204:207], v[84:87], v[48:63]
	ds_read_b128 v[204:207], v72 offset:9248
	v_exp_f32_e32 v34, v34
	v_exp_f32_e32 v35, v35
	v_mov_b32_e32 v232, v32
	v_mov_b32_e32 v233, v33
	v_cvt_pk_bf16_f32 v64, v32, v33
	v_exp_f32_e32 v36, v36
	v_exp_f32_e32 v37, v37
	v_add_f32_e32 v232, v232, v34
	v_add_f32_e32 v233, v233, v35
	v_cvt_pk_bf16_f32 v65, v34, v35
	v_exp_f32_e32 v38, v38
	v_exp_f32_e32 v39, v39
	v_add_f32_e32 v232, v232, v36
	v_add_f32_e32 v233, v233, v37
	v_cvt_pk_bf16_f32 v66, v36, v37
	v_add_f32_e32 v232, v232, v38
	v_add_f32_e32 v233, v233, v39
	v_cvt_pk_bf16_f32 v67, v38, v39
	s_waitcnt lgkmcnt(3)
	v_mfma_f32_32x32x16_bf16 v[48:63], v[208:211], v[88:91], v[48:63]
	ds_read_b128 v[208:211], v72 offset:9280
	v_exp_f32_e32 v40, v40
	v_exp_f32_e32 v41, v41
	s_waitcnt lgkmcnt(3)
	v_mfma_f32_32x32x16_bf16 v[48:63], v[212:215], v[92:95], v[48:63]
	ds_read_b128 v[212:215], v72 offset:9312
	v_exp_f32_e32 v42, v42
	v_exp_f32_e32 v43, v43
	v_add_f32_e32 v232, v232, v40
	v_add_f32_e32 v233, v233, v41
	v_cvt_pk_bf16_f32 v68, v40, v41
	v_mfma_f32_32x32x16_bf16 v[0:15], v[216:219], v[64:67], v[0:15]
	ds_read2_b64 v[216:219], v73 offset0:8 offset1:10
	v_exp_f32_e32 v44, v44
	v_exp_f32_e32 v45, v45
	v_add_f32_e32 v232, v232, v42
	v_add_f32_e32 v233, v233, v43
	v_cvt_pk_bf16_f32 v69, v42, v43
	v_mfma_f32_32x32x16_bf16 v[16:31], v[220:223], v[64:67], v[16:31]
	ds_read2_b64 v[220:223], v74 offset0:40 offset1:42
	v_exp_f32_e32 v46, v46
	v_exp_f32_e32 v47, v47
	v_add_f32_e32 v232, v232, v44
	v_add_f32_e32 v233, v233, v45
	v_cvt_pk_bf16_f32 v70, v44, v45
	v_add_f32_e32 v232, v232, v46
	v_add_f32_e32 v233, v233, v47
	v_cvt_pk_bf16_f32 v71, v46, v47
	s_waitcnt lgkmcnt(5)
	v_mfma_f32_32x32x16_bf16 v[32:47], v[200:203], v[80:83], 0
	ds_read_b128 v[200:203], v72 offset:13824
	v_exp_f32_e32 v48, v48
	v_exp_f32_e32 v49, v49
	s_waitcnt lgkmcnt(5)
; #define LAS __attribute__((address_space(3)))
; #define MFMA32(a, b, c) __builtin_amdgcn_mfma_f32_32x32x16_bf16((a), (b), (c), 0, 0, 0)
; __device__ __forceinline__ float ex2(float x) { return __builtin_amdgcn_exp2f(x); }
; template <int MODE>
; __device__ __forceinline__ void attn_tile(const LAS unsigned char* Kb, const LAS unsigned char* Vb, const bf16x8_t (&qf)[4], f32x16 (&oacc)[2], float& l_run,
;                                           int r, int h, int dlt0, int dlt1, bool hiw) {
;     ...
; #pragma unroll
;     for (int mt = 0; mt < 4; ++mt) {
;         if (mt == 0) { if (hiw) __builtin_amdgcn_s_setprio(1); else __builtin_amdgcn_s_setprio(0); }
;         if (mt == 2) { if (hiw) __builtin_amdgcn_s_setprio(0); else __builtin_amdgcn_s_setprio(1); }
;         const int dl = mt < 2 ? dlt0 : dlt1;
;         f32x16 sacc = zero16();
; #pragma unroll
;         for (int ks = 0; ks < 4; ++ks) { const bf16x8_t ka = *(const LAS bf16x8_t*)(Kb + (32 * mt + r) * A_KSTR + 32 * ks + 16 * h); sacc = MFMA32(ka, qf[ks], sacc); }
; #pragma unroll
;         for (int i = 0; i < 16; ++i) {
;             float p;
;             if (MODE == 2) p = ex2(sacc[i]);
;             else if (MODE == 3) p = ex2(sacc[i] + __int_as_float(dl));
;             else { const int ci = 32 * mt + (i & 3) + 8 * (i >> 2); p = ((unsigned)(dl - ci) < ulim) ? ex2(sacc[i]) : 0.f; }
;             sacc[i] = p; ls += p;
;         }
; #pragma unroll
;         for (int s = 0; s < 2; ++s) {
;             const bf16x8_t pf = pack8(sacc, 8 * s);
; #pragma unroll
;             for (int dt = 0; dt < 2; ++dt) {
;                 const LAS unsigned char* vp = Vb + (32 * dt + r) * A_CVSTR + (32 * mt + 16 * s + 4 * h) * 2;
;                 const s16x4_t lo = *(const LAS s16x4_t*)vp, hi = *(const LAS s16x4_t*)(vp + 16);
;                 oacc[dt] = MFMA32(__builtin_shufflevector(lo, hi, 0, 1, 2, 3, 4, 5, 6, 7), pf, oacc[dt]);
;             }
;         }
;     }
;     l_run += ls;
; }
	v_mfma_f32_32x32x16_bf16 v[32:47], v[204:207], v[84:87], v[32:47]
	ds_read_b128 v[204:207], v72 offset:13856
	v_exp_f32_e32 v50, v50
	v_exp_f32_e32 v51, v51
	v_add_f32_e32 v232, v232, v48
	v_add_f32_e32 v233, v233, v49
	v_cvt_pk_bf16_f32 v64, v48, v49
	v_mfma_f32_32x32x16_bf16 v[0:15], v[224:227], v[68:71], v[0:15]
	ds_read2_b64 v[224:227], v73 offset0:12 offset1:14
	v_exp_f32_e32 v52, v52
	v_exp_f32_e32 v53, v53
	v_add_f32_e32 v232, v232, v50
	v_add_f32_e32 v233, v233, v51
	v_cvt_pk_bf16_f32 v65, v50, v51
	v_mfma_f32_32x32x16_bf16 v[16:31], v[228:231], v[68:71], v[16:31]
	ds_read2_b64 v[228:231], v74 offset0:44 offset1:46
	v_exp_f32_e32 v54, v54
	v_exp_f32_e32 v55, v55
	v_add_f32_e32 v232, v232, v52
	v_add_f32_e32 v233, v233, v53
	v_cvt_pk_bf16_f32 v66, v52, v53
	v_add_f32_e32 v232, v232, v54
	v_add_f32_e32 v233, v233, v55
	v_cvt_pk_bf16_f32 v67, v54, v55
	s_waitcnt lgkmcnt(7)
	v_mfma_f32_32x32x16_bf16 v[32:47], v[208:211], v[88:91], v[32:47]
	ds_read_b128 v[208:211], v72 offset:13888
	v_exp_f32_e32 v56, v56
	v_exp_f32_e32 v57, v57
	s_waitcnt lgkmcnt(7)
	v_mfma_f32_32x32x16_bf16 v[32:47], v[212:215], v[92:95], v[32:47]
	ds_read_b128 v[212:215], v72 offset:13920
	v_exp_f32_e32 v58, v58
	v_exp_f32_e32 v59, v59
	v_add_f32_e32 v232, v232, v56
	v_add_f32_e32 v233, v233, v57
	v_cvt_pk_bf16_f32 v68, v56, v57
	s_waitcnt lgkmcnt(7)
	v_mfma_f32_32x32x16_bf16 v[0:15], v[216:219], v[64:67], v[0:15]
	ds_read2_b64 v[216:219], v73 offset0:16 offset1:18
	v_exp_f32_e32 v60, v60
	v_exp_f32_e32 v61, v61
	v_add_f32_e32 v232, v232, v58
	v_add_f32_e32 v233, v233, v59
	v_cvt_pk_bf16_f32 v69, v58, v59
	s_waitcnt lgkmcnt(7)
	v_mfma_f32_32x32x16_bf16 v[16:31], v[220:223], v[64:67], v[16:31]
	ds_read2_b64 v[220:223], v74 offset0:48 offset1:50
	v_exp_f32_e32 v62, v62
	v_exp_f32_e32 v63, v63
	v_add_f32_e32 v232, v232, v60
	v_add_f32_e32 v233, v233, v61
	v_cvt_pk_bf16_f32 v70, v60, v61
	v_add_f32_e32 v232, v232, v62
	v_add_f32_e32 v233, v233, v63
	v_cvt_pk_bf16_f32 v71, v62, v63
	s_waitcnt lgkmcnt(7)
	v_mfma_f32_32x32x16_bf16 v[48:63], v[200:203], v[80:83], 0
	v_exp_f32_e32 v32, v32
	v_exp_f32_e32 v33, v33
	s_waitcnt lgkmcnt(6)
	v_mfma_f32_32x32x16_bf16 v[48:63], v[204:207], v[84:87], v[48:63]
	v_exp_f32_e32 v34, v34
	v_exp_f32_e32 v35, v35
	v_add_f32_e32 v232, v232, v32
	v_add_f32_e32 v233, v233, v33
	v_cvt_pk_bf16_f32 v64, v32, v33
	s_waitcnt lgkmcnt(5)
	v_mfma_f32_32x32x16_bf16 v[0:15], v[224:227], v[68:71], v[0:15]
	ds_read2_b64 v[224:227], v73 offset0:20 offset1:22
	v_exp_f32_e32 v36, v36
	v_exp_f32_e32 v37, v37
	v_add_f32_e32 v232, v232, v34
	v_add_f32_e32 v233, v233, v35
	v_cvt_pk_bf16_f32 v65, v34, v35
	s_waitcnt lgkmcnt(5)
	v_mfma_f32_32x32x16_bf16 v[16:31], v[228:231], v[68:71], v[16:31]
	ds_read2_b64 v[228:231], v74 offset0:52 offset1:54
	v_exp_f32_e32 v38, v38
	v_exp_f32_e32 v39, v39
	v_add_f32_e32 v232, v232, v36
	v_add_f32_e32 v233, v233, v37
	v_cvt_pk_bf16_f32 v66, v36, v37
	v_add_f32_e32 v232, v232, v38
	v_add_f32_e32 v233, v233, v39
	v_cvt_pk_bf16_f32 v67, v38, v39
	s_cmp_eq_u32 s45, 0
	s_cbranch_scc1 .Lt1_d3_nostage
	s_waitcnt vmcnt(3)
	ds_write_b128 v251, v[96:99]
	s_waitcnt vmcnt(2)
	ds_write_b128 v251, v[100:103] offset:9216
	s_waitcnt vmcnt(1)
	ds_write2_b64 v252, v[104:105], v[106:107] offset1:1
	s_waitcnt vmcnt(0)
	ds_write2_b64 v252, v[108:109], v[110:111] offset0:16 offset1:17
	s_mov_b32 s47, 1
.Lt1_d3_nostage:
	s_waitcnt lgkmcnt(5)
	v_mfma_f32_32x32x16_bf16 v[48:63], v[208:211], v[88:91], v[48:63]
	v_exp_f32_e32 v40, v40
	v_exp_f32_e32 v41, v41
	s_waitcnt lgkmcnt(4)
	v_mfma_f32_32x32x16_bf16 v[48:63], v[212:215], v[92:95], v[48:63]
	v_exp_f32_e32 v42, v42
	v_exp_f32_e32 v43, v43
	v_add_f32_e32 v232, v232, v40
	v_add_f32_e32 v233, v233, v41
	v_cvt_pk_bf16_f32 v68, v40, v41
	s_waitcnt lgkmcnt(3)
	v_mfma_f32_32x32x16_bf16 v[0:15], v[216:219], v[64:67], v[0:15]
	ds_read2_b64 v[216:219], v73 offset0:24 offset1:26
	v_exp_f32_e32 v44, v44
	v_exp_f32_e32 v45, v45
	v_add_f32_e32 v232, v232, v42
	v_add_f32_e32 v233, v233, v43
	v_cvt_pk_bf16_f32 v69, v42, v43
	s_waitcnt lgkmcnt(3)
	v_mfma_f32_32x32x16_bf16 v[16:31], v[220:223], v[64:67], v[16:31]
	ds_read2_b64 v[220:223], v74 offset0:56 offset1:58
	v_exp_f32_e32 v46, v46
	v_exp_f32_e32 v47, v47
	v_add_f32_e32 v232, v232, v44
	v_add_f32_e32 v233, v233, v45
	v_cvt_pk_bf16_f32 v70, v44, v45
	v_add_f32_e32 v232, v232, v46
	v_add_f32_e32 v233, v233, v47
	v_cvt_pk_bf16_f32 v71, v46, v47
	v_cmp_le_i32_e64 s[0:1], 0, v250
	v_cmp_le_i32_e64 s[4:5], 1, v250
	v_exp_f32_e32 v48, v48
	v_exp_f32_e32 v49, v49
	v_cmp_le_i32_e64 s[6:7], 2, v250
	v_cmp_le_i32_e64 s[48:49], 3, v250
	v_exp_f32_e32 v50, v50
	v_exp_f32_e32 v51, v51
	v_cndmask_b32_e64 v48, 0, v48, s[0:1]
	v_cndmask_b32_e64 v49, 0, v49, s[4:5]
	v_add_f32_e32 v232, v232, v48
	v_add_f32_e32 v233, v233, v49
	v_cvt_pk_bf16_f32 v64, v48, v49
	s_waitcnt lgkmcnt(3)
	v_mfma_f32_32x32x16_bf16 v[0:15], v[224:227], v[68:71], v[0:15]
	ds_read2_b64 v[224:227], v73 offset0:28 offset1:30
	v_cmp_le_i32_e64 s[0:1], 8, v250
	v_cmp_le_i32_e64 s[4:5], 9, v250
	v_exp_f32_e32 v52, v52
	v_exp_f32_e32 v53, v53
	v_cndmask_b32_e64 v50, 0, v50, s[6:7]
	v_cndmask_b32_e64 v51, 0, v51, s[48:49]
	v_add_f32_e32 v232, v232, v50
	v_add_f32_e32 v233, v233, v51
	v_cvt_pk_bf16_f32 v65, v50, v51
	s_waitcnt lgkmcnt(3)
; #define LAS __attribute__((address_space(3)))
; #define MFMA32(a, b, c) __builtin_amdgcn_mfma_f32_32x32x16_bf16((a), (b), (c), 0, 0, 0)
; __device__ __forceinline__ float ex2(float x) { return __builtin_amdgcn_exp2f(x); }
; template <int MODE>
; __device__ __forceinline__ void attn_tile(const LAS unsigned char* Kb, const LAS unsigned char* Vb, const bf16x8_t (&qf)[4], f32x16 (&oacc)[2], float& l_run,
;                                           int r, int h, int dlt0, int dlt1, bool hiw) {
;     ...
; #pragma unroll
;     for (int mt = 0; mt < 4; ++mt) {
;         if (mt == 0) { if (hiw) __builtin_amdgcn_s_setprio(1); else __builtin_amdgcn_s_setprio(0); }
;         if (mt == 2) { if (hiw) __builtin_amdgcn_s_setprio(0); else __builtin_amdgcn_s_setprio(1); }
;         const int dl = mt < 2 ? dlt0 : dlt1;
;         f32x16 sacc = zero16();
; #pragma unroll
;         for (int ks = 0; ks < 4; ++ks) { const bf16x8_t ka = *(const LAS bf16x8_t*)(Kb + (32 * mt + r) * A_KSTR + 32 * ks + 16 * h); sacc = MFMA32(ka, qf[ks], sacc); }
; #pragma unroll
;         for (int i = 0; i < 16; ++i) {
;             float p;
;             if (MODE == 2) p = ex2(sacc[i]);
;             else if (MODE == 3) p = ex2(sacc[i] + __int_as_float(dl));
;             else { const int ci = 32 * mt + (i & 3) + 8 * (i >> 2); p = ((unsigned)(dl - ci) < ulim) ? ex2(sacc[i]) : 0.f; }
;             sacc[i] = p; ls += p;
;         }
; #pragma unroll
;         for (int s = 0; s < 2; ++s) {
;             const bf16x8_t pf = pack8(sacc, 8 * s);
; #pragma unroll
;             for (int dt = 0; dt < 2; ++dt) {
;                 const LAS unsigned char* vp = Vb + (32 * dt + r) * A_CVSTR + (32 * mt + 16 * s + 4 * h) * 2;
;                 const s16x4_t lo = *(const LAS s16x4_t*)vp, hi = *(const LAS s16x4_t*)(vp + 16);
;                 oacc[dt] = MFMA32(__builtin_shufflevector(lo, hi, 0, 1, 2, 3, 4, 5, 6, 7), pf, oacc[dt]);
;             }
;         }
;     }
;     l_run += ls;
; }
	v_mfma_f32_32x32x16_bf16 v[16:31], v[228:231], v[68:71], v[16:31]
	ds_read2_b64 v[228:231], v74 offset0:60 offset1:62
	v_cmp_le_i32_e64 s[6:7], 10, v250
	v_cmp_le_i32_e64 s[48:49], 11, v250
	v_exp_f32_e32 v54, v54
	v_exp_f32_e32 v55, v55
	v_cndmask_b32_e64 v52, 0, v52, s[0:1]
	v_cndmask_b32_e64 v53, 0, v53, s[4:5]
	v_add_f32_e32 v232, v232, v52
	v_add_f32_e32 v233, v233, v53
	v_cvt_pk_bf16_f32 v66, v52, v53
	v_cndmask_b32_e64 v54, 0, v54, s[6:7]
	v_cndmask_b32_e64 v55, 0, v55, s[48:49]
	v_add_f32_e32 v232, v232, v54
	v_add_f32_e32 v233, v233, v55
	v_cvt_pk_bf16_f32 v67, v54, v55
	v_cmp_le_i32_e64 s[0:1], 16, v250
	v_cmp_le_i32_e64 s[4:5], 17, v250
	v_exp_f32_e32 v56, v56
	v_exp_f32_e32 v57, v57
	v_cmp_le_i32_e64 s[6:7], 18, v250
	v_cmp_le_i32_e64 s[48:49], 19, v250
	v_exp_f32_e32 v58, v58
	v_exp_f32_e32 v59, v59
	v_cndmask_b32_e64 v56, 0, v56, s[0:1]
	v_cndmask_b32_e64 v57, 0, v57, s[4:5]
	v_add_f32_e32 v232, v232, v56
	v_add_f32_e32 v233, v233, v57
	v_cvt_pk_bf16_f32 v68, v56, v57
	s_waitcnt lgkmcnt(3)
	v_mfma_f32_32x32x16_bf16 v[0:15], v[216:219], v[64:67], v[0:15]
	v_cmp_le_i32_e64 s[0:1], 24, v250
	v_cmp_le_i32_e64 s[4:5], 25, v250
	v_exp_f32_e32 v60, v60
	v_exp_f32_e32 v61, v61
	v_cndmask_b32_e64 v58, 0, v58, s[6:7]
	v_cndmask_b32_e64 v59, 0, v59, s[48:49]
	v_add_f32_e32 v232, v232, v58
	v_add_f32_e32 v233, v233, v59
	v_cvt_pk_bf16_f32 v69, v58, v59
	s_waitcnt lgkmcnt(2)
	v_mfma_f32_32x32x16_bf16 v[16:31], v[220:223], v[64:67], v[16:31]
	v_cmp_le_i32_e64 s[6:7], 26, v250
	v_cmp_le_i32_e64 s[48:49], 27, v250
	v_exp_f32_e32 v62, v62
	v_exp_f32_e32 v63, v63
	v_cndmask_b32_e64 v60, 0, v60, s[0:1]
	v_cndmask_b32_e64 v61, 0, v61, s[4:5]
	v_add_f32_e32 v232, v232, v60
	v_add_f32_e32 v233, v233, v61
	v_cvt_pk_bf16_f32 v70, v60, v61
	v_cndmask_b32_e64 v62, 0, v62, s[6:7]
	v_cndmask_b32_e64 v63, 0, v63, s[48:49]
	v_add_f32_e32 v232, v232, v62
	v_add_f32_e32 v233, v233, v63
	v_cvt_pk_bf16_f32 v71, v62, v63
	s_nop 1
	s_waitcnt lgkmcnt(1)
	v_mfma_f32_32x32x16_bf16 v[0:15], v[224:227], v[68:71], v[0:15]
	s_waitcnt lgkmcnt(0)
	v_mfma_f32_32x32x16_bf16 v[16:31], v[228:231], v[68:71], v[16:31]
	v_add_f32_e32 v232, v232, v233
	v_add_f32_e32 v112, v112, v232
	s_branch .Lt1_join
.Lt1_e0:
	ds_read_b128 v[200:203], v72 offset:0
	ds_read_b128 v[204:207], v72 offset:32
	ds_read_b128 v[208:211], v72 offset:64
	ds_read_b128 v[212:215], v72 offset:96
	ds_read2_b64 v[216:219], v73 offset0:0 offset1:2
	ds_read2_b64 v[220:223], v74 offset0:32 offset1:34
	ds_read2_b64 v[224:227], v73 offset0:4 offset1:6
	ds_read2_b64 v[228:231], v74 offset0:36 offset1:38
	s_waitcnt lgkmcnt(7)
	v_mfma_f32_32x32x16_bf16 v[32:47], v[200:203], v[80:83], 0
	ds_read_b128 v[200:203], v72 offset:4608
	s_waitcnt lgkmcnt(7)
	v_mfma_f32_32x32x16_bf16 v[32:47], v[204:207], v[84:87], v[32:47]
	ds_read_b128 v[204:207], v72 offset:4640
	s_waitcnt lgkmcnt(7)
	v_mfma_f32_32x32x16_bf16 v[32:47], v[208:211], v[88:91], v[32:47]
	ds_read_b128 v[208:211], v72 offset:4672
	s_waitcnt lgkmcnt(7)
	v_mfma_f32_32x32x16_bf16 v[32:47], v[212:215], v[92:95], v[32:47]
	ds_read_b128 v[212:215], v72 offset:4704
	s_nop 7
	s_nop 3
	s_waitcnt lgkmcnt(3)
	v_mfma_f32_32x32x16_bf16 v[48:63], v[200:203], v[80:83], 0
	ds_read_b128 v[200:203], v72 offset:9216
	v_cmp_le_i32_e64 s[0:1], 0, v250
	v_cmp_le_i32_e64 s[4:5], 1, v250
	v_exp_f32_e32 v32, v32
	v_exp_f32_e32 v33, v33
	s_waitcnt lgkmcnt(3)
	v_mfma_f32_32x32x16_bf16 v[48:63], v[204:207], v[84:87], v[48:63]
	ds_read_b128 v[204:207], v72 offset:9248
	v_cmp_le_i32_e64 s[6:7], 2, v250
	v_cmp_le_i32_e64 s[48:49], 3, v250
	v_exp_f32_e32 v34, v34
	v_exp_f32_e32 v35, v35
	v_cndmask_b32_e64 v32, v32, 0, s[0:1]
	v_cndmask_b32_e64 v33, v33, 0, s[4:5]
	v_mov_b32_e32 v232, v32
	v_mov_b32_e32 v233, v33
	v_cvt_pk_bf16_f32 v64, v32, v33
	v_cmp_le_i32_e64 s[0:1], 8, v250
	v_cmp_le_i32_e64 s[4:5], 9, v250
	v_exp_f32_e32 v36, v36
	v_exp_f32_e32 v37, v37
	v_cndmask_b32_e64 v34, v34, 0, s[6:7]
	v_cndmask_b32_e64 v35, v35, 0, s[48:49]
	v_add_f32_e32 v232, v232, v34
	v_add_f32_e32 v233, v233, v35
	v_cvt_pk_bf16_f32 v65, v34, v35
	v_cmp_le_i32_e64 s[6:7], 10, v250
	v_cmp_le_i32_e64 s[48:49], 11, v250
	v_exp_f32_e32 v38, v38
	v_exp_f32_e32 v39, v39
	v_cndmask_b32_e64 v36, v36, 0, s[0:1]
	v_cndmask_b32_e64 v37, v37, 0, s[4:5]
	v_add_f32_e32 v232, v232, v36
	v_add_f32_e32 v233, v233, v37
	v_cvt_pk_bf16_f32 v66, v36, v37
	v_cndmask_b32_e64 v38, v38, 0, s[6:7]
	v_cndmask_b32_e64 v39, v39, 0, s[48:49]
	v_add_f32_e32 v232, v232, v38
	v_add_f32_e32 v233, v233, v39
	v_cvt_pk_bf16_f32 v67, v38, v39
	s_waitcnt lgkmcnt(3)
	v_mfma_f32_32x32x16_bf16 v[48:63], v[208:211], v[88:91], v[48:63]
	ds_read_b128 v[208:211], v72 offset:9280
	v_cmp_le_i32_e64 s[0:1], 16, v250
	v_cmp_le_i32_e64 s[4:5], 17, v250
	v_exp_f32_e32 v40, v40
	v_exp_f32_e32 v41, v41
	s_waitcnt lgkmcnt(3)
	v_mfma_f32_32x32x16_bf16 v[48:63], v[212:215], v[92:95], v[48:63]
	ds_read_b128 v[212:215], v72 offset:9312
	v_cmp_le_i32_e64 s[6:7], 18, v250
	v_cmp_le_i32_e64 s[48:49], 19, v250
	v_exp_f32_e32 v42, v42
	v_exp_f32_e32 v43, v43
	v_cndmask_b32_e64 v40, v40, 0, s[0:1]
	v_cndmask_b32_e64 v41, v41, 0, s[4:5]
	v_add_f32_e32 v232, v232, v40
	v_add_f32_e32 v233, v233, v41
	v_cvt_pk_bf16_f32 v68, v40, v41
	v_mfma_f32_32x32x16_bf16 v[0:15], v[216:219], v[64:67], v[0:15]
	ds_read2_b64 v[216:219], v73 offset0:8 offset1:10
	v_cmp_le_i32_e64 s[0:1], 24, v250
	v_cmp_le_i32_e64 s[4:5], 25, v250
	v_exp_f32_e32 v44, v44
	v_exp_f32_e32 v45, v45
	v_cndmask_b32_e64 v42, v42, 0, s[6:7]
	v_cndmask_b32_e64 v43, v43, 0, s[48:49]
	v_add_f32_e32 v232, v232, v42
	v_add_f32_e32 v233, v233, v43
	v_cvt_pk_bf16_f32 v69, v42, v43
	v_mfma_f32_32x32x16_bf16 v[16:31], v[220:223], v[64:67], v[16:31]
	ds_read2_b64 v[220:223], v74 offset0:40 offset1:42
	v_cmp_le_i32_e64 s[6:7], 26, v250
	v_cmp_le_i32_e64 s[48:49], 27, v250
	v_exp_f32_e32 v46, v46
	v_exp_f32_e32 v47, v47
	v_cndmask_b32_e64 v44, v44, 0, s[0:1]
	v_cndmask_b32_e64 v45, v45, 0, s[4:5]
	v_add_f32_e32 v232, v232, v44
	v_add_f32_e32 v233, v233, v45
	v_cvt_pk_bf16_f32 v70, v44, v45
	v_cndmask_b32_e64 v46, v46, 0, s[6:7]
	v_cndmask_b32_e64 v47, v47, 0, s[48:49]
	v_add_f32_e32 v232, v232, v46
	v_add_f32_e32 v233, v233, v47
	v_cvt_pk_bf16_f32 v71, v46, v47
	s_waitcnt lgkmcnt(5)
; #define LAS __attribute__((address_space(3)))
; #define MFMA32(a, b, c) __builtin_amdgcn_mfma_f32_32x32x16_bf16((a), (b), (c), 0, 0, 0)
; __device__ __forceinline__ float ex2(float x) { return __builtin_amdgcn_exp2f(x); }
; template <int MODE>
; __device__ __forceinline__ void attn_tile(const LAS unsigned char* Kb, const LAS unsigned char* Vb, const bf16x8_t (&qf)[4], f32x16 (&oacc)[2], float& l_run,
;                                           int r, int h, int dlt0, int dlt1, bool hiw) {
;     ...
; #pragma unroll
;     for (int mt = 0; mt < 4; ++mt) {
;         if (mt == 0) { if (hiw) __builtin_amdgcn_s_setprio(1); else __builtin_amdgcn_s_setprio(0); }
;         if (mt == 2) { if (hiw) __builtin_amdgcn_s_setprio(0); else __builtin_amdgcn_s_setprio(1); }
;         const int dl = mt < 2 ? dlt0 : dlt1;
;         f32x16 sacc = zero16();
; #pragma unroll
;         for (int ks = 0; ks < 4; ++ks) { const bf16x8_t ka = *(const LAS bf16x8_t*)(Kb + (32 * mt + r) * A_KSTR + 32 * ks + 16 * h); sacc = MFMA32(ka, qf[ks], sacc); }
; #pragma unroll
;         for (int i = 0; i < 16; ++i) {
;             float p;
;             if (MODE == 2) p = ex2(sacc[i]);
;             else if (MODE == 3) p = ex2(sacc[i] + __int_as_float(dl));
;             else { const int ci = 32 * mt + (i & 3) + 8 * (i >> 2); p = ((unsigned)(dl - ci) < ulim) ? ex2(sacc[i]) : 0.f; }
;             sacc[i] = p; ls += p;
;         }
; #pragma unroll
;         for (int s = 0; s < 2; ++s) {
;             const bf16x8_t pf = pack8(sacc, 8 * s);
; #pragma unroll
;             for (int dt = 0; dt < 2; ++dt) {
;                 const LAS unsigned char* vp = Vb + (32 * dt + r) * A_CVSTR + (32 * mt + 16 * s + 4 * h) * 2;
;                 const s16x4_t lo = *(const LAS s16x4_t*)vp, hi = *(const LAS s16x4_t*)(vp + 16);
;                 oacc[dt] = MFMA32(__builtin_shufflevector(lo, hi, 0, 1, 2, 3, 4, 5, 6, 7), pf, oacc[dt]);
;             }
;         }
;     }
;     l_run += ls;
; }
	v_mfma_f32_32x32x16_bf16 v[32:47], v[200:203], v[80:83], 0
	ds_read_b128 v[200:203], v72 offset:13824
	v_exp_f32_e32 v48, v48
	v_exp_f32_e32 v49, v49
	s_waitcnt lgkmcnt(5)
	v_mfma_f32_32x32x16_bf16 v[32:47], v[204:207], v[84:87], v[32:47]
	ds_read_b128 v[204:207], v72 offset:13856
	v_exp_f32_e32 v50, v50
	v_exp_f32_e32 v51, v51
	v_add_f32_e32 v232, v232, v48
	v_add_f32_e32 v233, v233, v49
	v_cvt_pk_bf16_f32 v64, v48, v49
	v_mfma_f32_32x32x16_bf16 v[0:15], v[224:227], v[68:71], v[0:15]
	ds_read2_b64 v[224:227], v73 offset0:12 offset1:14
	v_exp_f32_e32 v52, v52
	v_exp_f32_e32 v53, v53
	v_add_f32_e32 v232, v232, v50
	v_add_f32_e32 v233, v233, v51
	v_cvt_pk_bf16_f32 v65, v50, v51
	v_mfma_f32_32x32x16_bf16 v[16:31], v[228:231], v[68:71], v[16:31]
	ds_read2_b64 v[228:231], v74 offset0:44 offset1:46
	v_exp_f32_e32 v54, v54
	v_exp_f32_e32 v55, v55
	v_add_f32_e32 v232, v232, v52
	v_add_f32_e32 v233, v233, v53
	v_cvt_pk_bf16_f32 v66, v52, v53
	v_add_f32_e32 v232, v232, v54
	v_add_f32_e32 v233, v233, v55
	v_cvt_pk_bf16_f32 v67, v54, v55
	s_waitcnt lgkmcnt(7)
	v_mfma_f32_32x32x16_bf16 v[32:47], v[208:211], v[88:91], v[32:47]
	ds_read_b128 v[208:211], v72 offset:13888
	v_exp_f32_e32 v56, v56
	v_exp_f32_e32 v57, v57
	s_waitcnt lgkmcnt(7)
	v_mfma_f32_32x32x16_bf16 v[32:47], v[212:215], v[92:95], v[32:47]
	ds_read_b128 v[212:215], v72 offset:13920
	v_exp_f32_e32 v58, v58
	v_exp_f32_e32 v59, v59
	v_add_f32_e32 v232, v232, v56
	v_add_f32_e32 v233, v233, v57
	v_cvt_pk_bf16_f32 v68, v56, v57
	s_waitcnt lgkmcnt(7)
	v_mfma_f32_32x32x16_bf16 v[0:15], v[216:219], v[64:67], v[0:15]
	ds_read2_b64 v[216:219], v73 offset0:16 offset1:18
	v_exp_f32_e32 v60, v60
	v_exp_f32_e32 v61, v61
	v_add_f32_e32 v232, v232, v58
	v_add_f32_e32 v233, v233, v59
	v_cvt_pk_bf16_f32 v69, v58, v59
	s_waitcnt lgkmcnt(7)
	v_mfma_f32_32x32x16_bf16 v[16:31], v[220:223], v[64:67], v[16:31]
	ds_read2_b64 v[220:223], v74 offset0:48 offset1:50
	v_exp_f32_e32 v62, v62
	v_exp_f32_e32 v63, v63
	v_add_f32_e32 v232, v232, v60
	v_add_f32_e32 v233, v233, v61
	v_cvt_pk_bf16_f32 v70, v60, v61
	v_add_f32_e32 v232, v232, v62
	v_add_f32_e32 v233, v233, v63
	v_cvt_pk_bf16_f32 v71, v62, v63
	s_waitcnt lgkmcnt(7)
	v_mfma_f32_32x32x16_bf16 v[48:63], v[200:203], v[80:83], 0
	v_exp_f32_e32 v32, v32
	v_exp_f32_e32 v33, v33
	s_waitcnt lgkmcnt(6)
	v_mfma_f32_32x32x16_bf16 v[48:63], v[204:207], v[84:87], v[48:63]
	v_exp_f32_e32 v34, v34
	v_exp_f32_e32 v35, v35
	v_add_f32_e32 v232, v232, v32
	v_add_f32_e32 v233, v233, v33
	v_cvt_pk_bf16_f32 v64, v32, v33
	s_waitcnt lgkmcnt(5)
	v_mfma_f32_32x32x16_bf16 v[0:15], v[224:227], v[68:71], v[0:15]
	ds_read2_b64 v[224:227], v73 offset0:20 offset1:22
	v_exp_f32_e32 v36, v36
	v_exp_f32_e32 v37, v37
	v_add_f32_e32 v232, v232, v34
	v_add_f32_e32 v233, v233, v35
	v_cvt_pk_bf16_f32 v65, v34, v35
	s_waitcnt lgkmcnt(5)
	v_mfma_f32_32x32x16_bf16 v[16:31], v[228:231], v[68:71], v[16:31]
	ds_read2_b64 v[228:231], v74 offset0:52 offset1:54
	v_exp_f32_e32 v38, v38
	v_exp_f32_e32 v39, v39
	v_add_f32_e32 v232, v232, v36
	v_add_f32_e32 v233, v233, v37
	v_cvt_pk_bf16_f32 v66, v36, v37
	v_add_f32_e32 v232, v232, v38
	v_add_f32_e32 v233, v233, v39
	v_cvt_pk_bf16_f32 v67, v38, v39
	s_cmp_eq_u32 s45, 0
	s_cbranch_scc1 .Lt1_e0_nostage
	s_waitcnt vmcnt(3)
	ds_write_b128 v251, v[96:99]
	s_waitcnt vmcnt(2)
	ds_write_b128 v251, v[100:103] offset:9216
	s_waitcnt vmcnt(1)
	ds_write2_b64 v252, v[104:105], v[106:107] offset1:1
	s_waitcnt vmcnt(0)
	ds_write2_b64 v252, v[108:109], v[110:111] offset0:16 offset1:17
	s_mov_b32 s47, 1
.Lt1_e0_nostage:
	s_waitcnt lgkmcnt(5)
	v_mfma_f32_32x32x16_bf16 v[48:63], v[208:211], v[88:91], v[48:63]
	v_exp_f32_e32 v40, v40
	v_exp_f32_e32 v41, v41
	s_waitcnt lgkmcnt(4)
	v_mfma_f32_32x32x16_bf16 v[48:63], v[212:215], v[92:95], v[48:63]
	v_exp_f32_e32 v42, v42
	v_exp_f32_e32 v43, v43
	v_add_f32_e32 v232, v232, v40
	v_add_f32_e32 v233, v233, v41
	v_cvt_pk_bf16_f32 v68, v40, v41
	s_waitcnt lgkmcnt(3)
	v_mfma_f32_32x32x16_bf16 v[0:15], v[216:219], v[64:67], v[0:15]
	ds_read2_b64 v[216:219], v73 offset0:24 offset1:26
	v_exp_f32_e32 v44, v44
	v_exp_f32_e32 v45, v45
	v_add_f32_e32 v232, v232, v42
	v_add_f32_e32 v233, v233, v43
	v_cvt_pk_bf16_f32 v69, v42, v43
	s_waitcnt lgkmcnt(3)
	v_mfma_f32_32x32x16_bf16 v[16:31], v[220:223], v[64:67], v[16:31]
	ds_read2_b64 v[220:223], v74 offset0:56 offset1:58
	v_exp_f32_e32 v46, v46
	v_exp_f32_e32 v47, v47
	v_add_f32_e32 v232, v232, v44
	v_add_f32_e32 v233, v233, v45
	v_cvt_pk_bf16_f32 v70, v44, v45
	v_add_f32_e32 v232, v232, v46
	v_add_f32_e32 v233, v233, v47
	v_cvt_pk_bf16_f32 v71, v46, v47
	v_exp_f32_e32 v48, v48
	v_exp_f32_e32 v49, v49
	v_exp_f32_e32 v50, v50
	v_exp_f32_e32 v51, v51
	v_add_f32_e32 v232, v232, v48
	v_add_f32_e32 v233, v233, v49
	v_cvt_pk_bf16_f32 v64, v48, v49
	s_waitcnt lgkmcnt(3)
	v_mfma_f32_32x32x16_bf16 v[0:15], v[224:227], v[68:71], v[0:15]
	ds_read2_b64 v[224:227], v73 offset0:28 offset1:30
	v_exp_f32_e32 v52, v52
	v_exp_f32_e32 v53, v53
	v_add_f32_e32 v232, v232, v50
	v_add_f32_e32 v233, v233, v51
	v_cvt_pk_bf16_f32 v65, v50, v51
	s_waitcnt lgkmcnt(3)
	v_mfma_f32_32x32x16_bf16 v[16:31], v[228:231], v[68:71], v[16:31]
	ds_read2_b64 v[228:231], v74 offset0:60 offset1:62
	v_exp_f32_e32 v54, v54
	v_exp_f32_e32 v55, v55
	v_add_f32_e32 v232, v232, v52
	v_add_f32_e32 v233, v233, v53
	v_cvt_pk_bf16_f32 v66, v52, v53
	v_add_f32_e32 v232, v232, v54
	v_add_f32_e32 v233, v233, v55
	v_cvt_pk_bf16_f32 v67, v54, v55
	v_exp_f32_e32 v56, v56
	v_exp_f32_e32 v57, v57
	v_exp_f32_e32 v58, v58
	v_exp_f32_e32 v59, v59
	v_add_f32_e32 v232, v232, v56
	v_add_f32_e32 v233, v233, v57
	v_cvt_pk_bf16_f32 v68, v56, v57
	s_waitcnt lgkmcnt(3)
	v_mfma_f32_32x32x16_bf16 v[0:15], v[216:219], v[64:67], v[0:15]
	v_exp_f32_e32 v60, v60
	v_exp_f32_e32 v61, v61
	v_add_f32_e32 v232, v232, v58
	v_add_f32_e32 v233, v233, v59
	v_cvt_pk_bf16_f32 v69, v58, v59
	s_waitcnt lgkmcnt(2)
	v_mfma_f32_32x32x16_bf16 v[16:31], v[220:223], v[64:67], v[16:31]
	v_exp_f32_e32 v62, v62
	v_exp_f32_e32 v63, v63
	v_add_f32_e32 v232, v232, v60
	v_add_f32_e32 v233, v233, v61
	v_cvt_pk_bf16_f32 v70, v60, v61
	v_add_f32_e32 v232, v232, v62
	v_add_f32_e32 v233, v233, v63
	v_cvt_pk_bf16_f32 v71, v62, v63
	s_nop 1
	s_waitcnt lgkmcnt(1)
	v_mfma_f32_32x32x16_bf16 v[0:15], v[224:227], v[68:71], v[0:15]
	s_waitcnt lgkmcnt(0)
	v_mfma_f32_32x32x16_bf16 v[16:31], v[228:231], v[68:71], v[16:31]
	v_add_f32_e32 v232, v232, v233
	v_add_f32_e32 v112, v112, v232
	s_branch .Lt1_join
; #define LAS __attribute__((address_space(3)))
; #define MFMA32(a, b, c) __builtin_amdgcn_mfma_f32_32x32x16_bf16((a), (b), (c), 0, 0, 0)
; __device__ __forceinline__ float ex2(float x) { return __builtin_amdgcn_exp2f(x); }
; template <int MODE>
; __device__ __forceinline__ void attn_tile(const LAS unsigned char* Kb, const LAS unsigned char* Vb, const bf16x8_t (&qf)[4], f32x16 (&oacc)[2], float& l_run,
;                                           int r, int h, int dlt0, int dlt1, bool hiw) {
;     ...
; #pragma unroll
;     for (int mt = 0; mt < 4; ++mt) {
;         if (mt == 0) { if (hiw) __builtin_amdgcn_s_setprio(1); else __builtin_amdgcn_s_setprio(0); }
;         if (mt == 2) { if (hiw) __builtin_amdgcn_s_setprio(0); else __builtin_amdgcn_s_setprio(1); }
;         const int dl = mt < 2 ? dlt0 : dlt1;
;         f32x16 sacc = zero16();
; #pragma unroll
;         for (int ks = 0; ks < 4; ++ks) { const bf16x8_t ka = *(const LAS bf16x8_t*)(Kb + (32 * mt + r) * A_KSTR + 32 * ks + 16 * h); sacc = MFMA32(ka, qf[ks], sacc); }
; #pragma unroll
;         for (int i = 0; i < 16; ++i) {
;             float p;
;             if (MODE == 2) p = ex2(sacc[i]);
;             else if (MODE == 3) p = ex2(sacc[i] + __int_as_float(dl));
;             else { const int ci = 32 * mt + (i & 3) + 8 * (i >> 2); p = ((unsigned)(dl - ci) < ulim) ? ex2(sacc[i]) : 0.f; }
;             sacc[i] = p; ls += p;
;         }
; #pragma unroll
;         for (int s = 0; s < 2; ++s) {
;             const bf16x8_t pf = pack8(sacc, 8 * s);
; #pragma unroll
;             for (int dt = 0; dt < 2; ++dt) {
;                 const LAS unsigned char* vp = Vb + (32 * dt + r) * A_CVSTR + (32 * mt + 16 * s + 4 * h) * 2;
;                 const s16x4_t lo = *(const LAS s16x4_t*)vp, hi = *(const LAS s16x4_t*)(vp + 16);
;                 oacc[dt] = MFMA32(__builtin_shufflevector(lo, hi, 0, 1, 2, 3, 4, 5, 6, 7), pf, oacc[dt]);
;             }
;         }
;     }
.Lt1_e1:
	ds_read_b128 v[200:203], v72 offset:4608
	ds_read_b128 v[204:207], v72 offset:4640
	ds_read_b128 v[208:211], v72 offset:4672
	ds_read_b128 v[212:215], v72 offset:4704
	ds_read2_b64 v[216:219], v73 offset0:8 offset1:10
	ds_read2_b64 v[220:223], v74 offset0:40 offset1:42
	ds_read2_b64 v[224:227], v73 offset0:12 offset1:14
	ds_read2_b64 v[228:231], v74 offset0:44 offset1:46
	s_waitcnt lgkmcnt(7)
	v_mfma_f32_32x32x16_bf16 v[32:47], v[200:203], v[80:83], 0
	ds_read_b128 v[200:203], v72 offset:9216
	s_waitcnt lgkmcnt(7)
	v_mfma_f32_32x32x16_bf16 v[32:47], v[204:207], v[84:87], v[32:47]
	ds_read_b128 v[204:207], v72 offset:9248
	s_waitcnt lgkmcnt(7)
	v_mfma_f32_32x32x16_bf16 v[32:47], v[208:211], v[88:91], v[32:47]
	ds_read_b128 v[208:211], v72 offset:9280
	s_waitcnt lgkmcnt(7)
	v_mfma_f32_32x32x16_bf16 v[32:47], v[212:215], v[92:95], v[32:47]
	ds_read_b128 v[212:215], v72 offset:9312
	s_nop 7
	s_nop 3
	s_waitcnt lgkmcnt(3)
	v_mfma_f32_32x32x16_bf16 v[48:63], v[200:203], v[80:83], 0
	ds_read_b128 v[200:203], v72 offset:13824
	v_cmp_le_i32_e64 s[0:1], 0, v250
	v_cmp_le_i32_e64 s[4:5], 1, v250
	v_exp_f32_e32 v32, v32
	v_exp_f32_e32 v33, v33
	s_waitcnt lgkmcnt(3)
	v_mfma_f32_32x32x16_bf16 v[48:63], v[204:207], v[84:87], v[48:63]
	ds_read_b128 v[204:207], v72 offset:13856
	v_cmp_le_i32_e64 s[6:7], 2, v250
	v_cmp_le_i32_e64 s[48:49], 3, v250
	v_exp_f32_e32 v34, v34
	v_exp_f32_e32 v35, v35
	v_cndmask_b32_e64 v32, v32, 0, s[0:1]
	v_cndmask_b32_e64 v33, v33, 0, s[4:5]
	v_mov_b32_e32 v232, v32
	v_mov_b32_e32 v233, v33
	v_cvt_pk_bf16_f32 v64, v32, v33
	v_cmp_le_i32_e64 s[0:1], 8, v250
	v_cmp_le_i32_e64 s[4:5], 9, v250
	v_exp_f32_e32 v36, v36
	v_exp_f32_e32 v37, v37
	v_cndmask_b32_e64 v34, v34, 0, s[6:7]
	v_cndmask_b32_e64 v35, v35, 0, s[48:49]
	v_add_f32_e32 v232, v232, v34
	v_add_f32_e32 v233, v233, v35
	v_cvt_pk_bf16_f32 v65, v34, v35
	v_cmp_le_i32_e64 s[6:7], 10, v250
	v_cmp_le_i32_e64 s[48:49], 11, v250
	v_exp_f32_e32 v38, v38
	v_exp_f32_e32 v39, v39
	v_cndmask_b32_e64 v36, v36, 0, s[0:1]
	v_cndmask_b32_e64 v37, v37, 0, s[4:5]
	v_add_f32_e32 v232, v232, v36
	v_add_f32_e32 v233, v233, v37
	v_cvt_pk_bf16_f32 v66, v36, v37
	v_cndmask_b32_e64 v38, v38, 0, s[6:7]
	v_cndmask_b32_e64 v39, v39, 0, s[48:49]
	v_add_f32_e32 v232, v232, v38
	v_add_f32_e32 v233, v233, v39
	v_cvt_pk_bf16_f32 v67, v38, v39
	s_waitcnt lgkmcnt(3)
	v_mfma_f32_32x32x16_bf16 v[48:63], v[208:211], v[88:91], v[48:63]
	ds_read_b128 v[208:211], v72 offset:13888
	v_cmp_le_i32_e64 s[0:1], 16, v250
	v_cmp_le_i32_e64 s[4:5], 17, v250
	v_exp_f32_e32 v40, v40
	v_exp_f32_e32 v41, v41
	s_waitcnt lgkmcnt(3)
	v_mfma_f32_32x32x16_bf16 v[48:63], v[212:215], v[92:95], v[48:63]
	ds_read_b128 v[212:215], v72 offset:13920
	v_cmp_le_i32_e64 s[6:7], 18, v250
	v_cmp_le_i32_e64 s[48:49], 19, v250
	v_exp_f32_e32 v42, v42
	v_exp_f32_e32 v43, v43
	v_cndmask_b32_e64 v40, v40, 0, s[0:1]
	v_cndmask_b32_e64 v41, v41, 0, s[4:5]
	v_add_f32_e32 v232, v232, v40
	v_add_f32_e32 v233, v233, v41
	v_cvt_pk_bf16_f32 v68, v40, v41
	v_mfma_f32_32x32x16_bf16 v[0:15], v[216:219], v[64:67], v[0:15]
	ds_read2_b64 v[216:219], v73 offset0:16 offset1:18
	v_cmp_le_i32_e64 s[0:1], 24, v250
	v_cmp_le_i32_e64 s[4:5], 25, v250
	v_exp_f32_e32 v44, v44
	v_exp_f32_e32 v45, v45
	v_cndmask_b32_e64 v42, v42, 0, s[6:7]
	v_cndmask_b32_e64 v43, v43, 0, s[48:49]
	v_add_f32_e32 v232, v232, v42
	v_add_f32_e32 v233, v233, v43
	v_cvt_pk_bf16_f32 v69, v42, v43
	v_mfma_f32_32x32x16_bf16 v[16:31], v[220:223], v[64:67], v[16:31]
	ds_read2_b64 v[220:223], v74 offset0:48 offset1:50
	v_cmp_le_i32_e64 s[6:7], 26, v250
	v_cmp_le_i32_e64 s[48:49], 27, v250
	v_exp_f32_e32 v46, v46
	v_exp_f32_e32 v47, v47
	v_cndmask_b32_e64 v44, v44, 0, s[0:1]
	v_cndmask_b32_e64 v45, v45, 0, s[4:5]
	v_add_f32_e32 v232, v232, v44
	v_add_f32_e32 v233, v233, v45
	v_cvt_pk_bf16_f32 v70, v44, v45
	v_cndmask_b32_e64 v46, v46, 0, s[6:7]
	v_cndmask_b32_e64 v47, v47, 0, s[48:49]
	v_add_f32_e32 v232, v232, v46
	v_add_f32_e32 v233, v233, v47
	v_cvt_pk_bf16_f32 v71, v46, v47
	s_waitcnt lgkmcnt(5)
	v_mfma_f32_32x32x16_bf16 v[32:47], v[200:203], v[80:83], 0
	v_exp_f32_e32 v48, v48
	v_exp_f32_e32 v49, v49
	s_waitcnt lgkmcnt(4)
	v_mfma_f32_32x32x16_bf16 v[32:47], v[204:207], v[84:87], v[32:47]
	v_exp_f32_e32 v50, v50
	v_exp_f32_e32 v51, v51
	v_add_f32_e32 v232, v232, v48
	v_add_f32_e32 v233, v233, v49
	v_cvt_pk_bf16_f32 v64, v48, v49
	v_mfma_f32_32x32x16_bf16 v[0:15], v[224:227], v[68:71], v[0:15]
	ds_read2_b64 v[224:227], v73 offset0:20 offset1:22
	v_exp_f32_e32 v52, v52
	v_exp_f32_e32 v53, v53
	v_add_f32_e32 v232, v232, v50
	v_add_f32_e32 v233, v233, v51
	v_cvt_pk_bf16_f32 v65, v50, v51
	v_mfma_f32_32x32x16_bf16 v[16:31], v[228:231], v[68:71], v[16:31]
	ds_read2_b64 v[228:231], v74 offset0:52 offset1:54
	v_exp_f32_e32 v54, v54
	v_exp_f32_e32 v55, v55
	v_add_f32_e32 v232, v232, v52
	v_add_f32_e32 v233, v233, v53
	v_cvt_pk_bf16_f32 v66, v52, v53
	v_add_f32_e32 v232, v232, v54
	v_add_f32_e32 v233, v233, v55
	v_cvt_pk_bf16_f32 v67, v54, v55
	s_cmp_eq_u32 s45, 0
	s_cbranch_scc1 .Lt1_e1_nostage
	s_waitcnt vmcnt(3)
	ds_write_b128 v251, v[96:99]
	s_waitcnt vmcnt(2)
	ds_write_b128 v251, v[100:103] offset:9216
	s_waitcnt vmcnt(1)
	ds_write2_b64 v252, v[104:105], v[106:107] offset1:1
	s_waitcnt vmcnt(0)
	ds_write2_b64 v252, v[108:109], v[110:111] offset0:16 offset1:17
	s_mov_b32 s47, 1
; #define LAS __attribute__((address_space(3)))
; #define MFMA32(a, b, c) __builtin_amdgcn_mfma_f32_32x32x16_bf16((a), (b), (c), 0, 0, 0)
; __device__ __forceinline__ float ex2(float x) { return __builtin_amdgcn_exp2f(x); }
; template <int MODE>
; __device__ __forceinline__ void attn_tile(const LAS unsigned char* Kb, const LAS unsigned char* Vb, const bf16x8_t (&qf)[4], f32x16 (&oacc)[2], float& l_run,
;                                           int r, int h, int dlt0, int dlt1, bool hiw) {
;     ...
; #pragma unroll
;     for (int mt = 0; mt < 4; ++mt) {
;         if (mt == 0) { if (hiw) __builtin_amdgcn_s_setprio(1); else __builtin_amdgcn_s_setprio(0); }
;         if (mt == 2) { if (hiw) __builtin_amdgcn_s_setprio(0); else __builtin_amdgcn_s_setprio(1); }
;         const int dl = mt < 2 ? dlt0 : dlt1;
;         f32x16 sacc = zero16();
; #pragma unroll
;         for (int ks = 0; ks < 4; ++ks) { const bf16x8_t ka = *(const LAS bf16x8_t*)(Kb + (32 * mt + r) * A_KSTR + 32 * ks + 16 * h); sacc = MFMA32(ka, qf[ks], sacc); }
; #pragma unroll
;         for (int i = 0; i < 16; ++i) {
;             float p;
;             if (MODE == 2) p = ex2(sacc[i]);
;             else if (MODE == 3) p = ex2(sacc[i] + __int_as_float(dl));
;             else { const int ci = 32 * mt + (i & 3) + 8 * (i >> 2); p = ((unsigned)(dl - ci) < ulim) ? ex2(sacc[i]) : 0.f; }
;             sacc[i] = p; ls += p;
;         }
; #pragma unroll
;         for (int s = 0; s < 2; ++s) {
;             const bf16x8_t pf = pack8(sacc, 8 * s);
; #pragma unroll
;             for (int dt = 0; dt < 2; ++dt) {
;                 const LAS unsigned char* vp = Vb + (32 * dt + r) * A_CVSTR + (32 * mt + 16 * s + 4 * h) * 2;
;                 const s16x4_t lo = *(const LAS s16x4_t*)vp, hi = *(const LAS s16x4_t*)(vp + 16);
;                 oacc[dt] = MFMA32(__builtin_shufflevector(lo, hi, 0, 1, 2, 3, 4, 5, 6, 7), pf, oacc[dt]);
;             }
;         }
;     }
;     l_run += ls;
; }
.Lt1_e1_nostage:
	s_waitcnt lgkmcnt(5)
	v_mfma_f32_32x32x16_bf16 v[32:47], v[208:211], v[88:91], v[32:47]
	v_exp_f32_e32 v56, v56
	v_exp_f32_e32 v57, v57
	s_waitcnt lgkmcnt(4)
	v_mfma_f32_32x32x16_bf16 v[32:47], v[212:215], v[92:95], v[32:47]
	v_exp_f32_e32 v58, v58
	v_exp_f32_e32 v59, v59
	v_add_f32_e32 v232, v232, v56
	v_add_f32_e32 v233, v233, v57
	v_cvt_pk_bf16_f32 v68, v56, v57
	s_waitcnt lgkmcnt(3)
	v_mfma_f32_32x32x16_bf16 v[0:15], v[216:219], v[64:67], v[0:15]
	ds_read2_b64 v[216:219], v73 offset0:24 offset1:26
	v_exp_f32_e32 v60, v60
	v_exp_f32_e32 v61, v61
	v_add_f32_e32 v232, v232, v58
	v_add_f32_e32 v233, v233, v59
	v_cvt_pk_bf16_f32 v69, v58, v59
	s_waitcnt lgkmcnt(3)
	v_mfma_f32_32x32x16_bf16 v[16:31], v[220:223], v[64:67], v[16:31]
	ds_read2_b64 v[220:223], v74 offset0:56 offset1:58
	v_exp_f32_e32 v62, v62
	v_exp_f32_e32 v63, v63
	v_add_f32_e32 v232, v232, v60
	v_add_f32_e32 v233, v233, v61
	v_cvt_pk_bf16_f32 v70, v60, v61
	v_add_f32_e32 v232, v232, v62
	v_add_f32_e32 v233, v233, v63
	v_cvt_pk_bf16_f32 v71, v62, v63
	v_exp_f32_e32 v32, v32
	v_exp_f32_e32 v33, v33
	v_exp_f32_e32 v34, v34
	v_exp_f32_e32 v35, v35
	v_add_f32_e32 v232, v232, v32
	v_add_f32_e32 v233, v233, v33
	v_cvt_pk_bf16_f32 v64, v32, v33
	s_waitcnt lgkmcnt(3)
	v_mfma_f32_32x32x16_bf16 v[0:15], v[224:227], v[68:71], v[0:15]
	ds_read2_b64 v[224:227], v73 offset0:28 offset1:30
	v_exp_f32_e32 v36, v36
	v_exp_f32_e32 v37, v37
	v_add_f32_e32 v232, v232, v34
	v_add_f32_e32 v233, v233, v35
	v_cvt_pk_bf16_f32 v65, v34, v35
	s_waitcnt lgkmcnt(3)
	v_mfma_f32_32x32x16_bf16 v[16:31], v[228:231], v[68:71], v[16:31]
	ds_read2_b64 v[228:231], v74 offset0:60 offset1:62
	v_exp_f32_e32 v38, v38
	v_exp_f32_e32 v39, v39
	v_add_f32_e32 v232, v232, v36
	v_add_f32_e32 v233, v233, v37
	v_cvt_pk_bf16_f32 v66, v36, v37
	v_add_f32_e32 v232, v232, v38
	v_add_f32_e32 v233, v233, v39
	v_cvt_pk_bf16_f32 v67, v38, v39
	v_exp_f32_e32 v40, v40
	v_exp_f32_e32 v41, v41
	v_exp_f32_e32 v42, v42
	v_exp_f32_e32 v43, v43
	v_add_f32_e32 v232, v232, v40
	v_add_f32_e32 v233, v233, v41
	v_cvt_pk_bf16_f32 v68, v40, v41
	s_waitcnt lgkmcnt(3)
	v_mfma_f32_32x32x16_bf16 v[0:15], v[216:219], v[64:67], v[0:15]
	v_exp_f32_e32 v44, v44
	v_exp_f32_e32 v45, v45
	v_add_f32_e32 v232, v232, v42
	v_add_f32_e32 v233, v233, v43
	v_cvt_pk_bf16_f32 v69, v42, v43
	s_waitcnt lgkmcnt(2)
	v_mfma_f32_32x32x16_bf16 v[16:31], v[220:223], v[64:67], v[16:31]
	v_exp_f32_e32 v46, v46
	v_exp_f32_e32 v47, v47
	v_add_f32_e32 v232, v232, v44
	v_add_f32_e32 v233, v233, v45
	v_cvt_pk_bf16_f32 v70, v44, v45
	v_add_f32_e32 v232, v232, v46
	v_add_f32_e32 v233, v233, v47
	v_cvt_pk_bf16_f32 v71, v46, v47
	s_nop 1
	s_waitcnt lgkmcnt(1)
	v_mfma_f32_32x32x16_bf16 v[0:15], v[224:227], v[68:71], v[0:15]
	s_waitcnt lgkmcnt(0)
	v_mfma_f32_32x32x16_bf16 v[16:31], v[228:231], v[68:71], v[16:31]
	v_add_f32_e32 v232, v232, v233
	v_add_f32_e32 v112, v112, v232
	s_branch .Lt1_join
.Lt1_e2:
	ds_read_b128 v[200:203], v72 offset:9216
	ds_read_b128 v[204:207], v72 offset:9248
	ds_read_b128 v[208:211], v72 offset:9280
	ds_read_b128 v[212:215], v72 offset:9312
	ds_read2_b64 v[216:219], v73 offset0:16 offset1:18
	ds_read2_b64 v[220:223], v74 offset0:48 offset1:50
	ds_read2_b64 v[224:227], v73 offset0:20 offset1:22
	ds_read2_b64 v[228:231], v74 offset0:52 offset1:54
	s_waitcnt lgkmcnt(7)
	v_mfma_f32_32x32x16_bf16 v[32:47], v[200:203], v[80:83], 0
	ds_read_b128 v[200:203], v72 offset:13824
	s_waitcnt lgkmcnt(7)
	v_mfma_f32_32x32x16_bf16 v[32:47], v[204:207], v[84:87], v[32:47]
	ds_read_b128 v[204:207], v72 offset:13856
	s_waitcnt lgkmcnt(7)
	v_mfma_f32_32x32x16_bf16 v[32:47], v[208:211], v[88:91], v[32:47]
	ds_read_b128 v[208:211], v72 offset:13888
	s_waitcnt lgkmcnt(7)
	v_mfma_f32_32x32x16_bf16 v[32:47], v[212:215], v[92:95], v[32:47]
	ds_read_b128 v[212:215], v72 offset:13920
	s_nop 7
	s_nop 3
	s_waitcnt lgkmcnt(3)
	v_mfma_f32_32x32x16_bf16 v[48:63], v[200:203], v[80:83], 0
	v_cmp_le_i32_e64 s[0:1], 0, v250
	v_cmp_le_i32_e64 s[4:5], 1, v250
	v_exp_f32_e32 v32, v32
	v_exp_f32_e32 v33, v33
	s_waitcnt lgkmcnt(2)
	v_mfma_f32_32x32x16_bf16 v[48:63], v[204:207], v[84:87], v[48:63]
	v_cmp_le_i32_e64 s[6:7], 2, v250
	v_cmp_le_i32_e64 s[48:49], 3, v250
	v_exp_f32_e32 v34, v34
	v_exp_f32_e32 v35, v35
	v_cndmask_b32_e64 v32, v32, 0, s[0:1]
	v_cndmask_b32_e64 v33, v33, 0, s[4:5]
	v_mov_b32_e32 v232, v32
	v_mov_b32_e32 v233, v33
	v_cvt_pk_bf16_f32 v64, v32, v33
	v_cmp_le_i32_e64 s[0:1], 8, v250
	v_cmp_le_i32_e64 s[4:5], 9, v250
	v_exp_f32_e32 v36, v36
	v_exp_f32_e32 v37, v37
	v_cndmask_b32_e64 v34, v34, 0, s[6:7]
	v_cndmask_b32_e64 v35, v35, 0, s[48:49]
	v_add_f32_e32 v232, v232, v34
	v_add_f32_e32 v233, v233, v35
	v_cvt_pk_bf16_f32 v65, v34, v35
	v_cmp_le_i32_e64 s[6:7], 10, v250
	v_cmp_le_i32_e64 s[48:49], 11, v250
	v_exp_f32_e32 v38, v38
	v_exp_f32_e32 v39, v39
	v_cndmask_b32_e64 v36, v36, 0, s[0:1]
	v_cndmask_b32_e64 v37, v37, 0, s[4:5]
	v_add_f32_e32 v232, v232, v36
	v_add_f32_e32 v233, v233, v37
	v_cvt_pk_bf16_f32 v66, v36, v37
	v_cndmask_b32_e64 v38, v38, 0, s[6:7]
	v_cndmask_b32_e64 v39, v39, 0, s[48:49]
	v_add_f32_e32 v232, v232, v38
	v_add_f32_e32 v233, v233, v39
	v_cvt_pk_bf16_f32 v67, v38, v39
	s_cmp_eq_u32 s45, 0
	s_cbranch_scc1 .Lt1_e2_nostage
	s_waitcnt vmcnt(3)
	ds_write_b128 v251, v[96:99]
	s_waitcnt vmcnt(2)
	ds_write_b128 v251, v[100:103] offset:9216
	s_waitcnt vmcnt(1)
	ds_write2_b64 v252, v[104:105], v[106:107] offset1:1
	s_waitcnt vmcnt(0)
	ds_write2_b64 v252, v[108:109], v[110:111] offset0:16 offset1:17
	s_mov_b32 s47, 1
; #define LAS __attribute__((address_space(3)))
; #define MFMA32(a, b, c) __builtin_amdgcn_mfma_f32_32x32x16_bf16((a), (b), (c), 0, 0, 0)
; __device__ __forceinline__ float ex2(float x) { return __builtin_amdgcn_exp2f(x); }
; template <int MODE>
; __device__ __forceinline__ void attn_tile(const LAS unsigned char* Kb, const LAS unsigned char* Vb, const bf16x8_t (&qf)[4], f32x16 (&oacc)[2], float& l_run,
;                                           int r, int h, int dlt0, int dlt1, bool hiw) {
;     ...
; #pragma unroll
;     for (int mt = 0; mt < 4; ++mt) {
;         if (mt == 0) { if (hiw) __builtin_amdgcn_s_setprio(1); else __builtin_amdgcn_s_setprio(0); }
;         if (mt == 2) { if (hiw) __builtin_amdgcn_s_setprio(0); else __builtin_amdgcn_s_setprio(1); }
;         const int dl = mt < 2 ? dlt0 : dlt1;
;         f32x16 sacc = zero16();
; #pragma unroll
;         for (int ks = 0; ks < 4; ++ks) { const bf16x8_t ka = *(const LAS bf16x8_t*)(Kb + (32 * mt + r) * A_KSTR + 32 * ks + 16 * h); sacc = MFMA32(ka, qf[ks], sacc); }
; #pragma unroll
;         for (int i = 0; i < 16; ++i) {
;             float p;
;             if (MODE == 2) p = ex2(sacc[i]);
;             else if (MODE == 3) p = ex2(sacc[i] + __int_as_float(dl));
;             else { const int ci = 32 * mt + (i & 3) + 8 * (i >> 2); p = ((unsigned)(dl - ci) < ulim) ? ex2(sacc[i]) : 0.f; }
;             sacc[i] = p; ls += p;
;         }
; #pragma unroll
;         for (int s = 0; s < 2; ++s) {
;             const bf16x8_t pf = pack8(sacc, 8 * s);
; #pragma unroll
;             for (int dt = 0; dt < 2; ++dt) {
;                 const LAS unsigned char* vp = Vb + (32 * dt + r) * A_CVSTR + (32 * mt + 16 * s + 4 * h) * 2;
;                 const s16x4_t lo = *(const LAS s16x4_t*)vp, hi = *(const LAS s16x4_t*)(vp + 16);
;                 oacc[dt] = MFMA32(__builtin_shufflevector(lo, hi, 0, 1, 2, 3, 4, 5, 6, 7), pf, oacc[dt]);
;             }
;         }
;     }
;     l_run += ls;
; }
.Lt1_e2_nostage:
	s_waitcnt lgkmcnt(1)
	v_mfma_f32_32x32x16_bf16 v[48:63], v[208:211], v[88:91], v[48:63]
	v_cmp_le_i32_e64 s[0:1], 16, v250
	v_cmp_le_i32_e64 s[4:5], 17, v250
	v_exp_f32_e32 v40, v40
	v_exp_f32_e32 v41, v41
	s_waitcnt lgkmcnt(0)
	v_mfma_f32_32x32x16_bf16 v[48:63], v[212:215], v[92:95], v[48:63]
	v_cmp_le_i32_e64 s[6:7], 18, v250
	v_cmp_le_i32_e64 s[48:49], 19, v250
	v_exp_f32_e32 v42, v42
	v_exp_f32_e32 v43, v43
	v_cndmask_b32_e64 v40, v40, 0, s[0:1]
	v_cndmask_b32_e64 v41, v41, 0, s[4:5]
	v_add_f32_e32 v232, v232, v40
	v_add_f32_e32 v233, v233, v41
	v_cvt_pk_bf16_f32 v68, v40, v41
	v_mfma_f32_32x32x16_bf16 v[0:15], v[216:219], v[64:67], v[0:15]
	ds_read2_b64 v[216:219], v73 offset0:24 offset1:26
	v_cmp_le_i32_e64 s[0:1], 24, v250
	v_cmp_le_i32_e64 s[4:5], 25, v250
	v_exp_f32_e32 v44, v44
	v_exp_f32_e32 v45, v45
	v_cndmask_b32_e64 v42, v42, 0, s[6:7]
	v_cndmask_b32_e64 v43, v43, 0, s[48:49]
	v_add_f32_e32 v232, v232, v42
	v_add_f32_e32 v233, v233, v43
	v_cvt_pk_bf16_f32 v69, v42, v43
	v_mfma_f32_32x32x16_bf16 v[16:31], v[220:223], v[64:67], v[16:31]
	ds_read2_b64 v[220:223], v74 offset0:56 offset1:58
	v_cmp_le_i32_e64 s[6:7], 26, v250
	v_cmp_le_i32_e64 s[48:49], 27, v250
	v_exp_f32_e32 v46, v46
	v_exp_f32_e32 v47, v47
	v_cndmask_b32_e64 v44, v44, 0, s[0:1]
	v_cndmask_b32_e64 v45, v45, 0, s[4:5]
	v_add_f32_e32 v232, v232, v44
	v_add_f32_e32 v233, v233, v45
	v_cvt_pk_bf16_f32 v70, v44, v45
	v_cndmask_b32_e64 v46, v46, 0, s[6:7]
	v_cndmask_b32_e64 v47, v47, 0, s[48:49]
	v_add_f32_e32 v232, v232, v46
	v_add_f32_e32 v233, v233, v47
	v_cvt_pk_bf16_f32 v71, v46, v47
	v_exp_f32_e32 v48, v48
	v_exp_f32_e32 v49, v49
	v_exp_f32_e32 v50, v50
	v_exp_f32_e32 v51, v51
	v_add_f32_e32 v232, v232, v48
	v_add_f32_e32 v233, v233, v49
	v_cvt_pk_bf16_f32 v64, v48, v49
	v_mfma_f32_32x32x16_bf16 v[0:15], v[224:227], v[68:71], v[0:15]
	ds_read2_b64 v[224:227], v73 offset0:28 offset1:30
	v_exp_f32_e32 v52, v52
	v_exp_f32_e32 v53, v53
	v_add_f32_e32 v232, v232, v50
	v_add_f32_e32 v233, v233, v51
	v_cvt_pk_bf16_f32 v65, v50, v51
	v_mfma_f32_32x32x16_bf16 v[16:31], v[228:231], v[68:71], v[16:31]
	ds_read2_b64 v[228:231], v74 offset0:60 offset1:62
	v_exp_f32_e32 v54, v54
	v_exp_f32_e32 v55, v55
	v_add_f32_e32 v232, v232, v52
	v_add_f32_e32 v233, v233, v53
	v_cvt_pk_bf16_f32 v66, v52, v53
	v_add_f32_e32 v232, v232, v54
	v_add_f32_e32 v233, v233, v55
	v_cvt_pk_bf16_f32 v67, v54, v55
	v_exp_f32_e32 v56, v56
	v_exp_f32_e32 v57, v57
	v_exp_f32_e32 v58, v58
	v_exp_f32_e32 v59, v59
	v_add_f32_e32 v232, v232, v56
	v_add_f32_e32 v233, v233, v57
	v_cvt_pk_bf16_f32 v68, v56, v57
	s_waitcnt lgkmcnt(3)
	v_mfma_f32_32x32x16_bf16 v[0:15], v[216:219], v[64:67], v[0:15]
	v_exp_f32_e32 v60, v60
	v_exp_f32_e32 v61, v61
	v_add_f32_e32 v232, v232, v58
	v_add_f32_e32 v233, v233, v59
	v_cvt_pk_bf16_f32 v69, v58, v59
	s_waitcnt lgkmcnt(2)
	v_mfma_f32_32x32x16_bf16 v[16:31], v[220:223], v[64:67], v[16:31]
	v_exp_f32_e32 v62, v62
	v_exp_f32_e32 v63, v63
	v_add_f32_e32 v232, v232, v60
	v_add_f32_e32 v233, v233, v61
	v_cvt_pk_bf16_f32 v70, v60, v61
	v_add_f32_e32 v232, v232, v62
	v_add_f32_e32 v233, v233, v63
	v_cvt_pk_bf16_f32 v71, v62, v63
	s_nop 1
	s_waitcnt lgkmcnt(1)
	v_mfma_f32_32x32x16_bf16 v[0:15], v[224:227], v[68:71], v[0:15]
	s_waitcnt lgkmcnt(0)
	v_mfma_f32_32x32x16_bf16 v[16:31], v[228:231], v[68:71], v[16:31]
	v_add_f32_e32 v232, v232, v233
	v_add_f32_e32 v112, v112, v232
	s_branch .Lt1_join

; #define LAS __attribute__((address_space(3)))
; #define MFMA32(a, b, c) __builtin_amdgcn_mfma_f32_32x32x16_bf16((a), (b), (c), 0, 0, 0)
; __device__ __forceinline__ float ex2(float x) { return __builtin_amdgcn_exp2f(x); }
; template <int MODE>
; __device__ __forceinline__ void attn_tile(const LAS unsigned char* Kb, const LAS unsigned char* Vb, const bf16x8_t (&qf)[4], f32x16 (&oacc)[2], float& l_run,
;                                           int r, int h, int dlt0, int dlt1, bool hiw) {
;     ...
; #pragma unroll
;     for (int mt = 0; mt < 4; ++mt) {
;         if (mt == 0) { if (hiw) __builtin_amdgcn_s_setprio(1); else __builtin_amdgcn_s_setprio(0); }
;         if (mt == 2) { if (hiw) __builtin_amdgcn_s_setprio(0); else __builtin_amdgcn_s_setprio(1); }
;         const int dl = mt < 2 ? dlt0 : dlt1;
;         f32x16 sacc = zero16();
; #pragma unroll
;         for (int ks = 0; ks < 4; ++ks) { const bf16x8_t ka = *(const LAS bf16x8_t*)(Kb + (32 * mt + r) * A_KSTR + 32 * ks + 16 * h); sacc = MFMA32(ka, qf[ks], sacc); }
; #pragma unroll
;         for (int i = 0; i < 16; ++i) {
;             float p;
;             if (MODE == 2) p = ex2(sacc[i]);
;             else if (MODE == 3) p = ex2(sacc[i] + __int_as_float(dl));
;             else { const int ci = 32 * mt + (i & 3) + 8 * (i >> 2); p = ((unsigned)(dl - ci) < ulim) ? ex2(sacc[i]) : 0.f; }
;             sacc[i] = p; ls += p;
;         }
; #pragma unroll
;         for (int s = 0; s < 2; ++s) {
;             const bf16x8_t pf = pack8(sacc, 8 * s);
; #pragma unroll
;             for (int dt = 0; dt < 2; ++dt) {
;                 const LAS unsigned char* vp = Vb + (32 * dt + r) * A_CVSTR + (32 * mt + 16 * s + 4 * h) * 2;
;                 const s16x4_t lo = *(const LAS s16x4_t*)vp, hi = *(const LAS s16x4_t*)(vp + 16);
;                 oacc[dt] = MFMA32(__builtin_shufflevector(lo, hi, 0, 1, 2, 3, 4, 5, 6, 7), pf, oacc[dt]);
;             }
;         }
;     }
.Lt2_full:
	ds_read_b128 v[200:203], v72 offset:0
	ds_read_b128 v[204:207], v72 offset:32
	ds_read_b128 v[208:211], v72 offset:64
	ds_read_b128 v[212:215], v72 offset:96
	ds_read2_b64 v[216:219], v73 offset0:0 offset1:2
	ds_read2_b64 v[220:223], v74 offset0:32 offset1:34
	ds_read2_b64 v[224:227], v73 offset0:4 offset1:6
	ds_read2_b64 v[228:231], v74 offset0:36 offset1:38
	s_waitcnt lgkmcnt(7)
	v_mfma_f32_32x32x16_bf16 v[32:47], v[200:203], v[80:83], 0
	ds_read_b128 v[200:203], v72 offset:4608
	s_waitcnt lgkmcnt(7)
	v_mfma_f32_32x32x16_bf16 v[32:47], v[204:207], v[84:87], v[32:47]
	ds_read_b128 v[204:207], v72 offset:4640
	s_waitcnt lgkmcnt(7)
	v_mfma_f32_32x32x16_bf16 v[32:47], v[208:211], v[88:91], v[32:47]
	ds_read_b128 v[208:211], v72 offset:4672
	s_waitcnt lgkmcnt(7)
	v_mfma_f32_32x32x16_bf16 v[32:47], v[212:215], v[92:95], v[32:47]
	ds_read_b128 v[212:215], v72 offset:4704
	s_nop 7
	s_nop 3
	s_waitcnt lgkmcnt(3)
	v_mfma_f32_32x32x16_bf16 v[48:63], v[200:203], v[80:83], 0
	ds_read_b128 v[200:203], v72 offset:9216
	v_exp_f32_e32 v32, v32
	v_exp_f32_e32 v33, v33
	s_waitcnt lgkmcnt(3)
	v_mfma_f32_32x32x16_bf16 v[48:63], v[204:207], v[84:87], v[48:63]
	ds_read_b128 v[204:207], v72 offset:9248
	v_exp_f32_e32 v34, v34
	v_exp_f32_e32 v35, v35
	v_mov_b32_e32 v232, v32
	v_mov_b32_e32 v233, v33
	v_cvt_pk_bf16_f32 v64, v32, v33
	v_exp_f32_e32 v36, v36
	v_exp_f32_e32 v37, v37
	v_add_f32_e32 v232, v232, v34
	v_add_f32_e32 v233, v233, v35
	v_cvt_pk_bf16_f32 v65, v34, v35
	v_exp_f32_e32 v38, v38
	v_exp_f32_e32 v39, v39
	v_add_f32_e32 v232, v232, v36
	v_add_f32_e32 v233, v233, v37
	v_cvt_pk_bf16_f32 v66, v36, v37
	v_add_f32_e32 v232, v232, v38
	v_add_f32_e32 v233, v233, v39
	v_cvt_pk_bf16_f32 v67, v38, v39
	s_waitcnt lgkmcnt(3)
	v_mfma_f32_32x32x16_bf16 v[48:63], v[208:211], v[88:91], v[48:63]
	ds_read_b128 v[208:211], v72 offset:9280
	v_exp_f32_e32 v40, v40
	v_exp_f32_e32 v41, v41
	s_waitcnt lgkmcnt(3)
	v_mfma_f32_32x32x16_bf16 v[48:63], v[212:215], v[92:95], v[48:63]
	ds_read_b128 v[212:215], v72 offset:9312
	v_exp_f32_e32 v42, v42
	v_exp_f32_e32 v43, v43
	v_add_f32_e32 v232, v232, v40
	v_add_f32_e32 v233, v233, v41
	v_cvt_pk_bf16_f32 v68, v40, v41
	v_mfma_f32_32x32x16_bf16 v[0:15], v[216:219], v[64:67], v[0:15]
	ds_read2_b64 v[216:219], v73 offset0:8 offset1:10
	v_exp_f32_e32 v44, v44
	v_exp_f32_e32 v45, v45
	v_add_f32_e32 v232, v232, v42
	v_add_f32_e32 v233, v233, v43
	v_cvt_pk_bf16_f32 v69, v42, v43
	v_mfma_f32_32x32x16_bf16 v[16:31], v[220:223], v[64:67], v[16:31]
	ds_read2_b64 v[220:223], v74 offset0:40 offset1:42
	v_exp_f32_e32 v46, v46
	v_exp_f32_e32 v47, v47
	v_add_f32_e32 v232, v232, v44
	v_add_f32_e32 v233, v233, v45
	v_cvt_pk_bf16_f32 v70, v44, v45
	v_add_f32_e32 v232, v232, v46
	v_add_f32_e32 v233, v233, v47
	v_cvt_pk_bf16_f32 v71, v46, v47
	s_waitcnt lgkmcnt(5)
	v_mfma_f32_32x32x16_bf16 v[32:47], v[200:203], v[80:83], 0
	ds_read_b128 v[200:203], v72 offset:13824
	v_exp_f32_e32 v48, v48
	v_exp_f32_e32 v49, v49
	s_waitcnt lgkmcnt(5)
	v_mfma_f32_32x32x16_bf16 v[32:47], v[204:207], v[84:87], v[32:47]
	ds_read_b128 v[204:207], v72 offset:13856
	v_exp_f32_e32 v50, v50
	v_exp_f32_e32 v51, v51
	v_add_f32_e32 v232, v232, v48
	v_add_f32_e32 v233, v233, v49
	v_cvt_pk_bf16_f32 v64, v48, v49
	v_mfma_f32_32x32x16_bf16 v[0:15], v[224:227], v[68:71], v[0:15]
	ds_read2_b64 v[224:227], v73 offset0:12 offset1:14
	v_exp_f32_e32 v52, v52
	v_exp_f32_e32 v53, v53
	v_add_f32_e32 v232, v232, v50
	v_add_f32_e32 v233, v233, v51
	v_cvt_pk_bf16_f32 v65, v50, v51
	v_mfma_f32_32x32x16_bf16 v[16:31], v[228:231], v[68:71], v[16:31]
	ds_read2_b64 v[228:231], v74 offset0:44 offset1:46
	v_exp_f32_e32 v54, v54
	v_exp_f32_e32 v55, v55
	v_add_f32_e32 v232, v232, v52
	v_add_f32_e32 v233, v233, v53
	v_cvt_pk_bf16_f32 v66, v52, v53
	v_add_f32_e32 v232, v232, v54
	v_add_f32_e32 v233, v233, v55
	v_cvt_pk_bf16_f32 v67, v54, v55
	s_waitcnt lgkmcnt(7)
	v_mfma_f32_32x32x16_bf16 v[32:47], v[208:211], v[88:91], v[32:47]
	ds_read_b128 v[208:211], v72 offset:13888
	v_exp_f32_e32 v56, v56
	v_exp_f32_e32 v57, v57
	s_waitcnt lgkmcnt(7)
	v_mfma_f32_32x32x16_bf16 v[32:47], v[212:215], v[92:95], v[32:47]
	ds_read_b128 v[212:215], v72 offset:13920
	v_exp_f32_e32 v58, v58
	v_exp_f32_e32 v59, v59
	v_add_f32_e32 v232, v232, v56
	v_add_f32_e32 v233, v233, v57
	v_cvt_pk_bf16_f32 v68, v56, v57
	s_waitcnt lgkmcnt(7)
	v_mfma_f32_32x32x16_bf16 v[0:15], v[216:219], v[64:67], v[0:15]
	ds_read2_b64 v[216:219], v73 offset0:16 offset1:18
	v_exp_f32_e32 v60, v60
	v_exp_f32_e32 v61, v61
	v_add_f32_e32 v232, v232, v58
	v_add_f32_e32 v233, v233, v59
	v_cvt_pk_bf16_f32 v69, v58, v59
	s_waitcnt lgkmcnt(7)
	v_mfma_f32_32x32x16_bf16 v[16:31], v[220:223], v[64:67], v[16:31]
	ds_read2_b64 v[220:223], v74 offset0:48 offset1:50
	v_exp_f32_e32 v62, v62
	v_exp_f32_e32 v63, v63
	v_add_f32_e32 v232, v232, v60
	v_add_f32_e32 v233, v233, v61
	v_cvt_pk_bf16_f32 v70, v60, v61
	v_add_f32_e32 v232, v232, v62
	v_add_f32_e32 v233, v233, v63
	v_cvt_pk_bf16_f32 v71, v62, v63
	s_waitcnt lgkmcnt(7)
	v_mfma_f32_32x32x16_bf16 v[48:63], v[200:203], v[80:83], 0
	v_exp_f32_e32 v32, v32
	v_exp_f32_e32 v33, v33
	s_waitcnt lgkmcnt(6)
	v_mfma_f32_32x32x16_bf16 v[48:63], v[204:207], v[84:87], v[48:63]
	v_exp_f32_e32 v34, v34
	v_exp_f32_e32 v35, v35
	v_add_f32_e32 v232, v232, v32
	v_add_f32_e32 v233, v233, v33
	v_cvt_pk_bf16_f32 v64, v32, v33
	s_waitcnt lgkmcnt(5)
	v_mfma_f32_32x32x16_bf16 v[0:15], v[224:227], v[68:71], v[0:15]
	ds_read2_b64 v[224:227], v73 offset0:20 offset1:22
	v_exp_f32_e32 v36, v36
	v_exp_f32_e32 v37, v37
	v_add_f32_e32 v232, v232, v34
	v_add_f32_e32 v233, v233, v35
	v_cvt_pk_bf16_f32 v65, v34, v35
	s_waitcnt lgkmcnt(5)
	v_mfma_f32_32x32x16_bf16 v[16:31], v[228:231], v[68:71], v[16:31]
	ds_read2_b64 v[228:231], v74 offset0:52 offset1:54
	v_exp_f32_e32 v38, v38
	v_exp_f32_e32 v39, v39
	v_add_f32_e32 v232, v232, v36
	v_add_f32_e32 v233, v233, v37
	v_cvt_pk_bf16_f32 v66, v36, v37
	v_add_f32_e32 v232, v232, v38
	v_add_f32_e32 v233, v233, v39
	v_cvt_pk_bf16_f32 v67, v38, v39
	s_cmp_eq_u32 s45, 0
	s_cbranch_scc1 .Lt2_full_nostage
	s_waitcnt vmcnt(3)
	ds_write_b128 v251, v[96:99]
	s_waitcnt vmcnt(2)
	ds_write_b128 v251, v[100:103] offset:9216
	s_waitcnt vmcnt(1)
	ds_write2_b64 v252, v[104:105], v[106:107] offset1:1
	s_waitcnt vmcnt(0)
	ds_write2_b64 v252, v[108:109], v[110:111] offset0:16 offset1:17
	s_mov_b32 s47, 1
; #define LAS __attribute__((address_space(3)))
; #define MFMA32(a, b, c) __builtin_amdgcn_mfma_f32_32x32x16_bf16((a), (b), (c), 0, 0, 0)
; __device__ __forceinline__ float ex2(float x) { return __builtin_amdgcn_exp2f(x); }
; template <int MODE>
; __device__ __forceinline__ void attn_tile(const LAS unsigned char* Kb, const LAS unsigned char* Vb, const bf16x8_t (&qf)[4], f32x16 (&oacc)[2], float& l_run,
;                                           int r, int h, int dlt0, int dlt1, bool hiw) {
;     ...
; #pragma unroll
;     for (int mt = 0; mt < 4; ++mt) {
;         if (mt == 0) { if (hiw) __builtin_amdgcn_s_setprio(1); else __builtin_amdgcn_s_setprio(0); }
;         if (mt == 2) { if (hiw) __builtin_amdgcn_s_setprio(0); else __builtin_amdgcn_s_setprio(1); }
;         const int dl = mt < 2 ? dlt0 : dlt1;
;         f32x16 sacc = zero16();
; #pragma unroll
;         for (int ks = 0; ks < 4; ++ks) { const bf16x8_t ka = *(const LAS bf16x8_t*)(Kb + (32 * mt + r) * A_KSTR + 32 * ks + 16 * h); sacc = MFMA32(ka, qf[ks], sacc); }
; #pragma unroll
;         for (int i = 0; i < 16; ++i) {
;             float p;
;             if (MODE == 2) p = ex2(sacc[i]);
;             else if (MODE == 3) p = ex2(sacc[i] + __int_as_float(dl));
;             else { const int ci = 32 * mt + (i & 3) + 8 * (i >> 2); p = ((unsigned)(dl - ci) < ulim) ? ex2(sacc[i]) : 0.f; }
;             sacc[i] = p; ls += p;
;         }
; #pragma unroll
;         for (int s = 0; s < 2; ++s) {
;             const bf16x8_t pf = pack8(sacc, 8 * s);
; #pragma unroll
;             for (int dt = 0; dt < 2; ++dt) {
;                 const LAS unsigned char* vp = Vb + (32 * dt + r) * A_CVSTR + (32 * mt + 16 * s + 4 * h) * 2;
;                 const s16x4_t lo = *(const LAS s16x4_t*)vp, hi = *(const LAS s16x4_t*)(vp + 16);
;                 oacc[dt] = MFMA32(__builtin_shufflevector(lo, hi, 0, 1, 2, 3, 4, 5, 6, 7), pf, oacc[dt]);
;             }
;         }
;     }
;     l_run += ls;
; }
.Lt2_full_nostage:
	s_waitcnt lgkmcnt(5)
	v_mfma_f32_32x32x16_bf16 v[48:63], v[208:211], v[88:91], v[48:63]
	v_exp_f32_e32 v40, v40
	v_exp_f32_e32 v41, v41
	s_waitcnt lgkmcnt(4)
	v_mfma_f32_32x32x16_bf16 v[48:63], v[212:215], v[92:95], v[48:63]
	v_exp_f32_e32 v42, v42
	v_exp_f32_e32 v43, v43
	v_add_f32_e32 v232, v232, v40
	v_add_f32_e32 v233, v233, v41
	v_cvt_pk_bf16_f32 v68, v40, v41
	s_waitcnt lgkmcnt(3)
	v_mfma_f32_32x32x16_bf16 v[0:15], v[216:219], v[64:67], v[0:15]
	ds_read2_b64 v[216:219], v73 offset0:24 offset1:26
	v_exp_f32_e32 v44, v44
	v_exp_f32_e32 v45, v45
	v_add_f32_e32 v232, v232, v42
	v_add_f32_e32 v233, v233, v43
	v_cvt_pk_bf16_f32 v69, v42, v43
	s_waitcnt lgkmcnt(3)
	v_mfma_f32_32x32x16_bf16 v[16:31], v[220:223], v[64:67], v[16:31]
	ds_read2_b64 v[220:223], v74 offset0:56 offset1:58
	v_exp_f32_e32 v46, v46
	v_exp_f32_e32 v47, v47
	v_add_f32_e32 v232, v232, v44
	v_add_f32_e32 v233, v233, v45
	v_cvt_pk_bf16_f32 v70, v44, v45
	v_add_f32_e32 v232, v232, v46
	v_add_f32_e32 v233, v233, v47
	v_cvt_pk_bf16_f32 v71, v46, v47
	v_exp_f32_e32 v48, v48
	v_exp_f32_e32 v49, v49
	v_exp_f32_e32 v50, v50
	v_exp_f32_e32 v51, v51
	v_add_f32_e32 v232, v232, v48
	v_add_f32_e32 v233, v233, v49
	v_cvt_pk_bf16_f32 v64, v48, v49
	s_waitcnt lgkmcnt(3)
	v_mfma_f32_32x32x16_bf16 v[0:15], v[224:227], v[68:71], v[0:15]
	ds_read2_b64 v[224:227], v73 offset0:28 offset1:30
	v_exp_f32_e32 v52, v52
	v_exp_f32_e32 v53, v53
	v_add_f32_e32 v232, v232, v50
	v_add_f32_e32 v233, v233, v51
	v_cvt_pk_bf16_f32 v65, v50, v51
	s_waitcnt lgkmcnt(3)
	v_mfma_f32_32x32x16_bf16 v[16:31], v[228:231], v[68:71], v[16:31]
	ds_read2_b64 v[228:231], v74 offset0:60 offset1:62
	v_exp_f32_e32 v54, v54
	v_exp_f32_e32 v55, v55
	v_add_f32_e32 v232, v232, v52
	v_add_f32_e32 v233, v233, v53
	v_cvt_pk_bf16_f32 v66, v52, v53
	v_add_f32_e32 v232, v232, v54
	v_add_f32_e32 v233, v233, v55
	v_cvt_pk_bf16_f32 v67, v54, v55
	v_exp_f32_e32 v56, v56
	v_exp_f32_e32 v57, v57
	v_exp_f32_e32 v58, v58
	v_exp_f32_e32 v59, v59
	v_add_f32_e32 v232, v232, v56
	v_add_f32_e32 v233, v233, v57
	v_cvt_pk_bf16_f32 v68, v56, v57
	s_waitcnt lgkmcnt(3)
	v_mfma_f32_32x32x16_bf16 v[0:15], v[216:219], v[64:67], v[0:15]
	v_exp_f32_e32 v60, v60
	v_exp_f32_e32 v61, v61
	v_add_f32_e32 v232, v232, v58
	v_add_f32_e32 v233, v233, v59
	v_cvt_pk_bf16_f32 v69, v58, v59
	s_waitcnt lgkmcnt(2)
	v_mfma_f32_32x32x16_bf16 v[16:31], v[220:223], v[64:67], v[16:31]
	v_exp_f32_e32 v62, v62
	v_exp_f32_e32 v63, v63
	v_add_f32_e32 v232, v232, v60
	v_add_f32_e32 v233, v233, v61
	v_cvt_pk_bf16_f32 v70, v60, v61
	v_add_f32_e32 v232, v232, v62
	v_add_f32_e32 v233, v233, v63
	v_cvt_pk_bf16_f32 v71, v62, v63
	s_nop 1
	s_waitcnt lgkmcnt(1)
	v_mfma_f32_32x32x16_bf16 v[0:15], v[224:227], v[68:71], v[0:15]
	s_waitcnt lgkmcnt(0)
	v_mfma_f32_32x32x16_bf16 v[16:31], v[228:231], v[68:71], v[16:31]
	v_add_f32_e32 v232, v232, v233
	v_add_f32_e32 v112, v112, v232
	s_branch .Lt2_join
.Lt2_bias:
	ds_read_b128 v[200:203], v72 offset:0
	ds_read_b128 v[204:207], v72 offset:32
	ds_read_b128 v[208:211], v72 offset:64
	ds_read_b128 v[212:215], v72 offset:96
	ds_read2_b64 v[216:219], v73 offset0:0 offset1:2
	ds_read2_b64 v[220:223], v74 offset0:32 offset1:34
	ds_read2_b64 v[224:227], v73 offset0:4 offset1:6
	ds_read2_b64 v[228:231], v74 offset0:36 offset1:38
	v_bfe_i32 v236, v198, s49, 1
	s_add_i32 s49, s49, 1
	v_bfe_i32 v237, v198, s49, 1
	s_waitcnt lgkmcnt(7)
	v_mfma_f32_32x32x16_bf16 v[32:47], v[200:203], v[80:83], 0
	ds_read_b128 v[200:203], v72 offset:4608
	s_waitcnt lgkmcnt(7)
	v_mfma_f32_32x32x16_bf16 v[32:47], v[204:207], v[84:87], v[32:47]
	ds_read_b128 v[204:207], v72 offset:4640
	s_waitcnt lgkmcnt(7)
	v_mfma_f32_32x32x16_bf16 v[32:47], v[208:211], v[88:91], v[32:47]
	ds_read_b128 v[208:211], v72 offset:4672
	s_waitcnt lgkmcnt(7)
	v_mfma_f32_32x32x16_bf16 v[32:47], v[212:215], v[92:95], v[32:47]
	ds_read_b128 v[212:215], v72 offset:4704
	s_nop 7
	s_nop 3
	s_waitcnt lgkmcnt(3)
	v_mfma_f32_32x32x16_bf16 v[48:63], v[200:203], v[80:83], 0
	ds_read_b128 v[200:203], v72 offset:9216
	v_exp_f32_e32 v32, v32
	v_exp_f32_e32 v33, v33
	s_waitcnt lgkmcnt(3)
	v_mfma_f32_32x32x16_bf16 v[48:63], v[204:207], v[84:87], v[48:63]
	ds_read_b128 v[204:207], v72 offset:9248
	v_exp_f32_e32 v34, v34
	v_exp_f32_e32 v35, v35
	v_mov_b32_e32 v232, v32
	v_mov_b32_e32 v233, v33
	v_cvt_pk_bf16_f32 v64, v32, v33
	v_and_b32_e32 v64, v236, v64
	v_exp_f32_e32 v36, v36
	v_exp_f32_e32 v37, v37
	v_add_f32_e32 v232, v232, v34
	v_add_f32_e32 v233, v233, v35
	v_cvt_pk_bf16_f32 v65, v34, v35
	v_and_b32_e32 v65, v236, v65
	v_exp_f32_e32 v38, v38
	v_exp_f32_e32 v39, v39
	v_add_f32_e32 v232, v232, v36
	v_add_f32_e32 v233, v233, v37
	v_cvt_pk_bf16_f32 v66, v36, v37
	v_and_b32_e32 v66, v236, v66
	v_add_f32_e32 v232, v232, v38
	v_add_f32_e32 v233, v233, v39
	v_cvt_pk_bf16_f32 v67, v38, v39
	v_and_b32_e32 v67, v236, v67
	s_waitcnt lgkmcnt(3)
	v_mfma_f32_32x32x16_bf16 v[48:63], v[208:211], v[88:91], v[48:63]
	ds_read_b128 v[208:211], v72 offset:9280
	v_exp_f32_e32 v40, v40
	v_exp_f32_e32 v41, v41
	s_waitcnt lgkmcnt(3)
	v_mfma_f32_32x32x16_bf16 v[48:63], v[212:215], v[92:95], v[48:63]
	ds_read_b128 v[212:215], v72 offset:9312
	v_exp_f32_e32 v42, v42
	v_exp_f32_e32 v43, v43
	v_add_f32_e32 v232, v232, v40
	v_add_f32_e32 v233, v233, v41
	v_cvt_pk_bf16_f32 v68, v40, v41
	v_and_b32_e32 v68, v236, v68
	v_mfma_f32_32x32x16_bf16 v[0:15], v[216:219], v[64:67], v[0:15]
	ds_read2_b64 v[216:219], v73 offset0:8 offset1:10
	v_exp_f32_e32 v44, v44
	v_exp_f32_e32 v45, v45
	v_add_f32_e32 v232, v232, v42
	v_add_f32_e32 v233, v233, v43
	v_cvt_pk_bf16_f32 v69, v42, v43
	v_and_b32_e32 v69, v236, v69
	v_mfma_f32_32x32x16_bf16 v[16:31], v[220:223], v[64:67], v[16:31]
	ds_read2_b64 v[220:223], v74 offset0:40 offset1:42
	v_exp_f32_e32 v46, v46
	v_exp_f32_e32 v47, v47
	v_add_f32_e32 v232, v232, v44
	v_add_f32_e32 v233, v233, v45
	v_cvt_pk_bf16_f32 v70, v44, v45
	v_and_b32_e32 v70, v236, v70
	v_add_f32_e32 v232, v232, v46
	v_add_f32_e32 v233, v233, v47
	v_cvt_pk_bf16_f32 v71, v46, v47
	v_and_b32_e32 v71, v236, v71
	s_waitcnt lgkmcnt(5)
; #define LAS __attribute__((address_space(3)))
; #define MFMA32(a, b, c) __builtin_amdgcn_mfma_f32_32x32x16_bf16((a), (b), (c), 0, 0, 0)
; __device__ __forceinline__ float ex2(float x) { return __builtin_amdgcn_exp2f(x); }
; template <int MODE>
; __device__ __forceinline__ void attn_tile(const LAS unsigned char* Kb, const LAS unsigned char* Vb, const bf16x8_t (&qf)[4], f32x16 (&oacc)[2], float& l_run,
;                                           int r, int h, int dlt0, int dlt1, bool hiw) {
;     ...
;     for (int mt = 0; mt < 4; ++mt) {
;         if (mt == 0) { if (hiw) __builtin_amdgcn_s_setprio(1); else __builtin_amdgcn_s_setprio(0); }
;         if (mt == 2) { if (hiw) __builtin_amdgcn_s_setprio(0); else __builtin_amdgcn_s_setprio(1); }
;         const int dl = mt < 2 ? dlt0 : dlt1;
;         f32x16 sacc = zero16();
; #pragma unroll
;         for (int ks = 0; ks < 4; ++ks) { const bf16x8_t ka = *(const LAS bf16x8_t*)(Kb + (32 * mt + r) * A_KSTR + 32 * ks + 16 * h); sacc = MFMA32(ka, qf[ks], sacc); }
; #pragma unroll
;         for (int i = 0; i < 16; ++i) {
;             float p;
;             if (MODE == 2) p = ex2(sacc[i]);
;             else if (MODE == 3) p = ex2(sacc[i] + __int_as_float(dl));
;             else { const int ci = 32 * mt + (i & 3) + 8 * (i >> 2); p = ((unsigned)(dl - ci) < ulim) ? ex2(sacc[i]) : 0.f; }
;             sacc[i] = p; ls += p;
;         }
; #pragma unroll
;         for (int s = 0; s < 2; ++s) {
;             const bf16x8_t pf = pack8(sacc, 8 * s);
; #pragma unroll
;             for (int dt = 0; dt < 2; ++dt) {
;                 const LAS unsigned char* vp = Vb + (32 * dt + r) * A_CVSTR + (32 * mt + 16 * s + 4 * h) * 2;
;                 const s16x4_t lo = *(const LAS s16x4_t*)vp, hi = *(const LAS s16x4_t*)(vp + 16);
;                 oacc[dt] = MFMA32(__builtin_shufflevector(lo, hi, 0, 1, 2, 3, 4, 5, 6, 7), pf, oacc[dt]);
;             }
;         }
;     }
;     l_run += ls;
	v_mfma_f32_32x32x16_bf16 v[32:47], v[200:203], v[80:83], 0
	ds_read_b128 v[200:203], v72 offset:13824
	v_exp_f32_e32 v48, v48
	v_exp_f32_e32 v49, v49
	s_waitcnt lgkmcnt(5)
	v_mfma_f32_32x32x16_bf16 v[32:47], v[204:207], v[84:87], v[32:47]
	ds_read_b128 v[204:207], v72 offset:13856
	v_exp_f32_e32 v50, v50
	v_exp_f32_e32 v51, v51
	v_add_f32_e32 v232, v232, v48
	v_add_f32_e32 v233, v233, v49
	v_cvt_pk_bf16_f32 v64, v48, v49
	v_and_b32_e32 v64, v236, v64
	v_mfma_f32_32x32x16_bf16 v[0:15], v[224:227], v[68:71], v[0:15]
	ds_read2_b64 v[224:227], v73 offset0:12 offset1:14
	v_exp_f32_e32 v52, v52
	v_exp_f32_e32 v53, v53
	v_add_f32_e32 v232, v232, v50
	v_add_f32_e32 v233, v233, v51
	v_cvt_pk_bf16_f32 v65, v50, v51
	v_and_b32_e32 v65, v236, v65
	v_mfma_f32_32x32x16_bf16 v[16:31], v[228:231], v[68:71], v[16:31]
	ds_read2_b64 v[228:231], v74 offset0:44 offset1:46
	v_exp_f32_e32 v54, v54
	v_exp_f32_e32 v55, v55
	v_add_f32_e32 v232, v232, v52
	v_add_f32_e32 v233, v233, v53
	v_cvt_pk_bf16_f32 v66, v52, v53
	v_and_b32_e32 v66, v236, v66
	v_add_f32_e32 v232, v232, v54
	v_add_f32_e32 v233, v233, v55
	v_cvt_pk_bf16_f32 v67, v54, v55
	v_and_b32_e32 v67, v236, v67
	s_waitcnt lgkmcnt(7)
	v_mfma_f32_32x32x16_bf16 v[32:47], v[208:211], v[88:91], v[32:47]
	ds_read_b128 v[208:211], v72 offset:13888
	v_exp_f32_e32 v56, v56
	v_exp_f32_e32 v57, v57
	s_waitcnt lgkmcnt(7)
	v_mfma_f32_32x32x16_bf16 v[32:47], v[212:215], v[92:95], v[32:47]
	ds_read_b128 v[212:215], v72 offset:13920
	v_exp_f32_e32 v58, v58
	v_exp_f32_e32 v59, v59
	v_add_f32_e32 v232, v232, v56
	v_add_f32_e32 v233, v233, v57
	v_cvt_pk_bf16_f32 v68, v56, v57
	v_and_b32_e32 v68, v236, v68
	s_waitcnt lgkmcnt(7)
	v_mfma_f32_32x32x16_bf16 v[0:15], v[216:219], v[64:67], v[0:15]
	ds_read2_b64 v[216:219], v73 offset0:16 offset1:18
	v_exp_f32_e32 v60, v60
	v_exp_f32_e32 v61, v61
	v_add_f32_e32 v232, v232, v58
	v_add_f32_e32 v233, v233, v59
	v_cvt_pk_bf16_f32 v69, v58, v59
	v_and_b32_e32 v69, v236, v69
	s_waitcnt lgkmcnt(7)
	v_mfma_f32_32x32x16_bf16 v[16:31], v[220:223], v[64:67], v[16:31]
	ds_read2_b64 v[220:223], v74 offset0:48 offset1:50
	v_exp_f32_e32 v62, v62
	v_exp_f32_e32 v63, v63
	v_add_f32_e32 v232, v232, v60
	v_add_f32_e32 v233, v233, v61
	v_cvt_pk_bf16_f32 v70, v60, v61
	v_and_b32_e32 v70, v236, v70
	v_add_f32_e32 v232, v232, v62
	v_add_f32_e32 v233, v233, v63
	v_cvt_pk_bf16_f32 v71, v62, v63
	v_and_b32_e32 v71, v236, v71
	s_waitcnt lgkmcnt(7)
	v_mfma_f32_32x32x16_bf16 v[48:63], v[200:203], v[80:83], 0
	v_exp_f32_e32 v32, v32
	v_exp_f32_e32 v33, v33
	s_waitcnt lgkmcnt(6)
	v_mfma_f32_32x32x16_bf16 v[48:63], v[204:207], v[84:87], v[48:63]
	v_exp_f32_e32 v34, v34
	v_exp_f32_e32 v35, v35
	v_mov_b32_e32 v234, v32
	v_mov_b32_e32 v235, v33
	v_cvt_pk_bf16_f32 v64, v32, v33
	v_and_b32_e32 v64, v237, v64
	s_waitcnt lgkmcnt(5)
	v_mfma_f32_32x32x16_bf16 v[0:15], v[224:227], v[68:71], v[0:15]
	ds_read2_b64 v[224:227], v73 offset0:20 offset1:22
	v_exp_f32_e32 v36, v36
	v_exp_f32_e32 v37, v37
	v_add_f32_e32 v234, v234, v34
	v_add_f32_e32 v235, v235, v35
	v_cvt_pk_bf16_f32 v65, v34, v35
	v_and_b32_e32 v65, v237, v65
	s_waitcnt lgkmcnt(5)
	v_mfma_f32_32x32x16_bf16 v[16:31], v[228:231], v[68:71], v[16:31]
	ds_read2_b64 v[228:231], v74 offset0:52 offset1:54
	v_exp_f32_e32 v38, v38
	v_exp_f32_e32 v39, v39
	v_add_f32_e32 v234, v234, v36
	v_add_f32_e32 v235, v235, v37
	v_cvt_pk_bf16_f32 v66, v36, v37
	v_and_b32_e32 v66, v237, v66
	v_add_f32_e32 v234, v234, v38
	v_add_f32_e32 v235, v235, v39
	v_cvt_pk_bf16_f32 v67, v38, v39
	v_and_b32_e32 v67, v237, v67
	s_cmp_eq_u32 s45, 0
	s_cbranch_scc1 .Lt2_bias_nostage
	s_waitcnt vmcnt(3)
	ds_write_b128 v251, v[96:99]
	s_waitcnt vmcnt(2)
	ds_write_b128 v251, v[100:103] offset:9216
	s_waitcnt vmcnt(1)
	ds_write2_b64 v252, v[104:105], v[106:107] offset1:1
	s_waitcnt vmcnt(0)
	ds_write2_b64 v252, v[108:109], v[110:111] offset0:16 offset1:17
	s_mov_b32 s47, 1
; #define LAS __attribute__((address_space(3)))
; #define MFMA32(a, b, c) __builtin_amdgcn_mfma_f32_32x32x16_bf16((a), (b), (c), 0, 0, 0)
; __device__ __forceinline__ float ex2(float x) { return __builtin_amdgcn_exp2f(x); }
; template <int MODE>
; __device__ __forceinline__ void attn_tile(const LAS unsigned char* Kb, const LAS unsigned char* Vb, const bf16x8_t (&qf)[4], f32x16 (&oacc)[2], float& l_run,
;                                           int r, int h, int dlt0, int dlt1, bool hiw) {
;     ...
;     for (int mt = 0; mt < 4; ++mt) {
;         if (mt == 0) { if (hiw) __builtin_amdgcn_s_setprio(1); else __builtin_amdgcn_s_setprio(0); }
;         if (mt == 2) { if (hiw) __builtin_amdgcn_s_setprio(0); else __builtin_amdgcn_s_setprio(1); }
;         const int dl = mt < 2 ? dlt0 : dlt1;
;         f32x16 sacc = zero16();
; #pragma unroll
;         for (int ks = 0; ks < 4; ++ks) { const bf16x8_t ka = *(const LAS bf16x8_t*)(Kb + (32 * mt + r) * A_KSTR + 32 * ks + 16 * h); sacc = MFMA32(ka, qf[ks], sacc); }
; #pragma unroll
;         for (int i = 0; i < 16; ++i) {
;             float p;
;             if (MODE == 2) p = ex2(sacc[i]);
;             else if (MODE == 3) p = ex2(sacc[i] + __int_as_float(dl));
;             else { const int ci = 32 * mt + (i & 3) + 8 * (i >> 2); p = ((unsigned)(dl - ci) < ulim) ? ex2(sacc[i]) : 0.f; }
;             sacc[i] = p; ls += p;
;         }
; #pragma unroll
;         for (int s = 0; s < 2; ++s) {
;             const bf16x8_t pf = pack8(sacc, 8 * s);
; #pragma unroll
;             for (int dt = 0; dt < 2; ++dt) {
;                 const LAS unsigned char* vp = Vb + (32 * dt + r) * A_CVSTR + (32 * mt + 16 * s + 4 * h) * 2;
;                 const s16x4_t lo = *(const LAS s16x4_t*)vp, hi = *(const LAS s16x4_t*)(vp + 16);
;                 oacc[dt] = MFMA32(__builtin_shufflevector(lo, hi, 0, 1, 2, 3, 4, 5, 6, 7), pf, oacc[dt]);
;             }
;         }
;     }
;     l_run += ls;
.Lt2_bias_nostage:
	s_waitcnt lgkmcnt(5)
	v_mfma_f32_32x32x16_bf16 v[48:63], v[208:211], v[88:91], v[48:63]
	v_exp_f32_e32 v40, v40
	v_exp_f32_e32 v41, v41
	s_waitcnt lgkmcnt(4)
	v_mfma_f32_32x32x16_bf16 v[48:63], v[212:215], v[92:95], v[48:63]
	v_exp_f32_e32 v42, v42
	v_exp_f32_e32 v43, v43
	v_add_f32_e32 v234, v234, v40
	v_add_f32_e32 v235, v235, v41
	v_cvt_pk_bf16_f32 v68, v40, v41
	v_and_b32_e32 v68, v237, v68
	s_waitcnt lgkmcnt(3)
	v_mfma_f32_32x32x16_bf16 v[0:15], v[216:219], v[64:67], v[0:15]
	ds_read2_b64 v[216:219], v73 offset0:24 offset1:26
	v_exp_f32_e32 v44, v44
	v_exp_f32_e32 v45, v45
	v_add_f32_e32 v234, v234, v42
	v_add_f32_e32 v235, v235, v43
	v_cvt_pk_bf16_f32 v69, v42, v43
	v_and_b32_e32 v69, v237, v69
	s_waitcnt lgkmcnt(3)
	v_mfma_f32_32x32x16_bf16 v[16:31], v[220:223], v[64:67], v[16:31]
	ds_read2_b64 v[220:223], v74 offset0:56 offset1:58
	v_exp_f32_e32 v46, v46
	v_exp_f32_e32 v47, v47
	v_add_f32_e32 v234, v234, v44
	v_add_f32_e32 v235, v235, v45
	v_cvt_pk_bf16_f32 v70, v44, v45
	v_and_b32_e32 v70, v237, v70
	v_add_f32_e32 v234, v234, v46
	v_add_f32_e32 v235, v235, v47
	v_cvt_pk_bf16_f32 v71, v46, v47
	v_and_b32_e32 v71, v237, v71
	v_exp_f32_e32 v48, v48
	v_exp_f32_e32 v49, v49
	v_exp_f32_e32 v50, v50
	v_exp_f32_e32 v51, v51
	v_add_f32_e32 v234, v234, v48
	v_add_f32_e32 v235, v235, v49
	v_cvt_pk_bf16_f32 v64, v48, v49
	v_and_b32_e32 v64, v237, v64
	s_waitcnt lgkmcnt(3)
	v_mfma_f32_32x32x16_bf16 v[0:15], v[224:227], v[68:71], v[0:15]
	ds_read2_b64 v[224:227], v73 offset0:28 offset1:30
	v_exp_f32_e32 v52, v52
	v_exp_f32_e32 v53, v53
	v_add_f32_e32 v234, v234, v50
	v_add_f32_e32 v235, v235, v51
	v_cvt_pk_bf16_f32 v65, v50, v51
	v_and_b32_e32 v65, v237, v65
	s_waitcnt lgkmcnt(3)
	v_mfma_f32_32x32x16_bf16 v[16:31], v[228:231], v[68:71], v[16:31]
	ds_read2_b64 v[228:231], v74 offset0:60 offset1:62
	v_exp_f32_e32 v54, v54
	v_exp_f32_e32 v55, v55
	v_add_f32_e32 v234, v234, v52
	v_add_f32_e32 v235, v235, v53
	v_cvt_pk_bf16_f32 v66, v52, v53
	v_and_b32_e32 v66, v237, v66
	v_add_f32_e32 v234, v234, v54
	v_add_f32_e32 v235, v235, v55
	v_cvt_pk_bf16_f32 v67, v54, v55
	v_and_b32_e32 v67, v237, v67
	v_exp_f32_e32 v56, v56
	v_exp_f32_e32 v57, v57
	v_exp_f32_e32 v58, v58
	v_exp_f32_e32 v59, v59
	v_add_f32_e32 v234, v234, v56
	v_add_f32_e32 v235, v235, v57
	v_cvt_pk_bf16_f32 v68, v56, v57
	v_and_b32_e32 v68, v237, v68
	s_waitcnt lgkmcnt(3)
	v_mfma_f32_32x32x16_bf16 v[0:15], v[216:219], v[64:67], v[0:15]
	v_exp_f32_e32 v60, v60
	v_exp_f32_e32 v61, v61
	v_add_f32_e32 v234, v234, v58
	v_add_f32_e32 v235, v235, v59
	v_cvt_pk_bf16_f32 v69, v58, v59
	v_and_b32_e32 v69, v237, v69
	s_waitcnt lgkmcnt(2)
	v_mfma_f32_32x32x16_bf16 v[16:31], v[220:223], v[64:67], v[16:31]
	v_exp_f32_e32 v62, v62
	v_exp_f32_e32 v63, v63
	v_add_f32_e32 v234, v234, v60
	v_add_f32_e32 v235, v235, v61
	v_cvt_pk_bf16_f32 v70, v60, v61
	v_and_b32_e32 v70, v237, v70
	v_add_f32_e32 v234, v234, v62
	v_add_f32_e32 v235, v235, v63
	v_cvt_pk_bf16_f32 v71, v62, v63
	v_and_b32_e32 v71, v237, v71
	s_nop 1
	s_waitcnt lgkmcnt(1)
	v_mfma_f32_32x32x16_bf16 v[0:15], v[224:227], v[68:71], v[0:15]
	s_waitcnt lgkmcnt(0)
	v_mfma_f32_32x32x16_bf16 v[16:31], v[228:231], v[68:71], v[16:31]
	v_add_f32_e32 v232, v232, v233
	v_add_f32_e32 v234, v234, v235
	v_and_b32_e32 v239, 1.0, v236
	v_and_b32_e32 v240, 1.0, v237
	v_fmac_f32_e32 v112, v232, v239
	v_fmac_f32_e32 v112, v234, v240
	s_branch .Lt2_join

; #define LAS __attribute__((address_space(3)))
; #define MFMA32(a, b, c) __builtin_amdgcn_mfma_f32_32x32x16_bf16((a), (b), (c), 0, 0, 0)
; __device__ __forceinline__ float ex2(float x) { return __builtin_amdgcn_exp2f(x); }
; template <int MODE>
; __device__ __forceinline__ void attn_tile(const LAS unsigned char* Kb, const LAS unsigned char* Vb, const bf16x8_t (&qf)[4], f32x16 (&oacc)[2], float& l_run,
;                                           int r, int h, int dlt0, int dlt1, bool hiw) {
;     ...
;     for (int mt = 0; mt < 4; ++mt) {
;         if (mt == 0) { if (hiw) __builtin_amdgcn_s_setprio(1); else __builtin_amdgcn_s_setprio(0); }
;         if (mt == 2) { if (hiw) __builtin_amdgcn_s_setprio(0); else __builtin_amdgcn_s_setprio(1); }
;         const int dl = mt < 2 ? dlt0 : dlt1;
;         f32x16 sacc = zero16();
; #pragma unroll
;         for (int ks = 0; ks < 4; ++ks) { const bf16x8_t ka = *(const LAS bf16x8_t*)(Kb + (32 * mt + r) * A_KSTR + 32 * ks + 16 * h); sacc = MFMA32(ka, qf[ks], sacc); }
; #pragma unroll
;         for (int i = 0; i < 16; ++i) {
;             float p;
;             if (MODE == 2) p = ex2(sacc[i]);
;             else if (MODE == 3) p = ex2(sacc[i] + __int_as_float(dl));
;             else { const int ci = 32 * mt + (i & 3) + 8 * (i >> 2); p = ((unsigned)(dl - ci) < ulim) ? ex2(sacc[i]) : 0.f; }
;             sacc[i] = p; ls += p;
;         }
; #pragma unroll
;         for (int s = 0; s < 2; ++s) {
;             const bf16x8_t pf = pack8(sacc, 8 * s);
; #pragma unroll
;             for (int dt = 0; dt < 2; ++dt) {
;                 const LAS unsigned char* vp = Vb + (32 * dt + r) * A_CVSTR + (32 * mt + 16 * s + 4 * h) * 2;
;                 const s16x4_t lo = *(const LAS s16x4_t*)vp, hi = *(const LAS s16x4_t*)(vp + 16);
;                 oacc[dt] = MFMA32(__builtin_shufflevector(lo, hi, 0, 1, 2, 3, 4, 5, 6, 7), pf, oacc[dt]);
;             }
;         }
;     }
;     l_run += ls;
.Lt2_d1:
	ds_read_b128 v[200:203], v72 offset:0
	ds_read_b128 v[204:207], v72 offset:32
	ds_read_b128 v[208:211], v72 offset:64
	ds_read_b128 v[212:215], v72 offset:96
	ds_read2_b64 v[216:219], v73 offset0:0 offset1:2
	ds_read2_b64 v[220:223], v74 offset0:32 offset1:34
	ds_read2_b64 v[224:227], v73 offset0:4 offset1:6
	ds_read2_b64 v[228:231], v74 offset0:36 offset1:38
	s_waitcnt lgkmcnt(7)
	v_mfma_f32_32x32x16_bf16 v[32:47], v[200:203], v[80:83], 0
	ds_read_b128 v[200:203], v72 offset:4608
	s_waitcnt lgkmcnt(7)
	v_mfma_f32_32x32x16_bf16 v[32:47], v[204:207], v[84:87], v[32:47]
	ds_read_b128 v[204:207], v72 offset:4640
	s_waitcnt lgkmcnt(7)
	v_mfma_f32_32x32x16_bf16 v[32:47], v[208:211], v[88:91], v[32:47]
	ds_read_b128 v[208:211], v72 offset:4672
	s_waitcnt lgkmcnt(7)
	v_mfma_f32_32x32x16_bf16 v[32:47], v[212:215], v[92:95], v[32:47]
	ds_read_b128 v[212:215], v72 offset:4704
	s_nop 7
	s_nop 3
	s_waitcnt lgkmcnt(3)
	v_mfma_f32_32x32x16_bf16 v[48:63], v[200:203], v[80:83], 0
	v_exp_f32_e32 v32, v32
	v_exp_f32_e32 v33, v33
	s_waitcnt lgkmcnt(2)
	v_mfma_f32_32x32x16_bf16 v[48:63], v[204:207], v[84:87], v[48:63]
	v_exp_f32_e32 v34, v34
	v_exp_f32_e32 v35, v35
	v_mov_b32_e32 v232, v32
	v_mov_b32_e32 v233, v33
	v_cvt_pk_bf16_f32 v64, v32, v33
	v_exp_f32_e32 v36, v36
	v_exp_f32_e32 v37, v37
	v_add_f32_e32 v232, v232, v34
	v_add_f32_e32 v233, v233, v35
	v_cvt_pk_bf16_f32 v65, v34, v35
	v_exp_f32_e32 v38, v38
	v_exp_f32_e32 v39, v39
	v_add_f32_e32 v232, v232, v36
	v_add_f32_e32 v233, v233, v37
	v_cvt_pk_bf16_f32 v66, v36, v37
	v_add_f32_e32 v232, v232, v38
	v_add_f32_e32 v233, v233, v39
	v_cvt_pk_bf16_f32 v67, v38, v39
	s_cmp_eq_u32 s45, 0
	s_cbranch_scc1 .Lt2_d1_nostage
	s_waitcnt vmcnt(3)
	ds_write_b128 v251, v[96:99]
	s_waitcnt vmcnt(2)
	ds_write_b128 v251, v[100:103] offset:9216
	s_waitcnt vmcnt(1)
	ds_write2_b64 v252, v[104:105], v[106:107] offset1:1
	s_waitcnt vmcnt(0)
	ds_write2_b64 v252, v[108:109], v[110:111] offset0:16 offset1:17
	s_mov_b32 s47, 1
.Lt2_d1_nostage:
	s_waitcnt lgkmcnt(1)
	v_mfma_f32_32x32x16_bf16 v[48:63], v[208:211], v[88:91], v[48:63]
	v_exp_f32_e32 v40, v40
	v_exp_f32_e32 v41, v41
	s_waitcnt lgkmcnt(0)
	v_mfma_f32_32x32x16_bf16 v[48:63], v[212:215], v[92:95], v[48:63]
	v_exp_f32_e32 v42, v42
	v_exp_f32_e32 v43, v43
	v_add_f32_e32 v232, v232, v40
	v_add_f32_e32 v233, v233, v41
	v_cvt_pk_bf16_f32 v68, v40, v41
	v_mfma_f32_32x32x16_bf16 v[0:15], v[216:219], v[64:67], v[0:15]
	ds_read2_b64 v[216:219], v73 offset0:8 offset1:10
	v_exp_f32_e32 v44, v44
	v_exp_f32_e32 v45, v45
	v_add_f32_e32 v232, v232, v42
	v_add_f32_e32 v233, v233, v43
	v_cvt_pk_bf16_f32 v69, v42, v43
	v_mfma_f32_32x32x16_bf16 v[16:31], v[220:223], v[64:67], v[16:31]
	ds_read2_b64 v[220:223], v74 offset0:40 offset1:42
	v_exp_f32_e32 v46, v46
	v_exp_f32_e32 v47, v47
	v_add_f32_e32 v232, v232, v44
	v_add_f32_e32 v233, v233, v45
	v_cvt_pk_bf16_f32 v70, v44, v45
	v_add_f32_e32 v232, v232, v46
	v_add_f32_e32 v233, v233, v47
	v_cvt_pk_bf16_f32 v71, v46, v47
	v_cmp_le_i32_e64 s[0:1], 0, v250
	v_cmp_le_i32_e64 s[4:5], 1, v250
	v_exp_f32_e32 v48, v48
	v_exp_f32_e32 v49, v49
	v_cmp_le_i32_e64 s[6:7], 2, v250
	v_cmp_le_i32_e64 s[48:49], 3, v250
	v_exp_f32_e32 v50, v50
	v_exp_f32_e32 v51, v51
	v_cndmask_b32_e64 v48, 0, v48, s[0:1]
	v_cndmask_b32_e64 v49, 0, v49, s[4:5]
	v_add_f32_e32 v232, v232, v48
	v_add_f32_e32 v233, v233, v49
	v_cvt_pk_bf16_f32 v64, v48, v49
	v_mfma_f32_32x32x16_bf16 v[0:15], v[224:227], v[68:71], v[0:15]
	ds_read2_b64 v[224:227], v73 offset0:12 offset1:14
	v_cmp_le_i32_e64 s[0:1], 8, v250
	v_cmp_le_i32_e64 s[4:5], 9, v250
	v_exp_f32_e32 v52, v52
	v_exp_f32_e32 v53, v53
	v_cndmask_b32_e64 v50, 0, v50, s[6:7]
	v_cndmask_b32_e64 v51, 0, v51, s[48:49]
	v_add_f32_e32 v232, v232, v50
	v_add_f32_e32 v233, v233, v51
	v_cvt_pk_bf16_f32 v65, v50, v51
	v_mfma_f32_32x32x16_bf16 v[16:31], v[228:231], v[68:71], v[16:31]
	ds_read2_b64 v[228:231], v74 offset0:44 offset1:46
	v_cmp_le_i32_e64 s[6:7], 10, v250
	v_cmp_le_i32_e64 s[48:49], 11, v250
	v_exp_f32_e32 v54, v54
	v_exp_f32_e32 v55, v55
	v_cndmask_b32_e64 v52, 0, v52, s[0:1]
	v_cndmask_b32_e64 v53, 0, v53, s[4:5]
	v_add_f32_e32 v232, v232, v52
	v_add_f32_e32 v233, v233, v53
	v_cvt_pk_bf16_f32 v66, v52, v53
	v_cndmask_b32_e64 v54, 0, v54, s[6:7]
	v_cndmask_b32_e64 v55, 0, v55, s[48:49]
	v_add_f32_e32 v232, v232, v54
	v_add_f32_e32 v233, v233, v55
	v_cvt_pk_bf16_f32 v67, v54, v55
	v_cmp_le_i32_e64 s[0:1], 16, v250
	v_cmp_le_i32_e64 s[4:5], 17, v250
	v_exp_f32_e32 v56, v56
	v_exp_f32_e32 v57, v57
	v_cmp_le_i32_e64 s[6:7], 18, v250
	v_cmp_le_i32_e64 s[48:49], 19, v250
	v_exp_f32_e32 v58, v58
	v_exp_f32_e32 v59, v59
	v_cndmask_b32_e64 v56, 0, v56, s[0:1]
	v_cndmask_b32_e64 v57, 0, v57, s[4:5]
	v_add_f32_e32 v232, v232, v56
	v_add_f32_e32 v233, v233, v57
	v_cvt_pk_bf16_f32 v68, v56, v57
	s_waitcnt lgkmcnt(3)
	v_mfma_f32_32x32x16_bf16 v[0:15], v[216:219], v[64:67], v[0:15]
	v_cmp_le_i32_e64 s[0:1], 24, v250
	v_cmp_le_i32_e64 s[4:5], 25, v250
	v_exp_f32_e32 v60, v60
	v_exp_f32_e32 v61, v61
	v_cndmask_b32_e64 v58, 0, v58, s[6:7]
	v_cndmask_b32_e64 v59, 0, v59, s[48:49]
	v_add_f32_e32 v232, v232, v58
	v_add_f32_e32 v233, v233, v59
	v_cvt_pk_bf16_f32 v69, v58, v59
	s_waitcnt lgkmcnt(2)
	v_mfma_f32_32x32x16_bf16 v[16:31], v[220:223], v[64:67], v[16:31]
	v_cmp_le_i32_e64 s[6:7], 26, v250
	v_cmp_le_i32_e64 s[48:49], 27, v250
	v_exp_f32_e32 v62, v62
	v_exp_f32_e32 v63, v63
	v_cndmask_b32_e64 v60, 0, v60, s[0:1]
	v_cndmask_b32_e64 v61, 0, v61, s[4:5]
	v_add_f32_e32 v232, v232, v60
	v_add_f32_e32 v233, v233, v61
	v_cvt_pk_bf16_f32 v70, v60, v61
	v_cndmask_b32_e64 v62, 0, v62, s[6:7]
	v_cndmask_b32_e64 v63, 0, v63, s[48:49]
	v_add_f32_e32 v232, v232, v62
	v_add_f32_e32 v233, v233, v63
	v_cvt_pk_bf16_f32 v71, v62, v63
	s_nop 1
	s_waitcnt lgkmcnt(1)
	v_mfma_f32_32x32x16_bf16 v[0:15], v[224:227], v[68:71], v[0:15]
	s_waitcnt lgkmcnt(0)
	v_mfma_f32_32x32x16_bf16 v[16:31], v[228:231], v[68:71], v[16:31]
	v_add_f32_e32 v232, v232, v233
	v_add_f32_e32 v112, v112, v232
	s_branch .Lt2_join
; #define LAS __attribute__((address_space(3)))
; #define MFMA32(a, b, c) __builtin_amdgcn_mfma_f32_32x32x16_bf16((a), (b), (c), 0, 0, 0)
; __device__ __forceinline__ float ex2(float x) { return __builtin_amdgcn_exp2f(x); }
; template <int MODE>
; __device__ __forceinline__ void attn_tile(const LAS unsigned char* Kb, const LAS unsigned char* Vb, const bf16x8_t (&qf)[4], f32x16 (&oacc)[2], float& l_run,
;                                           int r, int h, int dlt0, int dlt1, bool hiw) {
;     ...
;     for (int mt = 0; mt < 4; ++mt) {
;         if (mt == 0) { if (hiw) __builtin_amdgcn_s_setprio(1); else __builtin_amdgcn_s_setprio(0); }
;         if (mt == 2) { if (hiw) __builtin_amdgcn_s_setprio(0); else __builtin_amdgcn_s_setprio(1); }
;         const int dl = mt < 2 ? dlt0 : dlt1;
;         f32x16 sacc = zero16();
; #pragma unroll
;         for (int ks = 0; ks < 4; ++ks) { const bf16x8_t ka = *(const LAS bf16x8_t*)(Kb + (32 * mt + r) * A_KSTR + 32 * ks + 16 * h); sacc = MFMA32(ka, qf[ks], sacc); }
; #pragma unroll
;         for (int i = 0; i < 16; ++i) {
;             float p;
;             if (MODE == 2) p = ex2(sacc[i]);
;             else if (MODE == 3) p = ex2(sacc[i] + __int_as_float(dl));
;             else { const int ci = 32 * mt + (i & 3) + 8 * (i >> 2); p = ((unsigned)(dl - ci) < ulim) ? ex2(sacc[i]) : 0.f; }
;             sacc[i] = p; ls += p;
;         }
; #pragma unroll
;         for (int s = 0; s < 2; ++s) {
;             const bf16x8_t pf = pack8(sacc, 8 * s);
; #pragma unroll
;             for (int dt = 0; dt < 2; ++dt) {
;                 const LAS unsigned char* vp = Vb + (32 * dt + r) * A_CVSTR + (32 * mt + 16 * s + 4 * h) * 2;
;                 const s16x4_t lo = *(const LAS s16x4_t*)vp, hi = *(const LAS s16x4_t*)(vp + 16);
;                 oacc[dt] = MFMA32(__builtin_shufflevector(lo, hi, 0, 1, 2, 3, 4, 5, 6, 7), pf, oacc[dt]);
;             }
;         }
;     }
;     l_run += ls;
.Lt2_d2:
	ds_read_b128 v[200:203], v72 offset:0
	ds_read_b128 v[204:207], v72 offset:32
	ds_read_b128 v[208:211], v72 offset:64
	ds_read_b128 v[212:215], v72 offset:96
	ds_read2_b64 v[216:219], v73 offset0:0 offset1:2
	ds_read2_b64 v[220:223], v74 offset0:32 offset1:34
	ds_read2_b64 v[224:227], v73 offset0:4 offset1:6
	ds_read2_b64 v[228:231], v74 offset0:36 offset1:38
	s_waitcnt lgkmcnt(7)
	v_mfma_f32_32x32x16_bf16 v[32:47], v[200:203], v[80:83], 0
	ds_read_b128 v[200:203], v72 offset:4608
	s_waitcnt lgkmcnt(7)
	v_mfma_f32_32x32x16_bf16 v[32:47], v[204:207], v[84:87], v[32:47]
	ds_read_b128 v[204:207], v72 offset:4640
	s_waitcnt lgkmcnt(7)
	v_mfma_f32_32x32x16_bf16 v[32:47], v[208:211], v[88:91], v[32:47]
	ds_read_b128 v[208:211], v72 offset:4672
	s_waitcnt lgkmcnt(7)
	v_mfma_f32_32x32x16_bf16 v[32:47], v[212:215], v[92:95], v[32:47]
	ds_read_b128 v[212:215], v72 offset:4704
	s_nop 7
	s_nop 3
	s_waitcnt lgkmcnt(3)
	v_mfma_f32_32x32x16_bf16 v[48:63], v[200:203], v[80:83], 0
	ds_read_b128 v[200:203], v72 offset:9216
	v_exp_f32_e32 v32, v32
	v_exp_f32_e32 v33, v33
	s_waitcnt lgkmcnt(3)
	v_mfma_f32_32x32x16_bf16 v[48:63], v[204:207], v[84:87], v[48:63]
	ds_read_b128 v[204:207], v72 offset:9248
	v_exp_f32_e32 v34, v34
	v_exp_f32_e32 v35, v35
	v_mov_b32_e32 v232, v32
	v_mov_b32_e32 v233, v33
	v_cvt_pk_bf16_f32 v64, v32, v33
	v_exp_f32_e32 v36, v36
	v_exp_f32_e32 v37, v37
	v_add_f32_e32 v232, v232, v34
	v_add_f32_e32 v233, v233, v35
	v_cvt_pk_bf16_f32 v65, v34, v35
	v_exp_f32_e32 v38, v38
	v_exp_f32_e32 v39, v39
	v_add_f32_e32 v232, v232, v36
	v_add_f32_e32 v233, v233, v37
	v_cvt_pk_bf16_f32 v66, v36, v37
	v_add_f32_e32 v232, v232, v38
	v_add_f32_e32 v233, v233, v39
	v_cvt_pk_bf16_f32 v67, v38, v39
	s_waitcnt lgkmcnt(3)
	v_mfma_f32_32x32x16_bf16 v[48:63], v[208:211], v[88:91], v[48:63]
	ds_read_b128 v[208:211], v72 offset:9280
	v_exp_f32_e32 v40, v40
	v_exp_f32_e32 v41, v41
	s_waitcnt lgkmcnt(3)
	v_mfma_f32_32x32x16_bf16 v[48:63], v[212:215], v[92:95], v[48:63]
	ds_read_b128 v[212:215], v72 offset:9312
	v_exp_f32_e32 v42, v42
	v_exp_f32_e32 v43, v43
	v_add_f32_e32 v232, v232, v40
	v_add_f32_e32 v233, v233, v41
	v_cvt_pk_bf16_f32 v68, v40, v41
	v_mfma_f32_32x32x16_bf16 v[0:15], v[216:219], v[64:67], v[0:15]
	ds_read2_b64 v[216:219], v73 offset0:8 offset1:10
	v_exp_f32_e32 v44, v44
	v_exp_f32_e32 v45, v45
	v_add_f32_e32 v232, v232, v42
	v_add_f32_e32 v233, v233, v43
	v_cvt_pk_bf16_f32 v69, v42, v43
	v_mfma_f32_32x32x16_bf16 v[16:31], v[220:223], v[64:67], v[16:31]
	ds_read2_b64 v[220:223], v74 offset0:40 offset1:42
	v_exp_f32_e32 v46, v46
	v_exp_f32_e32 v47, v47
	v_add_f32_e32 v232, v232, v44
	v_add_f32_e32 v233, v233, v45
	v_cvt_pk_bf16_f32 v70, v44, v45
	v_add_f32_e32 v232, v232, v46
	v_add_f32_e32 v233, v233, v47
	v_cvt_pk_bf16_f32 v71, v46, v47
	s_waitcnt lgkmcnt(5)
	v_mfma_f32_32x32x16_bf16 v[32:47], v[200:203], v[80:83], 0
	v_exp_f32_e32 v48, v48
	v_exp_f32_e32 v49, v49
	s_waitcnt lgkmcnt(4)
	v_mfma_f32_32x32x16_bf16 v[32:47], v[204:207], v[84:87], v[32:47]
	v_exp_f32_e32 v50, v50
	v_exp_f32_e32 v51, v51
	v_add_f32_e32 v232, v232, v48
	v_add_f32_e32 v233, v233, v49
	v_cvt_pk_bf16_f32 v64, v48, v49
	v_mfma_f32_32x32x16_bf16 v[0:15], v[224:227], v[68:71], v[0:15]
	ds_read2_b64 v[224:227], v73 offset0:12 offset1:14
	v_exp_f32_e32 v52, v52
	v_exp_f32_e32 v53, v53
	v_add_f32_e32 v232, v232, v50
	v_add_f32_e32 v233, v233, v51
	v_cvt_pk_bf16_f32 v65, v50, v51
	v_mfma_f32_32x32x16_bf16 v[16:31], v[228:231], v[68:71], v[16:31]
	ds_read2_b64 v[228:231], v74 offset0:44 offset1:46
	v_exp_f32_e32 v54, v54
	v_exp_f32_e32 v55, v55
	v_add_f32_e32 v232, v232, v52
	v_add_f32_e32 v233, v233, v53
	v_cvt_pk_bf16_f32 v66, v52, v53
	v_add_f32_e32 v232, v232, v54
	v_add_f32_e32 v233, v233, v55
	v_cvt_pk_bf16_f32 v67, v54, v55
	s_cmp_eq_u32 s45, 0
	s_cbranch_scc1 .Lt2_d2_nostage
	s_waitcnt vmcnt(3)
	ds_write_b128 v251, v[96:99]
	s_waitcnt vmcnt(2)
	ds_write_b128 v251, v[100:103] offset:9216
	s_waitcnt vmcnt(1)
	ds_write2_b64 v252, v[104:105], v[106:107] offset1:1
	s_waitcnt vmcnt(0)
	ds_write2_b64 v252, v[108:109], v[110:111] offset0:16 offset1:17
	s_mov_b32 s47, 1
.Lt2_d2_nostage:
	s_waitcnt lgkmcnt(5)
	v_mfma_f32_32x32x16_bf16 v[32:47], v[208:211], v[88:91], v[32:47]
	v_exp_f32_e32 v56, v56
	v_exp_f32_e32 v57, v57
	s_waitcnt lgkmcnt(4)
	v_mfma_f32_32x32x16_bf16 v[32:47], v[212:215], v[92:95], v[32:47]
	v_exp_f32_e32 v58, v58
	v_exp_f32_e32 v59, v59
	v_add_f32_e32 v232, v232, v56
	v_add_f32_e32 v233, v233, v57
	v_cvt_pk_bf16_f32 v68, v56, v57
	s_waitcnt lgkmcnt(3)
	v_mfma_f32_32x32x16_bf16 v[0:15], v[216:219], v[64:67], v[0:15]
	ds_read2_b64 v[216:219], v73 offset0:16 offset1:18
	v_exp_f32_e32 v60, v60
	v_exp_f32_e32 v61, v61
	v_add_f32_e32 v232, v232, v58
	v_add_f32_e32 v233, v233, v59
	v_cvt_pk_bf16_f32 v69, v58, v59
	s_waitcnt lgkmcnt(3)
	v_mfma_f32_32x32x16_bf16 v[16:31], v[220:223], v[64:67], v[16:31]
	ds_read2_b64 v[220:223], v74 offset0:48 offset1:50
	v_exp_f32_e32 v62, v62
	v_exp_f32_e32 v63, v63
	v_add_f32_e32 v232, v232, v60
	v_add_f32_e32 v233, v233, v61
	v_cvt_pk_bf16_f32 v70, v60, v61
	v_add_f32_e32 v232, v232, v62
	v_add_f32_e32 v233, v233, v63
	v_cvt_pk_bf16_f32 v71, v62, v63
	v_cmp_le_i32_e64 s[0:1], 0, v250
	v_cmp_le_i32_e64 s[4:5], 1, v250
	v_exp_f32_e32 v32, v32
	v_exp_f32_e32 v33, v33
	v_cmp_le_i32_e64 s[6:7], 2, v250
	v_cmp_le_i32_e64 s[48:49], 3, v250
	v_exp_f32_e32 v34, v34
	v_exp_f32_e32 v35, v35
	v_cndmask_b32_e64 v32, 0, v32, s[0:1]
	v_cndmask_b32_e64 v33, 0, v33, s[4:5]
	v_add_f32_e32 v232, v232, v32
	v_add_f32_e32 v233, v233, v33
	v_cvt_pk_bf16_f32 v64, v32, v33
	s_waitcnt lgkmcnt(3)
; #define LAS __attribute__((address_space(3)))
; #define MFMA32(a, b, c) __builtin_amdgcn_mfma_f32_32x32x16_bf16((a), (b), (c), 0, 0, 0)
; __device__ __forceinline__ float ex2(float x) { return __builtin_amdgcn_exp2f(x); }
; template <int MODE>
; __device__ __forceinline__ void attn_tile(const LAS unsigned char* Kb, const LAS unsigned char* Vb, const bf16x8_t (&qf)[4], f32x16 (&oacc)[2], float& l_run,
;                                           int r, int h, int dlt0, int dlt1, bool hiw) {
;     ...
;     for (int mt = 0; mt < 4; ++mt) {
;         if (mt == 0) { if (hiw) __builtin_amdgcn_s_setprio(1); else __builtin_amdgcn_s_setprio(0); }
;         if (mt == 2) { if (hiw) __builtin_amdgcn_s_setprio(0); else __builtin_amdgcn_s_setprio(1); }
;         const int dl = mt < 2 ? dlt0 : dlt1;
;         f32x16 sacc = zero16();
; #pragma unroll
;         for (int ks = 0; ks < 4; ++ks) { const bf16x8_t ka = *(const LAS bf16x8_t*)(Kb + (32 * mt + r) * A_KSTR + 32 * ks + 16 * h); sacc = MFMA32(ka, qf[ks], sacc); }
; #pragma unroll
;         for (int i = 0; i < 16; ++i) {
;             float p;
;             if (MODE == 2) p = ex2(sacc[i]);
;             else if (MODE == 3) p = ex2(sacc[i] + __int_as_float(dl));
;             else { const int ci = 32 * mt + (i & 3) + 8 * (i >> 2); p = ((unsigned)(dl - ci) < ulim) ? ex2(sacc[i]) : 0.f; }
;             sacc[i] = p; ls += p;
;         }
; #pragma unroll
;         for (int s = 0; s < 2; ++s) {
;             const bf16x8_t pf = pack8(sacc, 8 * s);
; #pragma unroll
;             for (int dt = 0; dt < 2; ++dt) {
;                 const LAS unsigned char* vp = Vb + (32 * dt + r) * A_CVSTR + (32 * mt + 16 * s + 4 * h) * 2;
;                 const s16x4_t lo = *(const LAS s16x4_t*)vp, hi = *(const LAS s16x4_t*)(vp + 16);
;                 oacc[dt] = MFMA32(__builtin_shufflevector(lo, hi, 0, 1, 2, 3, 4, 5, 6, 7), pf, oacc[dt]);
;             }
;         }
;     }
;     l_run += ls;
	v_mfma_f32_32x32x16_bf16 v[0:15], v[224:227], v[68:71], v[0:15]
	ds_read2_b64 v[224:227], v73 offset0:20 offset1:22
	v_cmp_le_i32_e64 s[0:1], 8, v250
	v_cmp_le_i32_e64 s[4:5], 9, v250
	v_exp_f32_e32 v36, v36
	v_exp_f32_e32 v37, v37
	v_cndmask_b32_e64 v34, 0, v34, s[6:7]
	v_cndmask_b32_e64 v35, 0, v35, s[48:49]
	v_add_f32_e32 v232, v232, v34
	v_add_f32_e32 v233, v233, v35
	v_cvt_pk_bf16_f32 v65, v34, v35
	s_waitcnt lgkmcnt(3)
	v_mfma_f32_32x32x16_bf16 v[16:31], v[228:231], v[68:71], v[16:31]
	ds_read2_b64 v[228:231], v74 offset0:52 offset1:54
	v_cmp_le_i32_e64 s[6:7], 10, v250
	v_cmp_le_i32_e64 s[48:49], 11, v250
	v_exp_f32_e32 v38, v38
	v_exp_f32_e32 v39, v39
	v_cndmask_b32_e64 v36, 0, v36, s[0:1]
	v_cndmask_b32_e64 v37, 0, v37, s[4:5]
	v_add_f32_e32 v232, v232, v36
	v_add_f32_e32 v233, v233, v37
	v_cvt_pk_bf16_f32 v66, v36, v37
	v_cndmask_b32_e64 v38, 0, v38, s[6:7]
	v_cndmask_b32_e64 v39, 0, v39, s[48:49]
	v_add_f32_e32 v232, v232, v38
	v_add_f32_e32 v233, v233, v39
	v_cvt_pk_bf16_f32 v67, v38, v39
	v_cmp_le_i32_e64 s[0:1], 16, v250
	v_cmp_le_i32_e64 s[4:5], 17, v250
	v_exp_f32_e32 v40, v40
	v_exp_f32_e32 v41, v41
	v_cmp_le_i32_e64 s[6:7], 18, v250
	v_cmp_le_i32_e64 s[48:49], 19, v250
	v_exp_f32_e32 v42, v42
	v_exp_f32_e32 v43, v43
	v_cndmask_b32_e64 v40, 0, v40, s[0:1]
	v_cndmask_b32_e64 v41, 0, v41, s[4:5]
	v_add_f32_e32 v232, v232, v40
	v_add_f32_e32 v233, v233, v41
	v_cvt_pk_bf16_f32 v68, v40, v41
	s_waitcnt lgkmcnt(3)
	v_mfma_f32_32x32x16_bf16 v[0:15], v[216:219], v[64:67], v[0:15]
	v_cmp_le_i32_e64 s[0:1], 24, v250
	v_cmp_le_i32_e64 s[4:5], 25, v250
	v_exp_f32_e32 v44, v44
	v_exp_f32_e32 v45, v45
	v_cndmask_b32_e64 v42, 0, v42, s[6:7]
	v_cndmask_b32_e64 v43, 0, v43, s[48:49]
	v_add_f32_e32 v232, v232, v42
	v_add_f32_e32 v233, v233, v43
	v_cvt_pk_bf16_f32 v69, v42, v43
	s_waitcnt lgkmcnt(2)
	v_mfma_f32_32x32x16_bf16 v[16:31], v[220:223], v[64:67], v[16:31]
	v_cmp_le_i32_e64 s[6:7], 26, v250
	v_cmp_le_i32_e64 s[48:49], 27, v250
	v_exp_f32_e32 v46, v46
	v_exp_f32_e32 v47, v47
	v_cndmask_b32_e64 v44, 0, v44, s[0:1]
	v_cndmask_b32_e64 v45, 0, v45, s[4:5]
	v_add_f32_e32 v232, v232, v44
	v_add_f32_e32 v233, v233, v45
	v_cvt_pk_bf16_f32 v70, v44, v45
	v_cndmask_b32_e64 v46, 0, v46, s[6:7]
	v_cndmask_b32_e64 v47, 0, v47, s[48:49]
	v_add_f32_e32 v232, v232, v46
	v_add_f32_e32 v233, v233, v47
	v_cvt_pk_bf16_f32 v71, v46, v47
	s_nop 1
	s_waitcnt lgkmcnt(1)
	v_mfma_f32_32x32x16_bf16 v[0:15], v[224:227], v[68:71], v[0:15]
	s_waitcnt lgkmcnt(0)
	v_mfma_f32_32x32x16_bf16 v[16:31], v[228:231], v[68:71], v[16:31]
	v_add_f32_e32 v232, v232, v233
	v_add_f32_e32 v112, v112, v232
	s_branch .Lt2_join
.Lt2_d3:
	ds_read_b128 v[200:203], v72 offset:0
	ds_read_b128 v[204:207], v72 offset:32
	ds_read_b128 v[208:211], v72 offset:64
	ds_read_b128 v[212:215], v72 offset:96
	ds_read2_b64 v[216:219], v73 offset0:0 offset1:2
	ds_read2_b64 v[220:223], v74 offset0:32 offset1:34
	ds_read2_b64 v[224:227], v73 offset0:4 offset1:6
	ds_read2_b64 v[228:231], v74 offset0:36 offset1:38
	s_waitcnt lgkmcnt(7)
	v_mfma_f32_32x32x16_bf16 v[32:47], v[200:203], v[80:83], 0
	ds_read_b128 v[200:203], v72 offset:4608
	s_waitcnt lgkmcnt(7)
	v_mfma_f32_32x32x16_bf16 v[32:47], v[204:207], v[84:87], v[32:47]
	ds_read_b128 v[204:207], v72 offset:4640
	s_waitcnt lgkmcnt(7)
	v_mfma_f32_32x32x16_bf16 v[32:47], v[208:211], v[88:91], v[32:47]
	ds_read_b128 v[208:211], v72 offset:4672
	s_waitcnt lgkmcnt(7)
	v_mfma_f32_32x32x16_bf16 v[32:47], v[212:215], v[92:95], v[32:47]
	ds_read_b128 v[212:215], v72 offset:4704
	s_nop 7
	s_nop 3
	s_waitcnt lgkmcnt(3)
	v_mfma_f32_32x32x16_bf16 v[48:63], v[200:203], v[80:83], 0
	ds_read_b128 v[200:203], v72 offset:9216
	v_exp_f32_e32 v32, v32
	v_exp_f32_e32 v33, v33
	s_waitcnt lgkmcnt(3)
	v_mfma_f32_32x32x16_bf16 v[48:63], v[204:207], v[84:87], v[48:63]
	ds_read_b128 v[204:207], v72 offset:9248
	v_exp_f32_e32 v34, v34
	v_exp_f32_e32 v35, v35
	v_mov_b32_e32 v232, v32
	v_mov_b32_e32 v233, v33
	v_cvt_pk_bf16_f32 v64, v32, v33
	v_exp_f32_e32 v36, v36
	v_exp_f32_e32 v37, v37
	v_add_f32_e32 v232, v232, v34
	v_add_f32_e32 v233, v233, v35
	v_cvt_pk_bf16_f32 v65, v34, v35
	v_exp_f32_e32 v38, v38
	v_exp_f32_e32 v39, v39
	v_add_f32_e32 v232, v232, v36
	v_add_f32_e32 v233, v233, v37
	v_cvt_pk_bf16_f32 v66, v36, v37
	v_add_f32_e32 v232, v232, v38
	v_add_f32_e32 v233, v233, v39
	v_cvt_pk_bf16_f32 v67, v38, v39
	s_waitcnt lgkmcnt(3)
	v_mfma_f32_32x32x16_bf16 v[48:63], v[208:211], v[88:91], v[48:63]
	ds_read_b128 v[208:211], v72 offset:9280
	v_exp_f32_e32 v40, v40
	v_exp_f32_e32 v41, v41
	s_waitcnt lgkmcnt(3)
	v_mfma_f32_32x32x16_bf16 v[48:63], v[212:215], v[92:95], v[48:63]
	ds_read_b128 v[212:215], v72 offset:9312
	v_exp_f32_e32 v42, v42
	v_exp_f32_e32 v43, v43
	v_add_f32_e32 v232, v232, v40
	v_add_f32_e32 v233, v233, v41
	v_cvt_pk_bf16_f32 v68, v40, v41
	v_mfma_f32_32x32x16_bf16 v[0:15], v[216:219], v[64:67], v[0:15]
	ds_read2_b64 v[216:219], v73 offset0:8 offset1:10
	v_exp_f32_e32 v44, v44
	v_exp_f32_e32 v45, v45
	v_add_f32_e32 v232, v232, v42
	v_add_f32_e32 v233, v233, v43
	v_cvt_pk_bf16_f32 v69, v42, v43
	v_mfma_f32_32x32x16_bf16 v[16:31], v[220:223], v[64:67], v[16:31]
	ds_read2_b64 v[220:223], v74 offset0:40 offset1:42
	v_exp_f32_e32 v46, v46
	v_exp_f32_e32 v47, v47
	v_add_f32_e32 v232, v232, v44
	v_add_f32_e32 v233, v233, v45
	v_cvt_pk_bf16_f32 v70, v44, v45
	v_add_f32_e32 v232, v232, v46
	v_add_f32_e32 v233, v233, v47
	v_cvt_pk_bf16_f32 v71, v46, v47
	s_waitcnt lgkmcnt(5)
	v_mfma_f32_32x32x16_bf16 v[32:47], v[200:203], v[80:83], 0
	ds_read_b128 v[200:203], v72 offset:13824
	v_exp_f32_e32 v48, v48
	v_exp_f32_e32 v49, v49
	s_waitcnt lgkmcnt(5)
; #define LAS __attribute__((address_space(3)))
; #define MFMA32(a, b, c) __builtin_amdgcn_mfma_f32_32x32x16_bf16((a), (b), (c), 0, 0, 0)
; __device__ __forceinline__ float ex2(float x) { return __builtin_amdgcn_exp2f(x); }
; template <int MODE>
; __device__ __forceinline__ void attn_tile(const LAS unsigned char* Kb, const LAS unsigned char* Vb, const bf16x8_t (&qf)[4], f32x16 (&oacc)[2], float& l_run,
;                                           int r, int h, int dlt0, int dlt1, bool hiw) {
;     ...
;     for (int mt = 0; mt < 4; ++mt) {
;         if (mt == 0) { if (hiw) __builtin_amdgcn_s_setprio(1); else __builtin_amdgcn_s_setprio(0); }
;         if (mt == 2) { if (hiw) __builtin_amdgcn_s_setprio(0); else __builtin_amdgcn_s_setprio(1); }
;         const int dl = mt < 2 ? dlt0 : dlt1;
;         f32x16 sacc = zero16();
; #pragma unroll
;         for (int ks = 0; ks < 4; ++ks) { const bf16x8_t ka = *(const LAS bf16x8_t*)(Kb + (32 * mt + r) * A_KSTR + 32 * ks + 16 * h); sacc = MFMA32(ka, qf[ks], sacc); }
; #pragma unroll
;         for (int i = 0; i < 16; ++i) {
;             float p;
;             if (MODE == 2) p = ex2(sacc[i]);
;             else if (MODE == 3) p = ex2(sacc[i] + __int_as_float(dl));
;             else { const int ci = 32 * mt + (i & 3) + 8 * (i >> 2); p = ((unsigned)(dl - ci) < ulim) ? ex2(sacc[i]) : 0.f; }
;             sacc[i] = p; ls += p;
;         }
; #pragma unroll
;         for (int s = 0; s < 2; ++s) {
;             const bf16x8_t pf = pack8(sacc, 8 * s);
; #pragma unroll
;             for (int dt = 0; dt < 2; ++dt) {
;                 const LAS unsigned char* vp = Vb + (32 * dt + r) * A_CVSTR + (32 * mt + 16 * s + 4 * h) * 2;
;                 const s16x4_t lo = *(const LAS s16x4_t*)vp, hi = *(const LAS s16x4_t*)(vp + 16);
;                 oacc[dt] = MFMA32(__builtin_shufflevector(lo, hi, 0, 1, 2, 3, 4, 5, 6, 7), pf, oacc[dt]);
;             }
;         }
;     }
;     l_run += ls;
	v_mfma_f32_32x32x16_bf16 v[32:47], v[204:207], v[84:87], v[32:47]
	ds_read_b128 v[204:207], v72 offset:13856
	v_exp_f32_e32 v50, v50
	v_exp_f32_e32 v51, v51
	v_add_f32_e32 v232, v232, v48
	v_add_f32_e32 v233, v233, v49
	v_cvt_pk_bf16_f32 v64, v48, v49
	v_mfma_f32_32x32x16_bf16 v[0:15], v[224:227], v[68:71], v[0:15]
	ds_read2_b64 v[224:227], v73 offset0:12 offset1:14
	v_exp_f32_e32 v52, v52
	v_exp_f32_e32 v53, v53
	v_add_f32_e32 v232, v232, v50
	v_add_f32_e32 v233, v233, v51
	v_cvt_pk_bf16_f32 v65, v50, v51
	v_mfma_f32_32x32x16_bf16 v[16:31], v[228:231], v[68:71], v[16:31]
	ds_read2_b64 v[228:231], v74 offset0:44 offset1:46
	v_exp_f32_e32 v54, v54
	v_exp_f32_e32 v55, v55
	v_add_f32_e32 v232, v232, v52
	v_add_f32_e32 v233, v233, v53
	v_cvt_pk_bf16_f32 v66, v52, v53
	v_add_f32_e32 v232, v232, v54
	v_add_f32_e32 v233, v233, v55
	v_cvt_pk_bf16_f32 v67, v54, v55
	s_waitcnt lgkmcnt(7)
	v_mfma_f32_32x32x16_bf16 v[32:47], v[208:211], v[88:91], v[32:47]
	ds_read_b128 v[208:211], v72 offset:13888
	v_exp_f32_e32 v56, v56
	v_exp_f32_e32 v57, v57
	s_waitcnt lgkmcnt(7)
	v_mfma_f32_32x32x16_bf16 v[32:47], v[212:215], v[92:95], v[32:47]
	ds_read_b128 v[212:215], v72 offset:13920
	v_exp_f32_e32 v58, v58
	v_exp_f32_e32 v59, v59
	v_add_f32_e32 v232, v232, v56
	v_add_f32_e32 v233, v233, v57
	v_cvt_pk_bf16_f32 v68, v56, v57
	s_waitcnt lgkmcnt(7)
	v_mfma_f32_32x32x16_bf16 v[0:15], v[216:219], v[64:67], v[0:15]
	ds_read2_b64 v[216:219], v73 offset0:16 offset1:18
	v_exp_f32_e32 v60, v60
	v_exp_f32_e32 v61, v61
	v_add_f32_e32 v232, v232, v58
	v_add_f32_e32 v233, v233, v59
	v_cvt_pk_bf16_f32 v69, v58, v59
	s_waitcnt lgkmcnt(7)
	v_mfma_f32_32x32x16_bf16 v[16:31], v[220:223], v[64:67], v[16:31]
	ds_read2_b64 v[220:223], v74 offset0:48 offset1:50
	v_exp_f32_e32 v62, v62
	v_exp_f32_e32 v63, v63
	v_add_f32_e32 v232, v232, v60
	v_add_f32_e32 v233, v233, v61
	v_cvt_pk_bf16_f32 v70, v60, v61
	v_add_f32_e32 v232, v232, v62
	v_add_f32_e32 v233, v233, v63
	v_cvt_pk_bf16_f32 v71, v62, v63
	s_waitcnt lgkmcnt(7)
	v_mfma_f32_32x32x16_bf16 v[48:63], v[200:203], v[80:83], 0
	v_exp_f32_e32 v32, v32
	v_exp_f32_e32 v33, v33
	s_waitcnt lgkmcnt(6)
	v_mfma_f32_32x32x16_bf16 v[48:63], v[204:207], v[84:87], v[48:63]
	v_exp_f32_e32 v34, v34
	v_exp_f32_e32 v35, v35
	v_add_f32_e32 v232, v232, v32
	v_add_f32_e32 v233, v233, v33
	v_cvt_pk_bf16_f32 v64, v32, v33
	s_waitcnt lgkmcnt(5)
	v_mfma_f32_32x32x16_bf16 v[0:15], v[224:227], v[68:71], v[0:15]
	ds_read2_b64 v[224:227], v73 offset0:20 offset1:22
	v_exp_f32_e32 v36, v36
	v_exp_f32_e32 v37, v37
	v_add_f32_e32 v232, v232, v34
	v_add_f32_e32 v233, v233, v35
	v_cvt_pk_bf16_f32 v65, v34, v35
	s_waitcnt lgkmcnt(5)
	v_mfma_f32_32x32x16_bf16 v[16:31], v[228:231], v[68:71], v[16:31]
	ds_read2_b64 v[228:231], v74 offset0:52 offset1:54
	v_exp_f32_e32 v38, v38
	v_exp_f32_e32 v39, v39
	v_add_f32_e32 v232, v232, v36
	v_add_f32_e32 v233, v233, v37
	v_cvt_pk_bf16_f32 v66, v36, v37
	v_add_f32_e32 v232, v232, v38
	v_add_f32_e32 v233, v233, v39
	v_cvt_pk_bf16_f32 v67, v38, v39
	s_cmp_eq_u32 s45, 0
	s_cbranch_scc1 .Lt2_d3_nostage
	s_waitcnt vmcnt(3)
	ds_write_b128 v251, v[96:99]
	s_waitcnt vmcnt(2)
	ds_write_b128 v251, v[100:103] offset:9216
	s_waitcnt vmcnt(1)
	ds_write2_b64 v252, v[104:105], v[106:107] offset1:1
	s_waitcnt vmcnt(0)
	ds_write2_b64 v252, v[108:109], v[110:111] offset0:16 offset1:17
	s_mov_b32 s47, 1
.Lt2_d3_nostage:
	s_waitcnt lgkmcnt(5)
	v_mfma_f32_32x32x16_bf16 v[48:63], v[208:211], v[88:91], v[48:63]
	v_exp_f32_e32 v40, v40
	v_exp_f32_e32 v41, v41
	s_waitcnt lgkmcnt(4)
	v_mfma_f32_32x32x16_bf16 v[48:63], v[212:215], v[92:95], v[48:63]
	v_exp_f32_e32 v42, v42
	v_exp_f32_e32 v43, v43
	v_add_f32_e32 v232, v232, v40
	v_add_f32_e32 v233, v233, v41
	v_cvt_pk_bf16_f32 v68, v40, v41
	s_waitcnt lgkmcnt(3)
	v_mfma_f32_32x32x16_bf16 v[0:15], v[216:219], v[64:67], v[0:15]
	ds_read2_b64 v[216:219], v73 offset0:24 offset1:26
	v_exp_f32_e32 v44, v44
	v_exp_f32_e32 v45, v45
	v_add_f32_e32 v232, v232, v42
	v_add_f32_e32 v233, v233, v43
	v_cvt_pk_bf16_f32 v69, v42, v43
	s_waitcnt lgkmcnt(3)
	v_mfma_f32_32x32x16_bf16 v[16:31], v[220:223], v[64:67], v[16:31]
	ds_read2_b64 v[220:223], v74 offset0:56 offset1:58
	v_exp_f32_e32 v46, v46
	v_exp_f32_e32 v47, v47
	v_add_f32_e32 v232, v232, v44
	v_add_f32_e32 v233, v233, v45
	v_cvt_pk_bf16_f32 v70, v44, v45
	v_add_f32_e32 v232, v232, v46
	v_add_f32_e32 v233, v233, v47
	v_cvt_pk_bf16_f32 v71, v46, v47
	v_cmp_le_i32_e64 s[0:1], 0, v250
	v_cmp_le_i32_e64 s[4:5], 1, v250
	v_exp_f32_e32 v48, v48
	v_exp_f32_e32 v49, v49
	v_cmp_le_i32_e64 s[6:7], 2, v250
	v_cmp_le_i32_e64 s[48:49], 3, v250
	v_exp_f32_e32 v50, v50
	v_exp_f32_e32 v51, v51
	v_cndmask_b32_e64 v48, 0, v48, s[0:1]
	v_cndmask_b32_e64 v49, 0, v49, s[4:5]
	v_add_f32_e32 v232, v232, v48
	v_add_f32_e32 v233, v233, v49
	v_cvt_pk_bf16_f32 v64, v48, v49
	s_waitcnt lgkmcnt(3)
	v_mfma_f32_32x32x16_bf16 v[0:15], v[224:227], v[68:71], v[0:15]
	ds_read2_b64 v[224:227], v73 offset0:28 offset1:30
	v_cmp_le_i32_e64 s[0:1], 8, v250
	v_cmp_le_i32_e64 s[4:5], 9, v250
	v_exp_f32_e32 v52, v52
	v_exp_f32_e32 v53, v53
	v_cndmask_b32_e64 v50, 0, v50, s[6:7]
	v_cndmask_b32_e64 v51, 0, v51, s[48:49]
	v_add_f32_e32 v232, v232, v50
	v_add_f32_e32 v233, v233, v51
	v_cvt_pk_bf16_f32 v65, v50, v51
	s_waitcnt lgkmcnt(3)
; #define LAS __attribute__((address_space(3)))
; #define MFMA32(a, b, c) __builtin_amdgcn_mfma_f32_32x32x16_bf16((a), (b), (c), 0, 0, 0)
; __device__ __forceinline__ float ex2(float x) { return __builtin_amdgcn_exp2f(x); }
; template <int MODE>
; __device__ __forceinline__ void attn_tile(const LAS unsigned char* Kb, const LAS unsigned char* Vb, const bf16x8_t (&qf)[4], f32x16 (&oacc)[2], float& l_run,
;                                           int r, int h, int dlt0, int dlt1, bool hiw) {
;     ...
;     for (int mt = 0; mt < 4; ++mt) {
;         if (mt == 0) { if (hiw) __builtin_amdgcn_s_setprio(1); else __builtin_amdgcn_s_setprio(0); }
;         if (mt == 2) { if (hiw) __builtin_amdgcn_s_setprio(0); else __builtin_amdgcn_s_setprio(1); }
;         const int dl = mt < 2 ? dlt0 : dlt1;
;         f32x16 sacc = zero16();
; #pragma unroll
;         for (int ks = 0; ks < 4; ++ks) { const bf16x8_t ka = *(const LAS bf16x8_t*)(Kb + (32 * mt + r) * A_KSTR + 32 * ks + 16 * h); sacc = MFMA32(ka, qf[ks], sacc); }
; #pragma unroll
;         for (int i = 0; i < 16; ++i) {
;             float p;
;             if (MODE == 2) p = ex2(sacc[i]);
;             else if (MODE == 3) p = ex2(sacc[i] + __int_as_float(dl));
;             else { const int ci = 32 * mt + (i & 3) + 8 * (i >> 2); p = ((unsigned)(dl - ci) < ulim) ? ex2(sacc[i]) : 0.f; }
;             sacc[i] = p; ls += p;
;         }
; #pragma unroll
;         for (int s = 0; s < 2; ++s) {
;             const bf16x8_t pf = pack8(sacc, 8 * s);
; #pragma unroll
;             for (int dt = 0; dt < 2; ++dt) {
;                 const LAS unsigned char* vp = Vb + (32 * dt + r) * A_CVSTR + (32 * mt + 16 * s + 4 * h) * 2;
;                 const s16x4_t lo = *(const LAS s16x4_t*)vp, hi = *(const LAS s16x4_t*)(vp + 16);
;                 oacc[dt] = MFMA32(__builtin_shufflevector(lo, hi, 0, 1, 2, 3, 4, 5, 6, 7), pf, oacc[dt]);
;             }
;         }
;     }
;     l_run += ls;
	v_mfma_f32_32x32x16_bf16 v[16:31], v[228:231], v[68:71], v[16:31]
	ds_read2_b64 v[228:231], v74 offset0:60 offset1:62
	v_cmp_le_i32_e64 s[6:7], 10, v250
	v_cmp_le_i32_e64 s[48:49], 11, v250
	v_exp_f32_e32 v54, v54
	v_exp_f32_e32 v55, v55
	v_cndmask_b32_e64 v52, 0, v52, s[0:1]
	v_cndmask_b32_e64 v53, 0, v53, s[4:5]
	v_add_f32_e32 v232, v232, v52
	v_add_f32_e32 v233, v233, v53
	v_cvt_pk_bf16_f32 v66, v52, v53
	v_cndmask_b32_e64 v54, 0, v54, s[6:7]
	v_cndmask_b32_e64 v55, 0, v55, s[48:49]
	v_add_f32_e32 v232, v232, v54
	v_add_f32_e32 v233, v233, v55
	v_cvt_pk_bf16_f32 v67, v54, v55
	v_cmp_le_i32_e64 s[0:1], 16, v250
	v_cmp_le_i32_e64 s[4:5], 17, v250
	v_exp_f32_e32 v56, v56
	v_exp_f32_e32 v57, v57
	v_cmp_le_i32_e64 s[6:7], 18, v250
	v_cmp_le_i32_e64 s[48:49], 19, v250
	v_exp_f32_e32 v58, v58
	v_exp_f32_e32 v59, v59
	v_cndmask_b32_e64 v56, 0, v56, s[0:1]
	v_cndmask_b32_e64 v57, 0, v57, s[4:5]
	v_add_f32_e32 v232, v232, v56
	v_add_f32_e32 v233, v233, v57
	v_cvt_pk_bf16_f32 v68, v56, v57
	s_waitcnt lgkmcnt(3)
	v_mfma_f32_32x32x16_bf16 v[0:15], v[216:219], v[64:67], v[0:15]
	v_cmp_le_i32_e64 s[0:1], 24, v250
	v_cmp_le_i32_e64 s[4:5], 25, v250
	v_exp_f32_e32 v60, v60
	v_exp_f32_e32 v61, v61
	v_cndmask_b32_e64 v58, 0, v58, s[6:7]
	v_cndmask_b32_e64 v59, 0, v59, s[48:49]
	v_add_f32_e32 v232, v232, v58
	v_add_f32_e32 v233, v233, v59
	v_cvt_pk_bf16_f32 v69, v58, v59
	s_waitcnt lgkmcnt(2)
	v_mfma_f32_32x32x16_bf16 v[16:31], v[220:223], v[64:67], v[16:31]
	v_cmp_le_i32_e64 s[6:7], 26, v250
	v_cmp_le_i32_e64 s[48:49], 27, v250
	v_exp_f32_e32 v62, v62
	v_exp_f32_e32 v63, v63
	v_cndmask_b32_e64 v60, 0, v60, s[0:1]
	v_cndmask_b32_e64 v61, 0, v61, s[4:5]
	v_add_f32_e32 v232, v232, v60
	v_add_f32_e32 v233, v233, v61
	v_cvt_pk_bf16_f32 v70, v60, v61
	v_cndmask_b32_e64 v62, 0, v62, s[6:7]
	v_cndmask_b32_e64 v63, 0, v63, s[48:49]
	v_add_f32_e32 v232, v232, v62
	v_add_f32_e32 v233, v233, v63
	v_cvt_pk_bf16_f32 v71, v62, v63
	s_nop 1
	s_waitcnt lgkmcnt(1)
	v_mfma_f32_32x32x16_bf16 v[0:15], v[224:227], v[68:71], v[0:15]
	s_waitcnt lgkmcnt(0)
	v_mfma_f32_32x32x16_bf16 v[16:31], v[228:231], v[68:71], v[16:31]
	v_add_f32_e32 v232, v232, v233
	v_add_f32_e32 v112, v112, v232
	s_branch .Lt2_join
.Lt2_e0:
	ds_read_b128 v[200:203], v72 offset:0
	ds_read_b128 v[204:207], v72 offset:32
	ds_read_b128 v[208:211], v72 offset:64
	ds_read_b128 v[212:215], v72 offset:96
	ds_read2_b64 v[216:219], v73 offset0:0 offset1:2
	ds_read2_b64 v[220:223], v74 offset0:32 offset1:34
	ds_read2_b64 v[224:227], v73 offset0:4 offset1:6
	ds_read2_b64 v[228:231], v74 offset0:36 offset1:38
	s_waitcnt lgkmcnt(7)
	v_mfma_f32_32x32x16_bf16 v[32:47], v[200:203], v[80:83], 0
	ds_read_b128 v[200:203], v72 offset:4608
	s_waitcnt lgkmcnt(7)
	v_mfma_f32_32x32x16_bf16 v[32:47], v[204:207], v[84:87], v[32:47]
	ds_read_b128 v[204:207], v72 offset:4640
	s_waitcnt lgkmcnt(7)
	v_mfma_f32_32x32x16_bf16 v[32:47], v[208:211], v[88:91], v[32:47]
	ds_read_b128 v[208:211], v72 offset:4672
	s_waitcnt lgkmcnt(7)
	v_mfma_f32_32x32x16_bf16 v[32:47], v[212:215], v[92:95], v[32:47]
	ds_read_b128 v[212:215], v72 offset:4704
	s_nop 7
	s_nop 3
	s_waitcnt lgkmcnt(3)
	v_mfma_f32_32x32x16_bf16 v[48:63], v[200:203], v[80:83], 0
	ds_read_b128 v[200:203], v72 offset:9216
	v_cmp_le_i32_e64 s[0:1], 0, v250
	v_cmp_le_i32_e64 s[4:5], 1, v250
	v_exp_f32_e32 v32, v32
	v_exp_f32_e32 v33, v33
	s_waitcnt lgkmcnt(3)
	v_mfma_f32_32x32x16_bf16 v[48:63], v[204:207], v[84:87], v[48:63]
	ds_read_b128 v[204:207], v72 offset:9248
	v_cmp_le_i32_e64 s[6:7], 2, v250
	v_cmp_le_i32_e64 s[48:49], 3, v250
	v_exp_f32_e32 v34, v34
	v_exp_f32_e32 v35, v35
	v_cndmask_b32_e64 v32, v32, 0, s[0:1]
	v_cndmask_b32_e64 v33, v33, 0, s[4:5]
	v_mov_b32_e32 v232, v32
	v_mov_b32_e32 v233, v33
	v_cvt_pk_bf16_f32 v64, v32, v33
	v_cmp_le_i32_e64 s[0:1], 8, v250
	v_cmp_le_i32_e64 s[4:5], 9, v250
	v_exp_f32_e32 v36, v36
	v_exp_f32_e32 v37, v37
	v_cndmask_b32_e64 v34, v34, 0, s[6:7]
	v_cndmask_b32_e64 v35, v35, 0, s[48:49]
	v_add_f32_e32 v232, v232, v34
	v_add_f32_e32 v233, v233, v35
	v_cvt_pk_bf16_f32 v65, v34, v35
	v_cmp_le_i32_e64 s[6:7], 10, v250
	v_cmp_le_i32_e64 s[48:49], 11, v250
	v_exp_f32_e32 v38, v38
	v_exp_f32_e32 v39, v39
	v_cndmask_b32_e64 v36, v36, 0, s[0:1]
	v_cndmask_b32_e64 v37, v37, 0, s[4:5]
	v_add_f32_e32 v232, v232, v36
	v_add_f32_e32 v233, v233, v37
	v_cvt_pk_bf16_f32 v66, v36, v37
	v_cndmask_b32_e64 v38, v38, 0, s[6:7]
	v_cndmask_b32_e64 v39, v39, 0, s[48:49]
	v_add_f32_e32 v232, v232, v38
	v_add_f32_e32 v233, v233, v39
	v_cvt_pk_bf16_f32 v67, v38, v39
	s_waitcnt lgkmcnt(3)
	v_mfma_f32_32x32x16_bf16 v[48:63], v[208:211], v[88:91], v[48:63]
	ds_read_b128 v[208:211], v72 offset:9280
	v_cmp_le_i32_e64 s[0:1], 16, v250
	v_cmp_le_i32_e64 s[4:5], 17, v250
	v_exp_f32_e32 v40, v40
	v_exp_f32_e32 v41, v41
	s_waitcnt lgkmcnt(3)
	v_mfma_f32_32x32x16_bf16 v[48:63], v[212:215], v[92:95], v[48:63]
	ds_read_b128 v[212:215], v72 offset:9312
	v_cmp_le_i32_e64 s[6:7], 18, v250
	v_cmp_le_i32_e64 s[48:49], 19, v250
	v_exp_f32_e32 v42, v42
	v_exp_f32_e32 v43, v43
	v_cndmask_b32_e64 v40, v40, 0, s[0:1]
	v_cndmask_b32_e64 v41, v41, 0, s[4:5]
	v_add_f32_e32 v232, v232, v40
	v_add_f32_e32 v233, v233, v41
	v_cvt_pk_bf16_f32 v68, v40, v41
	v_mfma_f32_32x32x16_bf16 v[0:15], v[216:219], v[64:67], v[0:15]
	ds_read2_b64 v[216:219], v73 offset0:8 offset1:10
	v_cmp_le_i32_e64 s[0:1], 24, v250
	v_cmp_le_i32_e64 s[4:5], 25, v250
	v_exp_f32_e32 v44, v44
	v_exp_f32_e32 v45, v45
	v_cndmask_b32_e64 v42, v42, 0, s[6:7]
	v_cndmask_b32_e64 v43, v43, 0, s[48:49]
	v_add_f32_e32 v232, v232, v42
	v_add_f32_e32 v233, v233, v43
	v_cvt_pk_bf16_f32 v69, v42, v43
	v_mfma_f32_32x32x16_bf16 v[16:31], v[220:223], v[64:67], v[16:31]
	ds_read2_b64 v[220:223], v74 offset0:40 offset1:42
	v_cmp_le_i32_e64 s[6:7], 26, v250
	v_cmp_le_i32_e64 s[48:49], 27, v250
	v_exp_f32_e32 v46, v46
	v_exp_f32_e32 v47, v47
	v_cndmask_b32_e64 v44, v44, 0, s[0:1]
	v_cndmask_b32_e64 v45, v45, 0, s[4:5]
	v_add_f32_e32 v232, v232, v44
	v_add_f32_e32 v233, v233, v45
	v_cvt_pk_bf16_f32 v70, v44, v45
	v_cndmask_b32_e64 v46, v46, 0, s[6:7]
	v_cndmask_b32_e64 v47, v47, 0, s[48:49]
	v_add_f32_e32 v232, v232, v46
	v_add_f32_e32 v233, v233, v47
	v_cvt_pk_bf16_f32 v71, v46, v47
	s_waitcnt lgkmcnt(5)
; #define LAS __attribute__((address_space(3)))
; #define MFMA32(a, b, c) __builtin_amdgcn_mfma_f32_32x32x16_bf16((a), (b), (c), 0, 0, 0)
; __device__ __forceinline__ float ex2(float x) { return __builtin_amdgcn_exp2f(x); }
; template <int MODE>
; __device__ __forceinline__ void attn_tile(const LAS unsigned char* Kb, const LAS unsigned char* Vb, const bf16x8_t (&qf)[4], f32x16 (&oacc)[2], float& l_run,
;                                           int r, int h, int dlt0, int dlt1, bool hiw) {
;     ...
;     for (int mt = 0; mt < 4; ++mt) {
;         if (mt == 0) { if (hiw) __builtin_amdgcn_s_setprio(1); else __builtin_amdgcn_s_setprio(0); }
;         if (mt == 2) { if (hiw) __builtin_amdgcn_s_setprio(0); else __builtin_amdgcn_s_setprio(1); }
;         const int dl = mt < 2 ? dlt0 : dlt1;
;         f32x16 sacc = zero16();
; #pragma unroll
;         for (int ks = 0; ks < 4; ++ks) { const bf16x8_t ka = *(const LAS bf16x8_t*)(Kb + (32 * mt + r) * A_KSTR + 32 * ks + 16 * h); sacc = MFMA32(ka, qf[ks], sacc); }
; #pragma unroll
;         for (int i = 0; i < 16; ++i) {
;             float p;
;             if (MODE == 2) p = ex2(sacc[i]);
;             else if (MODE == 3) p = ex2(sacc[i] + __int_as_float(dl));
;             else { const int ci = 32 * mt + (i & 3) + 8 * (i >> 2); p = ((unsigned)(dl - ci) < ulim) ? ex2(sacc[i]) : 0.f; }
;             sacc[i] = p; ls += p;
;         }
; #pragma unroll
;         for (int s = 0; s < 2; ++s) {
;             const bf16x8_t pf = pack8(sacc, 8 * s);
; #pragma unroll
;             for (int dt = 0; dt < 2; ++dt) {
;                 const LAS unsigned char* vp = Vb + (32 * dt + r) * A_CVSTR + (32 * mt + 16 * s + 4 * h) * 2;
;                 const s16x4_t lo = *(const LAS s16x4_t*)vp, hi = *(const LAS s16x4_t*)(vp + 16);
;                 oacc[dt] = MFMA32(__builtin_shufflevector(lo, hi, 0, 1, 2, 3, 4, 5, 6, 7), pf, oacc[dt]);
;             }
;         }
;     }
;     l_run += ls;
	v_mfma_f32_32x32x16_bf16 v[32:47], v[200:203], v[80:83], 0
	ds_read_b128 v[200:203], v72 offset:13824
	v_exp_f32_e32 v48, v48
	v_exp_f32_e32 v49, v49
	s_waitcnt lgkmcnt(5)
	v_mfma_f32_32x32x16_bf16 v[32:47], v[204:207], v[84:87], v[32:47]
	ds_read_b128 v[204:207], v72 offset:13856
	v_exp_f32_e32 v50, v50
	v_exp_f32_e32 v51, v51
	v_add_f32_e32 v232, v232, v48
	v_add_f32_e32 v233, v233, v49
	v_cvt_pk_bf16_f32 v64, v48, v49
	v_mfma_f32_32x32x16_bf16 v[0:15], v[224:227], v[68:71], v[0:15]
	ds_read2_b64 v[224:227], v73 offset0:12 offset1:14
	v_exp_f32_e32 v52, v52
	v_exp_f32_e32 v53, v53
	v_add_f32_e32 v232, v232, v50
	v_add_f32_e32 v233, v233, v51
	v_cvt_pk_bf16_f32 v65, v50, v51
	v_mfma_f32_32x32x16_bf16 v[16:31], v[228:231], v[68:71], v[16:31]
	ds_read2_b64 v[228:231], v74 offset0:44 offset1:46
	v_exp_f32_e32 v54, v54
	v_exp_f32_e32 v55, v55
	v_add_f32_e32 v232, v232, v52
	v_add_f32_e32 v233, v233, v53
	v_cvt_pk_bf16_f32 v66, v52, v53
	v_add_f32_e32 v232, v232, v54
	v_add_f32_e32 v233, v233, v55
	v_cvt_pk_bf16_f32 v67, v54, v55
	s_waitcnt lgkmcnt(7)
	v_mfma_f32_32x32x16_bf16 v[32:47], v[208:211], v[88:91], v[32:47]
	ds_read_b128 v[208:211], v72 offset:13888
	v_exp_f32_e32 v56, v56
	v_exp_f32_e32 v57, v57
	s_waitcnt lgkmcnt(7)
	v_mfma_f32_32x32x16_bf16 v[32:47], v[212:215], v[92:95], v[32:47]
	ds_read_b128 v[212:215], v72 offset:13920
	v_exp_f32_e32 v58, v58
	v_exp_f32_e32 v59, v59
	v_add_f32_e32 v232, v232, v56
	v_add_f32_e32 v233, v233, v57
	v_cvt_pk_bf16_f32 v68, v56, v57
	s_waitcnt lgkmcnt(7)
	v_mfma_f32_32x32x16_bf16 v[0:15], v[216:219], v[64:67], v[0:15]
	ds_read2_b64 v[216:219], v73 offset0:16 offset1:18
	v_exp_f32_e32 v60, v60
	v_exp_f32_e32 v61, v61
	v_add_f32_e32 v232, v232, v58
	v_add_f32_e32 v233, v233, v59
	v_cvt_pk_bf16_f32 v69, v58, v59
	s_waitcnt lgkmcnt(7)
	v_mfma_f32_32x32x16_bf16 v[16:31], v[220:223], v[64:67], v[16:31]
	ds_read2_b64 v[220:223], v74 offset0:48 offset1:50
	v_exp_f32_e32 v62, v62
	v_exp_f32_e32 v63, v63
	v_add_f32_e32 v232, v232, v60
	v_add_f32_e32 v233, v233, v61
	v_cvt_pk_bf16_f32 v70, v60, v61
	v_add_f32_e32 v232, v232, v62
	v_add_f32_e32 v233, v233, v63
	v_cvt_pk_bf16_f32 v71, v62, v63
	s_waitcnt lgkmcnt(7)
	v_mfma_f32_32x32x16_bf16 v[48:63], v[200:203], v[80:83], 0
	v_exp_f32_e32 v32, v32
	v_exp_f32_e32 v33, v33
	s_waitcnt lgkmcnt(6)
	v_mfma_f32_32x32x16_bf16 v[48:63], v[204:207], v[84:87], v[48:63]
	v_exp_f32_e32 v34, v34
	v_exp_f32_e32 v35, v35
	v_add_f32_e32 v232, v232, v32
	v_add_f32_e32 v233, v233, v33
	v_cvt_pk_bf16_f32 v64, v32, v33
	s_waitcnt lgkmcnt(5)
	v_mfma_f32_32x32x16_bf16 v[0:15], v[224:227], v[68:71], v[0:15]
	ds_read2_b64 v[224:227], v73 offset0:20 offset1:22
	v_exp_f32_e32 v36, v36
	v_exp_f32_e32 v37, v37
	v_add_f32_e32 v232, v232, v34
	v_add_f32_e32 v233, v233, v35
	v_cvt_pk_bf16_f32 v65, v34, v35
	s_waitcnt lgkmcnt(5)
	v_mfma_f32_32x32x16_bf16 v[16:31], v[228:231], v[68:71], v[16:31]
	ds_read2_b64 v[228:231], v74 offset0:52 offset1:54
	v_exp_f32_e32 v38, v38
	v_exp_f32_e32 v39, v39
	v_add_f32_e32 v232, v232, v36
	v_add_f32_e32 v233, v233, v37
	v_cvt_pk_bf16_f32 v66, v36, v37
	v_add_f32_e32 v232, v232, v38
	v_add_f32_e32 v233, v233, v39
	v_cvt_pk_bf16_f32 v67, v38, v39
	s_cmp_eq_u32 s45, 0
	s_cbranch_scc1 .Lt2_e0_nostage
	s_waitcnt vmcnt(3)
	ds_write_b128 v251, v[96:99]
	s_waitcnt vmcnt(2)
	ds_write_b128 v251, v[100:103] offset:9216
	s_waitcnt vmcnt(1)
	ds_write2_b64 v252, v[104:105], v[106:107] offset1:1
	s_waitcnt vmcnt(0)
	ds_write2_b64 v252, v[108:109], v[110:111] offset0:16 offset1:17
	s_mov_b32 s47, 1
.Lt2_e0_nostage:
	s_waitcnt lgkmcnt(5)
	v_mfma_f32_32x32x16_bf16 v[48:63], v[208:211], v[88:91], v[48:63]
	v_exp_f32_e32 v40, v40
	v_exp_f32_e32 v41, v41
	s_waitcnt lgkmcnt(4)
	v_mfma_f32_32x32x16_bf16 v[48:63], v[212:215], v[92:95], v[48:63]
	v_exp_f32_e32 v42, v42
	v_exp_f32_e32 v43, v43
	v_add_f32_e32 v232, v232, v40
	v_add_f32_e32 v233, v233, v41
	v_cvt_pk_bf16_f32 v68, v40, v41
	s_waitcnt lgkmcnt(3)
	v_mfma_f32_32x32x16_bf16 v[0:15], v[216:219], v[64:67], v[0:15]
	ds_read2_b64 v[216:219], v73 offset0:24 offset1:26
	v_exp_f32_e32 v44, v44
	v_exp_f32_e32 v45, v45
	v_add_f32_e32 v232, v232, v42
	v_add_f32_e32 v233, v233, v43
	v_cvt_pk_bf16_f32 v69, v42, v43
	s_waitcnt lgkmcnt(3)
	v_mfma_f32_32x32x16_bf16 v[16:31], v[220:223], v[64:67], v[16:31]
	ds_read2_b64 v[220:223], v74 offset0:56 offset1:58
	v_exp_f32_e32 v46, v46
	v_exp_f32_e32 v47, v47
	v_add_f32_e32 v232, v232, v44
	v_add_f32_e32 v233, v233, v45
	v_cvt_pk_bf16_f32 v70, v44, v45
	v_add_f32_e32 v232, v232, v46
	v_add_f32_e32 v233, v233, v47
	v_cvt_pk_bf16_f32 v71, v46, v47
	v_exp_f32_e32 v48, v48
	v_exp_f32_e32 v49, v49
	v_exp_f32_e32 v50, v50
	v_exp_f32_e32 v51, v51
	v_add_f32_e32 v232, v232, v48
	v_add_f32_e32 v233, v233, v49
	v_cvt_pk_bf16_f32 v64, v48, v49
	s_waitcnt lgkmcnt(3)
	v_mfma_f32_32x32x16_bf16 v[0:15], v[224:227], v[68:71], v[0:15]
	ds_read2_b64 v[224:227], v73 offset0:28 offset1:30
	v_exp_f32_e32 v52, v52
	v_exp_f32_e32 v53, v53
	v_add_f32_e32 v232, v232, v50
	v_add_f32_e32 v233, v233, v51
	v_cvt_pk_bf16_f32 v65, v50, v51
	s_waitcnt lgkmcnt(3)
	v_mfma_f32_32x32x16_bf16 v[16:31], v[228:231], v[68:71], v[16:31]
	ds_read2_b64 v[228:231], v74 offset0:60 offset1:62
	v_exp_f32_e32 v54, v54
	v_exp_f32_e32 v55, v55
	v_add_f32_e32 v232, v232, v52
	v_add_f32_e32 v233, v233, v53
	v_cvt_pk_bf16_f32 v66, v52, v53
	v_add_f32_e32 v232, v232, v54
	v_add_f32_e32 v233, v233, v55
	v_cvt_pk_bf16_f32 v67, v54, v55
	v_exp_f32_e32 v56, v56
	v_exp_f32_e32 v57, v57
	v_exp_f32_e32 v58, v58
	v_exp_f32_e32 v59, v59
	v_add_f32_e32 v232, v232, v56
	v_add_f32_e32 v233, v233, v57
	v_cvt_pk_bf16_f32 v68, v56, v57
	s_waitcnt lgkmcnt(3)
	v_mfma_f32_32x32x16_bf16 v[0:15], v[216:219], v[64:67], v[0:15]
	v_exp_f32_e32 v60, v60
	v_exp_f32_e32 v61, v61
	v_add_f32_e32 v232, v232, v58
	v_add_f32_e32 v233, v233, v59
	v_cvt_pk_bf16_f32 v69, v58, v59
	s_waitcnt lgkmcnt(2)
	v_mfma_f32_32x32x16_bf16 v[16:31], v[220:223], v[64:67], v[16:31]
	v_exp_f32_e32 v62, v62
	v_exp_f32_e32 v63, v63
	v_add_f32_e32 v232, v232, v60
	v_add_f32_e32 v233, v233, v61
	v_cvt_pk_bf16_f32 v70, v60, v61
	v_add_f32_e32 v232, v232, v62
	v_add_f32_e32 v233, v233, v63
	v_cvt_pk_bf16_f32 v71, v62, v63
	s_nop 1
	s_waitcnt lgkmcnt(1)
	v_mfma_f32_32x32x16_bf16 v[0:15], v[224:227], v[68:71], v[0:15]
	s_waitcnt lgkmcnt(0)
	v_mfma_f32_32x32x16_bf16 v[16:31], v[228:231], v[68:71], v[16:31]
	v_add_f32_e32 v232, v232, v233
	v_add_f32_e32 v112, v112, v232
	s_branch .Lt2_join
; #define LAS __attribute__((address_space(3)))
; #define MFMA32(a, b, c) __builtin_amdgcn_mfma_f32_32x32x16_bf16((a), (b), (c), 0, 0, 0)
; __device__ __forceinline__ float ex2(float x) { return __builtin_amdgcn_exp2f(x); }
; template <int MODE>
; __device__ __forceinline__ void attn_tile(const LAS unsigned char* Kb, const LAS unsigned char* Vb, const bf16x8_t (&qf)[4], f32x16 (&oacc)[2], float& l_run,
;                                           int r, int h, int dlt0, int dlt1, bool hiw) {
;     ...
;     for (int mt = 0; mt < 4; ++mt) {
;         if (mt == 0) { if (hiw) __builtin_amdgcn_s_setprio(1); else __builtin_amdgcn_s_setprio(0); }
;         if (mt == 2) { if (hiw) __builtin_amdgcn_s_setprio(0); else __builtin_amdgcn_s_setprio(1); }
;         const int dl = mt < 2 ? dlt0 : dlt1;
;         f32x16 sacc = zero16();
; #pragma unroll
;         for (int ks = 0; ks < 4; ++ks) { const bf16x8_t ka = *(const LAS bf16x8_t*)(Kb + (32 * mt + r) * A_KSTR + 32 * ks + 16 * h); sacc = MFMA32(ka, qf[ks], sacc); }
; #pragma unroll
;         for (int i = 0; i < 16; ++i) {
;             float p;
;             if (MODE == 2) p = ex2(sacc[i]);
;             else if (MODE == 3) p = ex2(sacc[i] + __int_as_float(dl));
;             else { const int ci = 32 * mt + (i & 3) + 8 * (i >> 2); p = ((unsigned)(dl - ci) < ulim) ? ex2(sacc[i]) : 0.f; }
;             sacc[i] = p; ls += p;
;         }
; #pragma unroll
;         for (int s = 0; s < 2; ++s) {
;             const bf16x8_t pf = pack8(sacc, 8 * s);
; #pragma unroll
;             for (int dt = 0; dt < 2; ++dt) {
;                 const LAS unsigned char* vp = Vb + (32 * dt + r) * A_CVSTR + (32 * mt + 16 * s + 4 * h) * 2;
;                 const s16x4_t lo = *(const LAS s16x4_t*)vp, hi = *(const LAS s16x4_t*)(vp + 16);
;                 oacc[dt] = MFMA32(__builtin_shufflevector(lo, hi, 0, 1, 2, 3, 4, 5, 6, 7), pf, oacc[dt]);
;             }
;         }
;     }
;     l_run += ls;
.Lt2_e1:
	ds_read_b128 v[200:203], v72 offset:4608
	ds_read_b128 v[204:207], v72 offset:4640
	ds_read_b128 v[208:211], v72 offset:4672
	ds_read_b128 v[212:215], v72 offset:4704
	ds_read2_b64 v[216:219], v73 offset0:8 offset1:10
	ds_read2_b64 v[220:223], v74 offset0:40 offset1:42
	ds_read2_b64 v[224:227], v73 offset0:12 offset1:14
	ds_read2_b64 v[228:231], v74 offset0:44 offset1:46
	s_waitcnt lgkmcnt(7)
	v_mfma_f32_32x32x16_bf16 v[32:47], v[200:203], v[80:83], 0
	ds_read_b128 v[200:203], v72 offset:9216
	s_waitcnt lgkmcnt(7)
	v_mfma_f32_32x32x16_bf16 v[32:47], v[204:207], v[84:87], v[32:47]
	ds_read_b128 v[204:207], v72 offset:9248
	s_waitcnt lgkmcnt(7)
	v_mfma_f32_32x32x16_bf16 v[32:47], v[208:211], v[88:91], v[32:47]
	ds_read_b128 v[208:211], v72 offset:9280
	s_waitcnt lgkmcnt(7)
	v_mfma_f32_32x32x16_bf16 v[32:47], v[212:215], v[92:95], v[32:47]
	ds_read_b128 v[212:215], v72 offset:9312
	s_nop 7
	s_nop 3
	s_waitcnt lgkmcnt(3)
	v_mfma_f32_32x32x16_bf16 v[48:63], v[200:203], v[80:83], 0
	ds_read_b128 v[200:203], v72 offset:13824
	v_cmp_le_i32_e64 s[0:1], 0, v250
	v_cmp_le_i32_e64 s[4:5], 1, v250
	v_exp_f32_e32 v32, v32
	v_exp_f32_e32 v33, v33
	s_waitcnt lgkmcnt(3)
	v_mfma_f32_32x32x16_bf16 v[48:63], v[204:207], v[84:87], v[48:63]
	ds_read_b128 v[204:207], v72 offset:13856
	v_cmp_le_i32_e64 s[6:7], 2, v250
	v_cmp_le_i32_e64 s[48:49], 3, v250
	v_exp_f32_e32 v34, v34
	v_exp_f32_e32 v35, v35
	v_cndmask_b32_e64 v32, v32, 0, s[0:1]
	v_cndmask_b32_e64 v33, v33, 0, s[4:5]
	v_mov_b32_e32 v232, v32
	v_mov_b32_e32 v233, v33
	v_cvt_pk_bf16_f32 v64, v32, v33
	v_cmp_le_i32_e64 s[0:1], 8, v250
	v_cmp_le_i32_e64 s[4:5], 9, v250
	v_exp_f32_e32 v36, v36
	v_exp_f32_e32 v37, v37
	v_cndmask_b32_e64 v34, v34, 0, s[6:7]
	v_cndmask_b32_e64 v35, v35, 0, s[48:49]
	v_add_f32_e32 v232, v232, v34
	v_add_f32_e32 v233, v233, v35
	v_cvt_pk_bf16_f32 v65, v34, v35
	v_cmp_le_i32_e64 s[6:7], 10, v250
	v_cmp_le_i32_e64 s[48:49], 11, v250
	v_exp_f32_e32 v38, v38
	v_exp_f32_e32 v39, v39
	v_cndmask_b32_e64 v36, v36, 0, s[0:1]
	v_cndmask_b32_e64 v37, v37, 0, s[4:5]
	v_add_f32_e32 v232, v232, v36
	v_add_f32_e32 v233, v233, v37
	v_cvt_pk_bf16_f32 v66, v36, v37
	v_cndmask_b32_e64 v38, v38, 0, s[6:7]
	v_cndmask_b32_e64 v39, v39, 0, s[48:49]
	v_add_f32_e32 v232, v232, v38
	v_add_f32_e32 v233, v233, v39
	v_cvt_pk_bf16_f32 v67, v38, v39
	s_waitcnt lgkmcnt(3)
	v_mfma_f32_32x32x16_bf16 v[48:63], v[208:211], v[88:91], v[48:63]
	ds_read_b128 v[208:211], v72 offset:13888
	v_cmp_le_i32_e64 s[0:1], 16, v250
	v_cmp_le_i32_e64 s[4:5], 17, v250
	v_exp_f32_e32 v40, v40
	v_exp_f32_e32 v41, v41
	s_waitcnt lgkmcnt(3)
	v_mfma_f32_32x32x16_bf16 v[48:63], v[212:215], v[92:95], v[48:63]
	ds_read_b128 v[212:215], v72 offset:13920
	v_cmp_le_i32_e64 s[6:7], 18, v250
	v_cmp_le_i32_e64 s[48:49], 19, v250
	v_exp_f32_e32 v42, v42
	v_exp_f32_e32 v43, v43
	v_cndmask_b32_e64 v40, v40, 0, s[0:1]
	v_cndmask_b32_e64 v41, v41, 0, s[4:5]
	v_add_f32_e32 v232, v232, v40
	v_add_f32_e32 v233, v233, v41
	v_cvt_pk_bf16_f32 v68, v40, v41
	v_mfma_f32_32x32x16_bf16 v[0:15], v[216:219], v[64:67], v[0:15]
	ds_read2_b64 v[216:219], v73 offset0:16 offset1:18
	v_cmp_le_i32_e64 s[0:1], 24, v250
	v_cmp_le_i32_e64 s[4:5], 25, v250
	v_exp_f32_e32 v44, v44
	v_exp_f32_e32 v45, v45
	v_cndmask_b32_e64 v42, v42, 0, s[6:7]
	v_cndmask_b32_e64 v43, v43, 0, s[48:49]
	v_add_f32_e32 v232, v232, v42
	v_add_f32_e32 v233, v233, v43
	v_cvt_pk_bf16_f32 v69, v42, v43
	v_mfma_f32_32x32x16_bf16 v[16:31], v[220:223], v[64:67], v[16:31]
	ds_read2_b64 v[220:223], v74 offset0:48 offset1:50
	v_cmp_le_i32_e64 s[6:7], 26, v250
	v_cmp_le_i32_e64 s[48:49], 27, v250
	v_exp_f32_e32 v46, v46
	v_exp_f32_e32 v47, v47
	v_cndmask_b32_e64 v44, v44, 0, s[0:1]
	v_cndmask_b32_e64 v45, v45, 0, s[4:5]
	v_add_f32_e32 v232, v232, v44
	v_add_f32_e32 v233, v233, v45
	v_cvt_pk_bf16_f32 v70, v44, v45
	v_cndmask_b32_e64 v46, v46, 0, s[6:7]
	v_cndmask_b32_e64 v47, v47, 0, s[48:49]
	v_add_f32_e32 v232, v232, v46
	v_add_f32_e32 v233, v233, v47
	v_cvt_pk_bf16_f32 v71, v46, v47
	s_waitcnt lgkmcnt(5)
	v_mfma_f32_32x32x16_bf16 v[32:47], v[200:203], v[80:83], 0
	v_exp_f32_e32 v48, v48
	v_exp_f32_e32 v49, v49
	s_waitcnt lgkmcnt(4)
	v_mfma_f32_32x32x16_bf16 v[32:47], v[204:207], v[84:87], v[32:47]
	v_exp_f32_e32 v50, v50
	v_exp_f32_e32 v51, v51
	v_add_f32_e32 v232, v232, v48
	v_add_f32_e32 v233, v233, v49
	v_cvt_pk_bf16_f32 v64, v48, v49
	v_mfma_f32_32x32x16_bf16 v[0:15], v[224:227], v[68:71], v[0:15]
	ds_read2_b64 v[224:227], v73 offset0:20 offset1:22
	v_exp_f32_e32 v52, v52
	v_exp_f32_e32 v53, v53
	v_add_f32_e32 v232, v232, v50
	v_add_f32_e32 v233, v233, v51
	v_cvt_pk_bf16_f32 v65, v50, v51
	v_mfma_f32_32x32x16_bf16 v[16:31], v[228:231], v[68:71], v[16:31]
	ds_read2_b64 v[228:231], v74 offset0:52 offset1:54
	v_exp_f32_e32 v54, v54
	v_exp_f32_e32 v55, v55
	v_add_f32_e32 v232, v232, v52
	v_add_f32_e32 v233, v233, v53
	v_cvt_pk_bf16_f32 v66, v52, v53
	v_add_f32_e32 v232, v232, v54
	v_add_f32_e32 v233, v233, v55
	v_cvt_pk_bf16_f32 v67, v54, v55
	s_cmp_eq_u32 s45, 0
	s_cbranch_scc1 .Lt2_e1_nostage
	s_waitcnt vmcnt(3)
	ds_write_b128 v251, v[96:99]
	s_waitcnt vmcnt(2)
	ds_write_b128 v251, v[100:103] offset:9216
	s_waitcnt vmcnt(1)
	ds_write2_b64 v252, v[104:105], v[106:107] offset1:1
	s_waitcnt vmcnt(0)
	ds_write2_b64 v252, v[108:109], v[110:111] offset0:16 offset1:17
	s_mov_b32 s47, 1
; #define LAS __attribute__((address_space(3)))
; #define MFMA32(a, b, c) __builtin_amdgcn_mfma_f32_32x32x16_bf16((a), (b), (c), 0, 0, 0)
; __device__ __forceinline__ float ex2(float x) { return __builtin_amdgcn_exp2f(x); }
; template <int MODE>
; __device__ __forceinline__ void attn_tile(const LAS unsigned char* Kb, const LAS unsigned char* Vb, const bf16x8_t (&qf)[4], f32x16 (&oacc)[2], float& l_run,
;                                           int r, int h, int dlt0, int dlt1, bool hiw) {
;     ...
;     for (int mt = 0; mt < 4; ++mt) {
;         if (mt == 0) { if (hiw) __builtin_amdgcn_s_setprio(1); else __builtin_amdgcn_s_setprio(0); }
;         if (mt == 2) { if (hiw) __builtin_amdgcn_s_setprio(0); else __builtin_amdgcn_s_setprio(1); }
;         const int dl = mt < 2 ? dlt0 : dlt1;
;         f32x16 sacc = zero16();
; #pragma unroll
;         for (int ks = 0; ks < 4; ++ks) { const bf16x8_t ka = *(const LAS bf16x8_t*)(Kb + (32 * mt + r) * A_KSTR + 32 * ks + 16 * h); sacc = MFMA32(ka, qf[ks], sacc); }
; #pragma unroll
;         for (int i = 0; i < 16; ++i) {
;             float p;
;             if (MODE == 2) p = ex2(sacc[i]);
;             else if (MODE == 3) p = ex2(sacc[i] + __int_as_float(dl));
;             else { const int ci = 32 * mt + (i & 3) + 8 * (i >> 2); p = ((unsigned)(dl - ci) < ulim) ? ex2(sacc[i]) : 0.f; }
;             sacc[i] = p; ls += p;
;         }
; #pragma unroll
;         for (int s = 0; s < 2; ++s) {
;             const bf16x8_t pf = pack8(sacc, 8 * s);
; #pragma unroll
;             for (int dt = 0; dt < 2; ++dt) {
;                 const LAS unsigned char* vp = Vb + (32 * dt + r) * A_CVSTR + (32 * mt + 16 * s + 4 * h) * 2;
;                 const s16x4_t lo = *(const LAS s16x4_t*)vp, hi = *(const LAS s16x4_t*)(vp + 16);
;                 oacc[dt] = MFMA32(__builtin_shufflevector(lo, hi, 0, 1, 2, 3, 4, 5, 6, 7), pf, oacc[dt]);
;             }
;         }
;     }
;     l_run += ls;
.Lt2_e1_nostage:
	s_waitcnt lgkmcnt(5)
	v_mfma_f32_32x32x16_bf16 v[32:47], v[208:211], v[88:91], v[32:47]
	v_exp_f32_e32 v56, v56
	v_exp_f32_e32 v57, v57
	s_waitcnt lgkmcnt(4)
	v_mfma_f32_32x32x16_bf16 v[32:47], v[212:215], v[92:95], v[32:47]
	v_exp_f32_e32 v58, v58
	v_exp_f32_e32 v59, v59
	v_add_f32_e32 v232, v232, v56
	v_add_f32_e32 v233, v233, v57
	v_cvt_pk_bf16_f32 v68, v56, v57
	s_waitcnt lgkmcnt(3)
	v_mfma_f32_32x32x16_bf16 v[0:15], v[216:219], v[64:67], v[0:15]
	ds_read2_b64 v[216:219], v73 offset0:24 offset1:26
	v_exp_f32_e32 v60, v60
	v_exp_f32_e32 v61, v61
	v_add_f32_e32 v232, v232, v58
	v_add_f32_e32 v233, v233, v59
	v_cvt_pk_bf16_f32 v69, v58, v59
	s_waitcnt lgkmcnt(3)
	v_mfma_f32_32x32x16_bf16 v[16:31], v[220:223], v[64:67], v[16:31]
	ds_read2_b64 v[220:223], v74 offset0:56 offset1:58
	v_exp_f32_e32 v62, v62
	v_exp_f32_e32 v63, v63
	v_add_f32_e32 v232, v232, v60
	v_add_f32_e32 v233, v233, v61
	v_cvt_pk_bf16_f32 v70, v60, v61
	v_add_f32_e32 v232, v232, v62
	v_add_f32_e32 v233, v233, v63
	v_cvt_pk_bf16_f32 v71, v62, v63
	v_exp_f32_e32 v32, v32
	v_exp_f32_e32 v33, v33
	v_exp_f32_e32 v34, v34
	v_exp_f32_e32 v35, v35
	v_add_f32_e32 v232, v232, v32
	v_add_f32_e32 v233, v233, v33
	v_cvt_pk_bf16_f32 v64, v32, v33
	s_waitcnt lgkmcnt(3)
	v_mfma_f32_32x32x16_bf16 v[0:15], v[224:227], v[68:71], v[0:15]
	ds_read2_b64 v[224:227], v73 offset0:28 offset1:30
	v_exp_f32_e32 v36, v36
	v_exp_f32_e32 v37, v37
	v_add_f32_e32 v232, v232, v34
	v_add_f32_e32 v233, v233, v35
	v_cvt_pk_bf16_f32 v65, v34, v35
	s_waitcnt lgkmcnt(3)
	v_mfma_f32_32x32x16_bf16 v[16:31], v[228:231], v[68:71], v[16:31]
	ds_read2_b64 v[228:231], v74 offset0:60 offset1:62
	v_exp_f32_e32 v38, v38
	v_exp_f32_e32 v39, v39
	v_add_f32_e32 v232, v232, v36
	v_add_f32_e32 v233, v233, v37
	v_cvt_pk_bf16_f32 v66, v36, v37
	v_add_f32_e32 v232, v232, v38
	v_add_f32_e32 v233, v233, v39
	v_cvt_pk_bf16_f32 v67, v38, v39
	v_exp_f32_e32 v40, v40
	v_exp_f32_e32 v41, v41
	v_exp_f32_e32 v42, v42
	v_exp_f32_e32 v43, v43
	v_add_f32_e32 v232, v232, v40
	v_add_f32_e32 v233, v233, v41
	v_cvt_pk_bf16_f32 v68, v40, v41
	s_waitcnt lgkmcnt(3)
	v_mfma_f32_32x32x16_bf16 v[0:15], v[216:219], v[64:67], v[0:15]
	v_exp_f32_e32 v44, v44
	v_exp_f32_e32 v45, v45
	v_add_f32_e32 v232, v232, v42
	v_add_f32_e32 v233, v233, v43
	v_cvt_pk_bf16_f32 v69, v42, v43
	s_waitcnt lgkmcnt(2)
	v_mfma_f32_32x32x16_bf16 v[16:31], v[220:223], v[64:67], v[16:31]
	v_exp_f32_e32 v46, v46
	v_exp_f32_e32 v47, v47
	v_add_f32_e32 v232, v232, v44
	v_add_f32_e32 v233, v233, v45
	v_cvt_pk_bf16_f32 v70, v44, v45
	v_add_f32_e32 v232, v232, v46
	v_add_f32_e32 v233, v233, v47
	v_cvt_pk_bf16_f32 v71, v46, v47
	s_nop 1
	s_waitcnt lgkmcnt(1)
	v_mfma_f32_32x32x16_bf16 v[0:15], v[224:227], v[68:71], v[0:15]
	s_waitcnt lgkmcnt(0)
	v_mfma_f32_32x32x16_bf16 v[16:31], v[228:231], v[68:71], v[16:31]
	v_add_f32_e32 v232, v232, v233
	v_add_f32_e32 v112, v112, v232
	s_branch .Lt2_join
.Lt2_e2:
	ds_read_b128 v[200:203], v72 offset:9216
	ds_read_b128 v[204:207], v72 offset:9248
	ds_read_b128 v[208:211], v72 offset:9280
	ds_read_b128 v[212:215], v72 offset:9312
	ds_read2_b64 v[216:219], v73 offset0:16 offset1:18
	ds_read2_b64 v[220:223], v74 offset0:48 offset1:50
	ds_read2_b64 v[224:227], v73 offset0:20 offset1:22
	ds_read2_b64 v[228:231], v74 offset0:52 offset1:54
	s_waitcnt lgkmcnt(7)
	v_mfma_f32_32x32x16_bf16 v[32:47], v[200:203], v[80:83], 0
	ds_read_b128 v[200:203], v72 offset:13824
	s_waitcnt lgkmcnt(7)
	v_mfma_f32_32x32x16_bf16 v[32:47], v[204:207], v[84:87], v[32:47]
	ds_read_b128 v[204:207], v72 offset:13856
	s_waitcnt lgkmcnt(7)
	v_mfma_f32_32x32x16_bf16 v[32:47], v[208:211], v[88:91], v[32:47]
	ds_read_b128 v[208:211], v72 offset:13888
	s_waitcnt lgkmcnt(7)
	v_mfma_f32_32x32x16_bf16 v[32:47], v[212:215], v[92:95], v[32:47]
	ds_read_b128 v[212:215], v72 offset:13920
	s_nop 7
	s_nop 3
	s_waitcnt lgkmcnt(3)
	v_mfma_f32_32x32x16_bf16 v[48:63], v[200:203], v[80:83], 0
	v_cmp_le_i32_e64 s[0:1], 0, v250
	v_cmp_le_i32_e64 s[4:5], 1, v250
	v_exp_f32_e32 v32, v32
	v_exp_f32_e32 v33, v33
	s_waitcnt lgkmcnt(2)
	v_mfma_f32_32x32x16_bf16 v[48:63], v[204:207], v[84:87], v[48:63]
	v_cmp_le_i32_e64 s[6:7], 2, v250
	v_cmp_le_i32_e64 s[48:49], 3, v250
	v_exp_f32_e32 v34, v34
	v_exp_f32_e32 v35, v35
	v_cndmask_b32_e64 v32, v32, 0, s[0:1]
	v_cndmask_b32_e64 v33, v33, 0, s[4:5]
	v_mov_b32_e32 v232, v32
	v_mov_b32_e32 v233, v33
	v_cvt_pk_bf16_f32 v64, v32, v33
	v_cmp_le_i32_e64 s[0:1], 8, v250
	v_cmp_le_i32_e64 s[4:5], 9, v250
	v_exp_f32_e32 v36, v36
	v_exp_f32_e32 v37, v37
	v_cndmask_b32_e64 v34, v34, 0, s[6:7]
	v_cndmask_b32_e64 v35, v35, 0, s[48:49]
	v_add_f32_e32 v232, v232, v34
	v_add_f32_e32 v233, v233, v35
	v_cvt_pk_bf16_f32 v65, v34, v35
	v_cmp_le_i32_e64 s[6:7], 10, v250
	v_cmp_le_i32_e64 s[48:49], 11, v250
	v_exp_f32_e32 v38, v38
	v_exp_f32_e32 v39, v39
	v_cndmask_b32_e64 v36, v36, 0, s[0:1]
	v_cndmask_b32_e64 v37, v37, 0, s[4:5]
	v_add_f32_e32 v232, v232, v36
	v_add_f32_e32 v233, v233, v37
	v_cvt_pk_bf16_f32 v66, v36, v37
	v_cndmask_b32_e64 v38, v38, 0, s[6:7]
	v_cndmask_b32_e64 v39, v39, 0, s[48:49]
	v_add_f32_e32 v232, v232, v38
	v_add_f32_e32 v233, v233, v39
	v_cvt_pk_bf16_f32 v67, v38, v39
	s_cmp_eq_u32 s45, 0
	s_cbranch_scc1 .Lt2_e2_nostage
	s_waitcnt vmcnt(3)
	ds_write_b128 v251, v[96:99]
	s_waitcnt vmcnt(2)
	ds_write_b128 v251, v[100:103] offset:9216
	s_waitcnt vmcnt(1)
	ds_write2_b64 v252, v[104:105], v[106:107] offset1:1
	s_waitcnt vmcnt(0)
	ds_write2_b64 v252, v[108:109], v[110:111] offset0:16 offset1:17
	s_mov_b32 s47, 1
; #define LAS __attribute__((address_space(3)))
; #define MFMA32(a, b, c) __builtin_amdgcn_mfma_f32_32x32x16_bf16((a), (b), (c), 0, 0, 0)
; __device__ __forceinline__ float ex2(float x) { return __builtin_amdgcn_exp2f(x); }
; template <int MODE>
; __device__ __forceinline__ void attn_tile(const LAS unsigned char* Kb, const LAS unsigned char* Vb, const bf16x8_t (&qf)[4], f32x16 (&oacc)[2], float& l_run,
;                                           int r, int h, int dlt0, int dlt1, bool hiw) {
;     ...
;     for (int mt = 0; mt < 4; ++mt) {
;         if (mt == 0) { if (hiw) __builtin_amdgcn_s_setprio(1); else __builtin_amdgcn_s_setprio(0); }
;         if (mt == 2) { if (hiw) __builtin_amdgcn_s_setprio(0); else __builtin_amdgcn_s_setprio(1); }
;         const int dl = mt < 2 ? dlt0 : dlt1;
;         f32x16 sacc = zero16();
; #pragma unroll
;         for (int ks = 0; ks < 4; ++ks) { const bf16x8_t ka = *(const LAS bf16x8_t*)(Kb + (32 * mt + r) * A_KSTR + 32 * ks + 16 * h); sacc = MFMA32(ka, qf[ks], sacc); }
; #pragma unroll
;         for (int i = 0; i < 16; ++i) {
;             float p;
;             if (MODE == 2) p = ex2(sacc[i]);
;             else if (MODE == 3) p = ex2(sacc[i] + __int_as_float(dl));
;             else { const int ci = 32 * mt + (i & 3) + 8 * (i >> 2); p = ((unsigned)(dl - ci) < ulim) ? ex2(sacc[i]) : 0.f; }
;             sacc[i] = p; ls += p;
;         }
; #pragma unroll
;         for (int s = 0; s < 2; ++s) {
;             const bf16x8_t pf = pack8(sacc, 8 * s);
; #pragma unroll
;             for (int dt = 0; dt < 2; ++dt) {
;                 const LAS unsigned char* vp = Vb + (32 * dt + r) * A_CVSTR + (32 * mt + 16 * s + 4 * h) * 2;
;                 const s16x4_t lo = *(const LAS s16x4_t*)vp, hi = *(const LAS s16x4_t*)(vp + 16);
;                 oacc[dt] = MFMA32(__builtin_shufflevector(lo, hi, 0, 1, 2, 3, 4, 5, 6, 7), pf, oacc[dt]);
;             }
;         }
;     }
;     l_run += ls;
.Lt2_e2_nostage:
	s_waitcnt lgkmcnt(1)
	v_mfma_f32_32x32x16_bf16 v[48:63], v[208:211], v[88:91], v[48:63]
	v_cmp_le_i32_e64 s[0:1], 16, v250
	v_cmp_le_i32_e64 s[4:5], 17, v250
	v_exp_f32_e32 v40, v40
	v_exp_f32_e32 v41, v41
	s_waitcnt lgkmcnt(0)
	v_mfma_f32_32x32x16_bf16 v[48:63], v[212:215], v[92:95], v[48:63]
	v_cmp_le_i32_e64 s[6:7], 18, v250
	v_cmp_le_i32_e64 s[48:49], 19, v250
	v_exp_f32_e32 v42, v42
	v_exp_f32_e32 v43, v43
	v_cndmask_b32_e64 v40, v40, 0, s[0:1]
	v_cndmask_b32_e64 v41, v41, 0, s[4:5]
	v_add_f32_e32 v232, v232, v40
	v_add_f32_e32 v233, v233, v41
	v_cvt_pk_bf16_f32 v68, v40, v41
	v_mfma_f32_32x32x16_bf16 v[0:15], v[216:219], v[64:67], v[0:15]
	ds_read2_b64 v[216:219], v73 offset0:24 offset1:26
	v_cmp_le_i32_e64 s[0:1], 24, v250
	v_cmp_le_i32_e64 s[4:5], 25, v250
	v_exp_f32_e32 v44, v44
	v_exp_f32_e32 v45, v45
	v_cndmask_b32_e64 v42, v42, 0, s[6:7]
	v_cndmask_b32_e64 v43, v43, 0, s[48:49]
	v_add_f32_e32 v232, v232, v42
	v_add_f32_e32 v233, v233, v43
	v_cvt_pk_bf16_f32 v69, v42, v43
	v_mfma_f32_32x32x16_bf16 v[16:31], v[220:223], v[64:67], v[16:31]
	ds_read2_b64 v[220:223], v74 offset0:56 offset1:58
	v_cmp_le_i32_e64 s[6:7], 26, v250
	v_cmp_le_i32_e64 s[48:49], 27, v250
	v_exp_f32_e32 v46, v46
	v_exp_f32_e32 v47, v47
	v_cndmask_b32_e64 v44, v44, 0, s[0:1]
	v_cndmask_b32_e64 v45, v45, 0, s[4:5]
	v_add_f32_e32 v232, v232, v44
	v_add_f32_e32 v233, v233, v45
	v_cvt_pk_bf16_f32 v70, v44, v45
	v_cndmask_b32_e64 v46, v46, 0, s[6:7]
	v_cndmask_b32_e64 v47, v47, 0, s[48:49]
	v_add_f32_e32 v232, v232, v46
	v_add_f32_e32 v233, v233, v47
	v_cvt_pk_bf16_f32 v71, v46, v47
	v_exp_f32_e32 v48, v48
	v_exp_f32_e32 v49, v49
	v_exp_f32_e32 v50, v50
	v_exp_f32_e32 v51, v51
	v_add_f32_e32 v232, v232, v48
	v_add_f32_e32 v233, v233, v49
	v_cvt_pk_bf16_f32 v64, v48, v49
	v_mfma_f32_32x32x16_bf16 v[0:15], v[224:227], v[68:71], v[0:15]
	ds_read2_b64 v[224:227], v73 offset0:28 offset1:30
	v_exp_f32_e32 v52, v52
	v_exp_f32_e32 v53, v53
	v_add_f32_e32 v232, v232, v50
	v_add_f32_e32 v233, v233, v51
	v_cvt_pk_bf16_f32 v65, v50, v51
	v_mfma_f32_32x32x16_bf16 v[16:31], v[228:231], v[68:71], v[16:31]
	ds_read2_b64 v[228:231], v74 offset0:60 offset1:62
	v_exp_f32_e32 v54, v54
	v_exp_f32_e32 v55, v55
	v_add_f32_e32 v232, v232, v52
	v_add_f32_e32 v233, v233, v53
	v_cvt_pk_bf16_f32 v66, v52, v53
	v_add_f32_e32 v232, v232, v54
	v_add_f32_e32 v233, v233, v55
	v_cvt_pk_bf16_f32 v67, v54, v55
	v_exp_f32_e32 v56, v56
	v_exp_f32_e32 v57, v57
	v_exp_f32_e32 v58, v58
	v_exp_f32_e32 v59, v59
	v_add_f32_e32 v232, v232, v56
	v_add_f32_e32 v233, v233, v57
	v_cvt_pk_bf16_f32 v68, v56, v57
	s_waitcnt lgkmcnt(3)
	v_mfma_f32_32x32x16_bf16 v[0:15], v[216:219], v[64:67], v[0:15]
	v_exp_f32_e32 v60, v60
	v_exp_f32_e32 v61, v61
	v_add_f32_e32 v232, v232, v58
	v_add_f32_e32 v233, v233, v59
	v_cvt_pk_bf16_f32 v69, v58, v59
	s_waitcnt lgkmcnt(2)
	v_mfma_f32_32x32x16_bf16 v[16:31], v[220:223], v[64:67], v[16:31]
	v_exp_f32_e32 v62, v62
	v_exp_f32_e32 v63, v63
	v_add_f32_e32 v232, v232, v60
	v_add_f32_e32 v233, v233, v61
	v_cvt_pk_bf16_f32 v70, v60, v61
	v_add_f32_e32 v232, v232, v62
	v_add_f32_e32 v233, v233, v63
	v_cvt_pk_bf16_f32 v71, v62, v63
	s_nop 1
	s_waitcnt lgkmcnt(1)
	v_mfma_f32_32x32x16_bf16 v[0:15], v[224:227], v[68:71], v[0:15]
	s_waitcnt lgkmcnt(0)
	v_mfma_f32_32x32x16_bf16 v[16:31], v[228:231], v[68:71], v[16:31]
	v_add_f32_e32 v232, v232, v233
	v_add_f32_e32 v112, v112, v232
	s_branch .Lt2_join

; #define LAS __attribute__((address_space(3)))
; __device__ __forceinline__ unsigned xb_ld(unsigned* p) { return __hip_atomic_load(p, __ATOMIC_RELAXED, __HIP_MEMORY_SCOPE_AGENT); }
; __device__ __forceinline__ unsigned xb_add(unsigned* p, unsigned v) { return __hip_atomic_fetch_add(p, v, __ATOMIC_RELAXED, __HIP_MEMORY_SCOPE_AGENT); }
; __device__ __forceinline__ unsigned xb_xcc_id() { return (unsigned)__builtin_amdgcn_s_getreg((3 << 11) | 20) & 0xFu; }
; __device__ __forceinline__ void grid_barrier(unsigned* barw, int k, volatile LAS unsigned* st) {
;     asm volatile("s_waitcnt vmcnt(0)" ::: "memory");
;     __syncthreads();
;     if (threadIdx.x == 0) {
;         __builtin_amdgcn_s_waitcnt(0);
;         const unsigned x = xb_xcc_id();
;         unsigned nloc = st[0], nx = st[1];
;         if (nloc == 0u) {
;             const unsigned G = gridDim.x;
;             for (;;) { unsigned sum = 0u, cnt = 0u, mine = 0u;
; #pragma unroll
;                 for (unsigned j = 0; j < 16; ++j) { const unsigned c = xb_ld(barw + 64 * j); sum += c; cnt += (c > 0u) ? 1u : 0u; mine = (j == x) ? c : mine; }
;                 if (sum == G) { nloc = mine; nx = cnt; break; }
;                 __builtin_amdgcn_s_sleep(1); }
;             st[0] = nloc; st[1] = nx;
;         }
;         unsigned* sb = barw + 1024 + k * 2304;
;         const unsigned old = xb_add(sb + 64 * x, 1u);
;         if (old + 1u == nloc) {
;             __builtin_amdgcn_fence(__ATOMIC_RELEASE, "agent");
;             asm volatile("s_waitcnt vmcnt(0)" ::: "memory");
;             const unsigned og = xb_add(sb + 2048, 1u);
;             if (og + 1u == nx) xb_add(sb + 2112, 1u);
;             else while (xb_ld(sb + 2112) == 0u) __builtin_amdgcn_s_sleep(1);
;             __builtin_amdgcn_fence(__ATOMIC_ACQUIRE, "agent");
;             xb_add(sb + 1024 + 64 * x, 1u);
;             asm volatile("s_waitcnt vmcnt(0)" ::: "memory");
;         } else {
;             while (xb_ld(sb + 1024 + 64 * x) == 0u) __builtin_amdgcn_s_sleep(1);
;             __builtin_amdgcn_fence(__ATOMIC_ACQUIRE, "agent");
;             asm volatile("s_waitcnt vmcnt(0)" ::: "memory");
;         }
;     }
;     __syncthreads();
; }
.LBB0_960:
	v_readlane_b32 s2, v254, 0
	v_readlane_b32 s3, v254, 1
	s_cmp_gt_i32 s3, 6
	s_cselect_b64 s[72:73], -1, 0
	s_and_b64 s[0:1], s[0:1], s[72:73]
	s_andn2_b64 vcc, exec, s[0:1]
	s_cbranch_vccnz .LBB0_989
	s_waitcnt vmcnt(0)
	s_waitcnt vmcnt(0) lgkmcnt(0)
	s_barrier
	s_mov_b64 s[74:75], exec
	v_readlane_b32 s0, v254, 2
	v_readlane_b32 s1, v254, 3
	s_and_b64 s[0:1], s[74:75], s[0:1]
	s_mov_b64 exec, s[0:1]
	s_cbranch_execz .LBB0_988
	s_and_b32 s0, s88, 7
	s_cmp_lg_u32 s0, 0
	s_cbranch_scc1 .Lgb0_orig
	s_waitcnt vmcnt(0) lgkmcnt(0)
	s_and_b32 s0, s70, 7
	s_lshl_b32 s0, s0, 8
	s_add_i32 s0, s0, 0x10c00
	s_add_u32 s4, s78, s0
	s_addc_u32 s5, s79, 0
	s_lshr_b32 s6, s88, 3
	s_getreg_b32 s8, hwreg(HW_REG_XCC_ID, 0, 4)
	s_lshl_b32 s8, 1, s8
	v_mov_b32_e32 v0, 0
	v_mov_b32_e32 v1, s8
	global_atomic_or v2, v0, v1, s[4:5] offset:64 sc0
	s_waitcnt vmcnt(0)
	v_mov_b32_e32 v1, 1
	global_atomic_add v2, v0, v1, s[4:5] sc0
	s_waitcnt vmcnt(0)
	v_readfirstlane_b32 s7, v2
	s_add_i32 s7, s7, 1
	s_cmp_ge_u32 s7, s6
	s_cbranch_scc1 .Lgb0_all1
.Lgb0_spin1:
	s_sleep 1
	global_load_dword v2, v0, s[4:5] sc1
	s_waitcnt vmcnt(0)
	v_readfirstlane_b32 s7, v2
	s_cmp_lt_u32 s7, s6
	s_cbranch_scc1 .Lgb0_spin1
.Lgb0_all1:
	global_load_dword v2, v0, s[4:5] offset:64 sc1
	s_waitcnt vmcnt(0)
	v_readfirstlane_b32 s7, v2
	s_bcnt1_i32_b32 s7, s7
	s_cmp_eq_u32 s7, 1
	s_cbranch_scc1 .Lgb0_acq
	buffer_wbl2 sc1
	s_waitcnt vmcnt(0)
	global_atomic_add v2, v0, v1, s[4:5] offset:128 sc0
	s_waitcnt vmcnt(0)
	v_readfirstlane_b32 s7, v2
	s_add_i32 s7, s7, 1
	s_cmp_ge_u32 s7, s6
	s_cbranch_scc1 .Lgb0_acq
.Lgb0_spin2:
	s_sleep 1
	global_load_dword v2, v0, s[4:5] offset:128 sc1
	s_waitcnt vmcnt(0)
	v_readfirstlane_b32 s7, v2
	s_cmp_lt_u32 s7, s6
	s_cbranch_scc1 .Lgb0_spin2
.Lgb0_acq:
	buffer_inv sc1
	s_waitcnt vmcnt(0)
	s_branch .LBB0_988
.Lgb0_orig:
	s_add_i32 s1, 0, 0x23fc0
	v_mov_b32_e32 v0, s1
	s_waitcnt vmcnt(0) expcnt(0) lgkmcnt(0)
	s_getreg_b32 s0, hwreg(HW_REG_XCC_ID, 0, 4)
	ds_read_b32 v1, v0
	s_add_i32 s1, 0, 0x23fc4
	v_mov_b32_e32 v0, s1
	ds_read_b32 v0, v0
	s_and_b32 s14, s0, 15
	s_waitcnt lgkmcnt(1)
	v_cmp_ne_u32_e32 vcc, 0, v1
	s_cbranch_vccnz .LBB0_968
	s_cmp_eq_u32 s14, 0
	s_cselect_b64 s[2:3], -1, 0
	s_cmp_eq_u32 s14, 1
	s_cselect_b64 s[4:5], -1, 0
	s_cmp_eq_u32 s14, 2
	s_cselect_b64 s[6:7], -1, 0
	s_cmp_eq_u32 s14, 3
	s_cselect_b64 s[8:9], -1, 0
	s_cmp_eq_u32 s14, 4
	s_cselect_b64 s[10:11], -1, 0
	s_cmp_eq_u32 s14, 5
	s_cselect_b64 s[12:13], -1, 0
	s_cmp_eq_u32 s14, 6
	s_cselect_b64 s[0:1], -1, 0
	s_cmp_eq_u32 s14, 7
	s_cselect_b64 s[16:17], -1, 0
	s_cmp_eq_u32 s14, 8
	s_cselect_b64 s[18:19], -1, 0
	s_cmp_eq_u32 s14, 9
	s_cselect_b64 s[20:21], -1, 0
	s_cmp_eq_u32 s14, 10
	s_cselect_b64 s[22:23], -1, 0
	s_cmp_eq_u32 s14, 11
	s_cselect_b64 s[24:25], -1, 0
	s_cmp_eq_u32 s14, 12
	s_cselect_b64 s[26:27], -1, 0
	s_cmp_eq_u32 s14, 13
	s_cselect_b64 s[28:29], -1, 0
	s_cmp_eq_u32 s14, 14
	s_cselect_b64 s[30:31], -1, 0
	s_cmp_eq_u32 s14, 15
	s_cselect_b64 s[34:35], -1, 0
	v_mov_b32_e32 v2, 0
	v_mov_b32_e32 v1, 0
	s_branch .LBB0_965

; #define LAS __attribute__((address_space(3)))
; __device__ __forceinline__ unsigned xb_ld(unsigned* p) { return __hip_atomic_load(p, __ATOMIC_RELAXED, __HIP_MEMORY_SCOPE_AGENT); }
; __device__ __forceinline__ unsigned xb_add(unsigned* p, unsigned v) { return __hip_atomic_fetch_add(p, v, __ATOMIC_RELAXED, __HIP_MEMORY_SCOPE_AGENT); }
; __device__ __forceinline__ unsigned xb_xcc_id() { return (unsigned)__builtin_amdgcn_s_getreg((3 << 11) | 20) & 0xFu; }
; __device__ __forceinline__ void grid_barrier(unsigned* barw, int k, volatile LAS unsigned* st) {
;     asm volatile("s_waitcnt vmcnt(0)" ::: "memory");
;     __syncthreads();
;     if (threadIdx.x == 0) {
;         __builtin_amdgcn_s_waitcnt(0);
;         const unsigned x = xb_xcc_id();
;         unsigned nloc = st[0], nx = st[1];
;         if (nloc == 0u) {
;             const unsigned G = gridDim.x;
;             for (;;) { unsigned sum = 0u, cnt = 0u, mine = 0u;
; #pragma unroll
;                 for (unsigned j = 0; j < 16; ++j) { const unsigned c = xb_ld(barw + 64 * j); sum += c; cnt += (c > 0u) ? 1u : 0u; mine = (j == x) ? c : mine; }
;                 if (sum == G) { nloc = mine; nx = cnt; break; }
;                 __builtin_amdgcn_s_sleep(1); }
;             st[0] = nloc; st[1] = nx;
;         }
;         unsigned* sb = barw + 1024 + k * 2304;
;         const unsigned old = xb_add(sb + 64 * x, 1u);
;         if (old + 1u == nloc) {
;             __builtin_amdgcn_fence(__ATOMIC_RELEASE, "agent");
;             asm volatile("s_waitcnt vmcnt(0)" ::: "memory");
;             const unsigned og = xb_add(sb + 2048, 1u);
;             if (og + 1u == nx) xb_add(sb + 2112, 1u);
;             else while (xb_ld(sb + 2112) == 0u) __builtin_amdgcn_s_sleep(1);
;             __builtin_amdgcn_fence(__ATOMIC_ACQUIRE, "agent");
;             xb_add(sb + 1024 + 64 * x, 1u);
;             asm volatile("s_waitcnt vmcnt(0)" ::: "memory");
;         } else {
;             while (xb_ld(sb + 1024 + 64 * x) == 0u) __builtin_amdgcn_s_sleep(1);
;             __builtin_amdgcn_fence(__ATOMIC_ACQUIRE, "agent");
;             asm volatile("s_waitcnt vmcnt(0)" ::: "memory");
;         }
;     }
;     __syncthreads();
; }
.LBB0_1014:
	v_readlane_b32 s2, v254, 0
	v_readlane_b32 s3, v254, 1
	s_cmp_gt_i32 s3, 7
	s_cselect_b64 s[68:69], -1, 0
	s_and_b64 s[0:1], s[0:1], s[68:69]
	s_andn2_b64 vcc, exec, s[0:1]
	s_cbranch_vccnz .LBB0_1043
	s_waitcnt vmcnt(0)
	s_waitcnt vmcnt(0) lgkmcnt(0)
	s_barrier
	s_mov_b64 s[72:73], exec
	v_readlane_b32 s0, v254, 2
	v_readlane_b32 s1, v254, 3
	s_and_b64 s[0:1], s[72:73], s[0:1]
	s_mov_b64 exec, s[0:1]
	s_cbranch_execz .LBB0_1042
	s_and_b32 s0, s88, 7
	s_cmp_lg_u32 s0, 0
	s_cbranch_scc1 .Lgb1_orig
	s_waitcnt vmcnt(0) lgkmcnt(0)
	s_and_b32 s0, s70, 7
	s_lshl_b32 s0, s0, 8
	s_add_i32 s0, s0, 0x11400
	s_add_u32 s4, s78, s0
	s_addc_u32 s5, s79, 0
	s_lshr_b32 s6, s88, 3
	s_getreg_b32 s8, hwreg(HW_REG_XCC_ID, 0, 4)
	s_lshl_b32 s8, 1, s8
	v_mov_b32_e32 v0, 0
	v_mov_b32_e32 v1, s8
	global_atomic_or v2, v0, v1, s[4:5] offset:64 sc0
	s_waitcnt vmcnt(0)
	v_mov_b32_e32 v1, 1
	global_atomic_add v2, v0, v1, s[4:5] sc0
	s_waitcnt vmcnt(0)
	v_readfirstlane_b32 s7, v2
	s_add_i32 s7, s7, 1
	s_cmp_ge_u32 s7, s6
	s_cbranch_scc1 .Lgb1_all1

; #define LAS __attribute__((address_space(3)))
; __device__ __forceinline__ unsigned xb_ld(unsigned* p) { return __hip_atomic_load(p, __ATOMIC_RELAXED, __HIP_MEMORY_SCOPE_AGENT); }
; __device__ __forceinline__ unsigned xb_xcc_id() { return (unsigned)__builtin_amdgcn_s_getreg((3 << 11) | 20) & 0xFu; }
; __device__ __forceinline__ void grid_barrier(unsigned* barw, int k, volatile LAS unsigned* st) {
;     asm volatile("s_waitcnt vmcnt(0)" ::: "memory");
;     __syncthreads();
;     if (threadIdx.x == 0) {
;         __builtin_amdgcn_s_waitcnt(0);
;         const unsigned x = xb_xcc_id();
;         unsigned nloc = st[0], nx = st[1];
;         if (nloc == 0u) {
;             const unsigned G = gridDim.x;
;             for (;;) { unsigned sum = 0u, cnt = 0u, mine = 0u;
; #pragma unroll
;                 for (unsigned j = 0; j < 16; ++j) { const unsigned c = xb_ld(barw + 64 * j); sum += c; cnt += (c > 0u) ? 1u : 0u; mine = (j == x) ? c : mine; }
;                 if (sum == G) { nloc = mine; nx = cnt; break; }
;                 __builtin_amdgcn_s_sleep(1); }
;             st[0] = nloc; st[1] = nx;
;         }
.Lgb1_orig:
	s_add_i32 s1, 0, 0x23fc0
	v_mov_b32_e32 v0, s1
	s_waitcnt vmcnt(0) expcnt(0) lgkmcnt(0)
	s_getreg_b32 s0, hwreg(HW_REG_XCC_ID, 0, 4)
	ds_read_b32 v1, v0
	s_add_i32 s1, 0, 0x23fc4
	v_mov_b32_e32 v0, s1
	ds_read_b32 v0, v0
	s_and_b32 s33, s0, 15
	s_waitcnt lgkmcnt(1)
	v_cmp_ne_u32_e32 vcc, 0, v1
	s_cbranch_vccnz .LBB0_1022
	s_cmp_eq_u32 s33, 0
	s_cselect_b64 s[0:1], -1, 0
	s_cmp_eq_u32 s33, 1
	s_cselect_b64 s[2:3], -1, 0
	s_cmp_eq_u32 s33, 2
	s_cselect_b64 s[4:5], -1, 0
	s_cmp_eq_u32 s33, 3
	s_cselect_b64 s[6:7], -1, 0
	s_cmp_eq_u32 s33, 4
	s_cselect_b64 s[8:9], -1, 0
	s_cmp_eq_u32 s33, 5
	s_cselect_b64 s[10:11], -1, 0
	s_cmp_eq_u32 s33, 6
	s_cselect_b64 s[12:13], -1, 0
	s_cmp_eq_u32 s33, 7
	s_cselect_b64 s[14:15], -1, 0
	s_cmp_eq_u32 s33, 8
	s_cselect_b64 s[16:17], -1, 0
	s_cmp_eq_u32 s33, 9
	s_cselect_b64 s[18:19], -1, 0
	s_cmp_eq_u32 s33, 10
	s_cselect_b64 s[20:21], -1, 0
	s_cmp_eq_u32 s33, 11
	s_cselect_b64 s[22:23], -1, 0
	s_cmp_eq_u32 s33, 12
	s_cselect_b64 s[24:25], -1, 0
	s_cmp_eq_u32 s33, 13
	s_cselect_b64 s[26:27], -1, 0
	s_cmp_eq_u32 s33, 14
	s_cselect_b64 s[28:29], -1, 0
	s_cmp_eq_u32 s33, 15
	s_cselect_b64 s[30:31], -1, 0
	v_mov_b32_e32 v2, 0
	v_mov_b32_e32 v1, 0
	s_branch .LBB0_1019
